# K-loop load segments: s_waitcnt vmcnt(8) and s_waitcnt lgkmcnt(0) merged into one s_waitcnt (28 sites), on top of v25
# baseline (speedup 1.0000x reference)
.LBB0_131:
	s_add_u32 s60, s57, 0xffffff80
	s_addc_u32 s61, s58, -1
	s_cmp_eq_u32 s59, 60
	s_cselect_b32 s36, s17, s57
	s_cselect_b32 s37, s7, s58
	s_cselect_b32 s39, s21, s56
	s_cselect_b32 s38, s33, s55
	s_add_u32 s30, s36, 0x80
	s_addc_u32 s31, s37, 0
	s_add_u32 s34, s38, 0x80
	s_addc_u32 s35, s39, 0
	s_add_i32 s62, 0, 0x10000
	s_add_i32 s63, 0, 0x14000
	v_add_u32_e32 v152, s62, v1
	v_add_u32_e32 v168, s63, v1
	ds_read_b128 v[140:143], v152
	ds_read_b128 v[144:147], v152 offset:1024
	ds_read_b128 v[148:151], v152 offset:2048
	ds_read_b128 v[152:155], v152 offset:3072
	ds_read_b128 v[156:159], v168
	ds_read_b128 v[160:163], v168 offset:1024
	ds_read_b128 v[164:167], v168 offset:2048
	ds_read_b128 v[168:171], v168 offset:3072
	s_add_u32 s60, s60, 0x100000
	s_addc_u32 s61, s61, 0
	v_lshl_add_u64 v[204:205], s[60:61], 0, v[2:3]
	s_add_i32 m0, s29, 0xc000
	ds_read_b128 v[172:175], v5
	ds_read_b128 v[176:179], v5 offset:1024
	ds_read_b128 v[180:183], v5 offset:2048
	ds_read_b128 v[184:187], v5 offset:3072
	ds_read_b128 v[188:191], v5 offset:4096
	ds_read_b128 v[192:195], v5 offset:5120
	ds_read_b128 v[196:199], v5 offset:6144
	ds_read_b128 v[200:203], v5 offset:7168
	global_load_lds_dwordx4 v[204:205], off
	v_lshl_add_u64 v[204:205], s[60:61], 0, v[136:137]
	s_add_i32 m0, s29, 0xe000
	s_nop 0
	global_load_lds_dwordx4 v[204:205], off
	s_waitcnt vmcnt(8) lgkmcnt(0)
	s_barrier
	s_setprio 1
	v_mfma_f32_16x16x32_bf16 v[130:133], v[140:143], v[172:175], v[130:133]
	v_mfma_f32_16x16x32_bf16 v[126:129], v[148:151], v[172:175], v[126:129]
	v_mfma_f32_16x16x32_bf16 v[114:117], v[140:143], v[180:183], v[114:117]
	v_mfma_f32_16x16x32_bf16 v[110:113], v[148:151], v[180:183], v[110:113]
	v_mfma_f32_16x16x32_bf16 v[98:101], v[140:143], v[188:191], v[98:101]
	v_mfma_f32_16x16x32_bf16 v[94:97], v[148:151], v[188:191], v[94:97]
	v_mfma_f32_16x16x32_bf16 v[82:85], v[140:143], v[196:199], v[82:85]
	v_mfma_f32_16x16x32_bf16 v[78:81], v[148:151], v[196:199], v[78:81]
	v_mfma_f32_16x16x32_bf16 v[130:133], v[144:147], v[176:179], v[130:133]
	v_mfma_f32_16x16x32_bf16 v[126:129], v[152:155], v[176:179], v[126:129]
	v_mfma_f32_16x16x32_bf16 v[114:117], v[144:147], v[184:187], v[114:117]
	v_mfma_f32_16x16x32_bf16 v[110:113], v[152:155], v[184:187], v[110:113]
	v_mfma_f32_16x16x32_bf16 v[98:101], v[144:147], v[192:195], v[98:101]
	v_mfma_f32_16x16x32_bf16 v[94:97], v[152:155], v[192:195], v[94:97]
	v_mfma_f32_16x16x32_bf16 v[82:85], v[144:147], v[200:203], v[82:85]
	v_mfma_f32_16x16x32_bf16 v[78:81], v[152:155], v[200:203], v[78:81]
	s_setprio 0
	s_setprio 1
	v_mfma_f32_16x16x32_bf16 v[122:125], v[156:159], v[172:175], v[122:125]
	v_mfma_f32_16x16x32_bf16 v[118:121], v[164:167], v[172:175], v[118:121]
	v_mfma_f32_16x16x32_bf16 v[106:109], v[156:159], v[180:183], v[106:109]
	v_mfma_f32_16x16x32_bf16 v[102:105], v[164:167], v[180:183], v[102:105]
	v_mfma_f32_16x16x32_bf16 v[90:93], v[156:159], v[188:191], v[90:93]
	v_mfma_f32_16x16x32_bf16 v[86:89], v[164:167], v[188:191], v[86:89]
	v_mfma_f32_16x16x32_bf16 v[74:77], v[156:159], v[196:199], v[74:77]
	v_mfma_f32_16x16x32_bf16 v[70:73], v[164:167], v[196:199], v[70:73]
	v_mfma_f32_16x16x32_bf16 v[122:125], v[160:163], v[176:179], v[122:125]
	v_mfma_f32_16x16x32_bf16 v[118:121], v[168:171], v[176:179], v[118:121]
	v_mfma_f32_16x16x32_bf16 v[106:109], v[160:163], v[184:187], v[106:109]
	v_mfma_f32_16x16x32_bf16 v[102:105], v[168:171], v[184:187], v[102:105]
	v_mfma_f32_16x16x32_bf16 v[90:93], v[160:163], v[192:195], v[90:93]
	v_mfma_f32_16x16x32_bf16 v[86:89], v[168:171], v[192:195], v[86:89]
	v_mfma_f32_16x16x32_bf16 v[74:77], v[160:163], v[200:203], v[74:77]
	v_mfma_f32_16x16x32_bf16 v[70:73], v[168:171], v[200:203], v[70:73]
	s_setprio 0
	s_barrier
	s_add_i32 s60, s62, s42
	v_lshl_add_u64 v[204:205], s[38:39], 0, v[134:135]
	s_mov_b32 m0, s60
	ds_read_b128 v[172:175], v5 offset:16384
	ds_read_b128 v[176:179], v5 offset:17408
	ds_read_b128 v[180:183], v5 offset:18432
	ds_read_b128 v[184:187], v5 offset:19456
	ds_read_b128 v[188:191], v5 offset:20480
	ds_read_b128 v[192:195], v5 offset:21504
	ds_read_b128 v[196:199], v5 offset:22528
	ds_read_b128 v[200:203], v5 offset:23552
	global_load_lds_dwordx4 v[204:205], off
	s_add_i32 m0, s60, 0x2000
	v_lshl_add_u64 v[204:205], s[38:39], 0, v[138:139]
	s_add_u32 s38, s38, 0x100000
	s_addc_u32 s39, s39, 0
	s_add_i32 s60, s63, s42
	global_load_lds_dwordx4 v[204:205], off
	v_lshl_add_u64 v[204:205], s[38:39], 0, v[134:135]
	s_mov_b32 m0, s60
	s_nop 0
	global_load_lds_dwordx4 v[204:205], off
	v_lshl_add_u64 v[204:205], s[38:39], 0, v[138:139]
	s_add_i32 m0, s60, 0x2000
	s_nop 0
	global_load_lds_dwordx4 v[204:205], off
	v_lshl_add_u64 v[204:205], s[36:37], 0, v[2:3]
	s_mov_b32 m0, s29
	s_nop 0
	global_load_lds_dwordx4 v[204:205], off
	v_lshl_add_u64 v[204:205], s[36:37], 0, v[136:137]
	s_mov_b32 m0, s43
	s_nop 0
	global_load_lds_dwordx4 v[204:205], off
	s_waitcnt vmcnt(8) lgkmcnt(0)
	s_barrier
	s_setprio 1
	v_mfma_f32_16x16x32_bf16 v[66:69], v[140:143], v[172:175], v[66:69]
	v_mfma_f32_16x16x32_bf16 v[62:65], v[148:151], v[172:175], v[62:65]
	v_mfma_f32_16x16x32_bf16 v[50:53], v[140:143], v[180:183], v[50:53]
	v_mfma_f32_16x16x32_bf16 v[46:49], v[148:151], v[180:183], v[46:49]
	v_mfma_f32_16x16x32_bf16 v[34:37], v[140:143], v[188:191], v[34:37]
	v_mfma_f32_16x16x32_bf16 v[30:33], v[148:151], v[188:191], v[30:33]
	v_mfma_f32_16x16x32_bf16 v[18:21], v[140:143], v[196:199], v[18:21]
	v_mfma_f32_16x16x32_bf16 v[14:17], v[148:151], v[196:199], v[14:17]
	v_mfma_f32_16x16x32_bf16 v[66:69], v[144:147], v[176:179], v[66:69]
	v_mfma_f32_16x16x32_bf16 v[62:65], v[152:155], v[176:179], v[62:65]
	v_mfma_f32_16x16x32_bf16 v[50:53], v[144:147], v[184:187], v[50:53]
	v_mfma_f32_16x16x32_bf16 v[46:49], v[152:155], v[184:187], v[46:49]
	v_mfma_f32_16x16x32_bf16 v[34:37], v[144:147], v[192:195], v[34:37]
	v_mfma_f32_16x16x32_bf16 v[30:33], v[152:155], v[192:195], v[30:33]
	v_mfma_f32_16x16x32_bf16 v[18:21], v[144:147], v[200:203], v[18:21]
	v_mfma_f32_16x16x32_bf16 v[14:17], v[152:155], v[200:203], v[14:17]
	s_setprio 0
	s_setprio 1
	v_mfma_f32_16x16x32_bf16 v[58:61], v[156:159], v[172:175], v[58:61]
	v_mfma_f32_16x16x32_bf16 v[54:57], v[164:167], v[172:175], v[54:57]
	v_mfma_f32_16x16x32_bf16 v[42:45], v[156:159], v[180:183], v[42:45]
	v_mfma_f32_16x16x32_bf16 v[38:41], v[164:167], v[180:183], v[38:41]
	v_mfma_f32_16x16x32_bf16 v[26:29], v[156:159], v[188:191], v[26:29]
	v_mfma_f32_16x16x32_bf16 v[22:25], v[164:167], v[188:191], v[22:25]
	v_mfma_f32_16x16x32_bf16 v[10:13], v[156:159], v[196:199], v[10:13]
	v_mfma_f32_16x16x32_bf16 v[6:9], v[164:167], v[196:199], v[6:9]
	v_mfma_f32_16x16x32_bf16 v[58:61], v[160:163], v[176:179], v[58:61]
	v_mfma_f32_16x16x32_bf16 v[54:57], v[168:171], v[176:179], v[54:57]
	v_mfma_f32_16x16x32_bf16 v[42:45], v[160:163], v[184:187], v[42:45]
	v_mfma_f32_16x16x32_bf16 v[38:41], v[168:171], v[184:187], v[38:41]
	v_mfma_f32_16x16x32_bf16 v[26:29], v[160:163], v[192:195], v[26:29]
	v_mfma_f32_16x16x32_bf16 v[22:25], v[168:171], v[192:195], v[22:25]
	v_mfma_f32_16x16x32_bf16 v[10:13], v[160:163], v[200:203], v[10:13]
	v_mfma_f32_16x16x32_bf16 v[6:9], v[168:171], v[200:203], v[6:9]
	s_setprio 0
	s_barrier
	s_add_i32 s38, 0, 0x18000
	s_add_i32 s39, 0, 0x1c000
	v_add_u32_e32 v152, s38, v1
	v_add_u32_e32 v168, s39, v1
	ds_read_b128 v[140:143], v152
	ds_read_b128 v[144:147], v152 offset:1024
	ds_read_b128 v[148:151], v152 offset:2048
	ds_read_b128 v[152:155], v152 offset:3072
	ds_read_b128 v[156:159], v168
	ds_read_b128 v[160:163], v168 offset:1024
	ds_read_b128 v[164:167], v168 offset:2048
	ds_read_b128 v[168:171], v168 offset:3072
	s_add_u32 s36, s36, 0x100000
	s_addc_u32 s37, s37, 0
	s_mov_b32 m0, s48
	v_lshl_add_u64 v[204:205], s[36:37], 0, v[2:3]
	ds_read_b128 v[172:175], v5 offset:32768
	ds_read_b128 v[176:179], v5 offset:33792
	ds_read_b128 v[180:183], v5 offset:34816
	ds_read_b128 v[184:187], v5 offset:35840
	ds_read_b128 v[188:191], v5 offset:36864
	ds_read_b128 v[192:195], v5 offset:37888
	ds_read_b128 v[196:199], v5 offset:38912
	ds_read_b128 v[200:203], v5 offset:39936
	global_load_lds_dwordx4 v[204:205], off
	v_lshl_add_u64 v[204:205], s[36:37], 0, v[136:137]
	s_mov_b32 m0, s49
	s_nop 0
	global_load_lds_dwordx4 v[204:205], off
	s_waitcnt vmcnt(8) lgkmcnt(0)
	s_barrier
	s_setprio 1
	v_mfma_f32_16x16x32_bf16 v[130:133], v[140:143], v[172:175], v[130:133]
	v_mfma_f32_16x16x32_bf16 v[126:129], v[148:151], v[172:175], v[126:129]
	v_mfma_f32_16x16x32_bf16 v[114:117], v[140:143], v[180:183], v[114:117]
	v_mfma_f32_16x16x32_bf16 v[110:113], v[148:151], v[180:183], v[110:113]
	v_mfma_f32_16x16x32_bf16 v[98:101], v[140:143], v[188:191], v[98:101]
	v_mfma_f32_16x16x32_bf16 v[94:97], v[148:151], v[188:191], v[94:97]
	v_mfma_f32_16x16x32_bf16 v[82:85], v[140:143], v[196:199], v[82:85]
	v_mfma_f32_16x16x32_bf16 v[78:81], v[148:151], v[196:199], v[78:81]
	v_mfma_f32_16x16x32_bf16 v[130:133], v[144:147], v[176:179], v[130:133]
	v_mfma_f32_16x16x32_bf16 v[126:129], v[152:155], v[176:179], v[126:129]
	v_mfma_f32_16x16x32_bf16 v[114:117], v[144:147], v[184:187], v[114:117]
	v_mfma_f32_16x16x32_bf16 v[110:113], v[152:155], v[184:187], v[110:113]
	v_mfma_f32_16x16x32_bf16 v[98:101], v[144:147], v[192:195], v[98:101]
	v_mfma_f32_16x16x32_bf16 v[94:97], v[152:155], v[192:195], v[94:97]
	v_mfma_f32_16x16x32_bf16 v[82:85], v[144:147], v[200:203], v[82:85]
	v_mfma_f32_16x16x32_bf16 v[78:81], v[152:155], v[200:203], v[78:81]
	s_setprio 0
	s_setprio 1
	v_mfma_f32_16x16x32_bf16 v[122:125], v[156:159], v[172:175], v[122:125]
	v_mfma_f32_16x16x32_bf16 v[118:121], v[164:167], v[172:175], v[118:121]
	v_mfma_f32_16x16x32_bf16 v[106:109], v[156:159], v[180:183], v[106:109]
	v_mfma_f32_16x16x32_bf16 v[102:105], v[164:167], v[180:183], v[102:105]
	v_mfma_f32_16x16x32_bf16 v[90:93], v[156:159], v[188:191], v[90:93]
	v_mfma_f32_16x16x32_bf16 v[86:89], v[164:167], v[188:191], v[86:89]
	v_mfma_f32_16x16x32_bf16 v[74:77], v[156:159], v[196:199], v[74:77]
	v_mfma_f32_16x16x32_bf16 v[70:73], v[164:167], v[196:199], v[70:73]
	v_mfma_f32_16x16x32_bf16 v[122:125], v[160:163], v[176:179], v[122:125]
	v_mfma_f32_16x16x32_bf16 v[118:121], v[168:171], v[176:179], v[118:121]
	v_mfma_f32_16x16x32_bf16 v[106:109], v[160:163], v[184:187], v[106:109]
	v_mfma_f32_16x16x32_bf16 v[102:105], v[168:171], v[184:187], v[102:105]
	v_mfma_f32_16x16x32_bf16 v[90:93], v[160:163], v[192:195], v[90:93]
	v_mfma_f32_16x16x32_bf16 v[86:89], v[168:171], v[192:195], v[86:89]
	v_mfma_f32_16x16x32_bf16 v[74:77], v[160:163], v[200:203], v[74:77]
	v_mfma_f32_16x16x32_bf16 v[70:73], v[168:171], v[200:203], v[70:73]
	s_setprio 0
	s_barrier
	s_add_i32 s36, s38, s42
	v_lshl_add_u64 v[204:205], s[34:35], 0, v[134:135]
	s_mov_b32 m0, s36
	ds_read_b128 v[172:175], v5 offset:49152
	ds_read_b128 v[176:179], v5 offset:50176
	ds_read_b128 v[180:183], v5 offset:51200
	ds_read_b128 v[184:187], v5 offset:52224
	ds_read_b128 v[188:191], v5 offset:53248
	ds_read_b128 v[192:195], v5 offset:54272
	ds_read_b128 v[196:199], v5 offset:55296
	ds_read_b128 v[200:203], v5 offset:56320
	global_load_lds_dwordx4 v[204:205], off
	s_add_i32 m0, s36, 0x2000
	v_lshl_add_u64 v[204:205], s[34:35], 0, v[138:139]
	s_add_u32 s34, s34, 0x100000
	s_addc_u32 s35, s35, 0
	s_add_i32 s36, s39, s42
	global_load_lds_dwordx4 v[204:205], off
	v_lshl_add_u64 v[204:205], s[34:35], 0, v[134:135]
	s_mov_b32 m0, s36
	s_nop 0
	global_load_lds_dwordx4 v[204:205], off
	v_lshl_add_u64 v[204:205], s[34:35], 0, v[138:139]
	s_add_i32 m0, s36, 0x2000
	s_nop 0
	global_load_lds_dwordx4 v[204:205], off
	v_lshl_add_u64 v[204:205], s[30:31], 0, v[2:3]
	s_mov_b32 m0, s52
	s_nop 0
	global_load_lds_dwordx4 v[204:205], off
	v_lshl_add_u64 v[204:205], s[30:31], 0, v[136:137]
	s_mov_b32 m0, s53
	s_nop 0
	global_load_lds_dwordx4 v[204:205], off
	s_waitcnt vmcnt(8) lgkmcnt(0)
	s_barrier
	s_setprio 1
	v_mfma_f32_16x16x32_bf16 v[66:69], v[140:143], v[172:175], v[66:69]
	v_mfma_f32_16x16x32_bf16 v[62:65], v[148:151], v[172:175], v[62:65]
	v_mfma_f32_16x16x32_bf16 v[50:53], v[140:143], v[180:183], v[50:53]
	v_mfma_f32_16x16x32_bf16 v[46:49], v[148:151], v[180:183], v[46:49]
	v_mfma_f32_16x16x32_bf16 v[34:37], v[140:143], v[188:191], v[34:37]
	v_mfma_f32_16x16x32_bf16 v[30:33], v[148:151], v[188:191], v[30:33]
	v_mfma_f32_16x16x32_bf16 v[18:21], v[140:143], v[196:199], v[18:21]
	v_mfma_f32_16x16x32_bf16 v[14:17], v[148:151], v[196:199], v[14:17]
	v_mfma_f32_16x16x32_bf16 v[66:69], v[144:147], v[176:179], v[66:69]
	v_mfma_f32_16x16x32_bf16 v[62:65], v[152:155], v[176:179], v[62:65]
	v_mfma_f32_16x16x32_bf16 v[50:53], v[144:147], v[184:187], v[50:53]
	v_mfma_f32_16x16x32_bf16 v[46:49], v[152:155], v[184:187], v[46:49]
	v_mfma_f32_16x16x32_bf16 v[34:37], v[144:147], v[192:195], v[34:37]
	v_mfma_f32_16x16x32_bf16 v[30:33], v[152:155], v[192:195], v[30:33]
	v_mfma_f32_16x16x32_bf16 v[18:21], v[144:147], v[200:203], v[18:21]
	v_mfma_f32_16x16x32_bf16 v[14:17], v[152:155], v[200:203], v[14:17]
	s_setprio 0
	s_setprio 1
	v_mfma_f32_16x16x32_bf16 v[58:61], v[156:159], v[172:175], v[58:61]
	v_mfma_f32_16x16x32_bf16 v[54:57], v[164:167], v[172:175], v[54:57]
	v_mfma_f32_16x16x32_bf16 v[42:45], v[156:159], v[180:183], v[42:45]
	v_mfma_f32_16x16x32_bf16 v[38:41], v[164:167], v[180:183], v[38:41]
	v_mfma_f32_16x16x32_bf16 v[26:29], v[156:159], v[188:191], v[26:29]
	v_mfma_f32_16x16x32_bf16 v[22:25], v[164:167], v[188:191], v[22:25]
	v_mfma_f32_16x16x32_bf16 v[10:13], v[156:159], v[196:199], v[10:13]
	v_mfma_f32_16x16x32_bf16 v[6:9], v[164:167], v[196:199], v[6:9]
	v_mfma_f32_16x16x32_bf16 v[58:61], v[160:163], v[176:179], v[58:61]
	v_mfma_f32_16x16x32_bf16 v[54:57], v[168:171], v[176:179], v[54:57]
	v_mfma_f32_16x16x32_bf16 v[42:45], v[160:163], v[184:187], v[42:45]
	v_mfma_f32_16x16x32_bf16 v[38:41], v[168:171], v[184:187], v[38:41]
	v_mfma_f32_16x16x32_bf16 v[26:29], v[160:163], v[192:195], v[26:29]
	v_mfma_f32_16x16x32_bf16 v[22:25], v[168:171], v[192:195], v[22:25]
	v_mfma_f32_16x16x32_bf16 v[10:13], v[160:163], v[200:203], v[10:13]
	v_mfma_f32_16x16x32_bf16 v[6:9], v[168:171], v[200:203], v[6:9]
	s_setprio 0
	s_barrier
	s_add_i32 s59, s59, 2
	s_add_u32 s55, s55, 0x100
	s_addc_u32 s56, s56, 0
	s_add_u32 s57, s57, 0x100
	s_addc_u32 s58, s58, 0
	s_cmp_gt_u32 s59, 61
	s_cbranch_scc0 .LBB0_131
	s_and_b64 vcc, exec, s[8:9]
	s_cbranch_vccz .LBB0_134
	s_barrier

.LBB0_251:
	s_add_u32 s56, s52, 0xffffff80
	s_addc_u32 s57, s53, -1
	s_cmp_eq_u32 s54, 60
	s_cselect_b32 s28, s2, s52
	s_cselect_b32 s29, s1, s53
	s_cselect_b32 s31, s11, s33
	s_cselect_b32 s30, s15, s19
	s_add_u32 s24, s28, 0x80
	s_addc_u32 s25, s29, 0
	s_add_u32 s26, s30, 0x80
	s_addc_u32 s27, s31, 0
	s_add_i32 s55, 0, 0x10000
	s_add_i32 s58, 0, 0x14000
	v_add_u32_e32 v152, s55, v1
	v_add_u32_e32 v168, s58, v1
	ds_read_b128 v[140:143], v152
	ds_read_b128 v[144:147], v152 offset:1024
	ds_read_b128 v[148:151], v152 offset:2048
	ds_read_b128 v[152:155], v152 offset:3072
	ds_read_b128 v[156:159], v168
	ds_read_b128 v[160:163], v168 offset:1024
	ds_read_b128 v[164:167], v168 offset:2048
	ds_read_b128 v[168:171], v168 offset:3072
	s_add_u32 s56, s56, 0x100000
	s_addc_u32 s57, s57, 0
	v_lshl_add_u64 v[204:205], s[56:57], 0, v[138:139]
	s_add_i32 m0, s23, 0xc000
	ds_read_b128 v[172:175], v5
	ds_read_b128 v[176:179], v5 offset:1024
	ds_read_b128 v[180:183], v5 offset:2048
	ds_read_b128 v[184:187], v5 offset:3072
	ds_read_b128 v[188:191], v5 offset:4096
	ds_read_b128 v[192:195], v5 offset:5120
	ds_read_b128 v[196:199], v5 offset:6144
	ds_read_b128 v[200:203], v5 offset:7168
	global_load_lds_dwordx4 v[204:205], off
	v_lshl_add_u64 v[204:205], s[56:57], 0, v[134:135]
	s_add_i32 m0, s23, 0xe000
	s_nop 0
	global_load_lds_dwordx4 v[204:205], off
	s_waitcnt vmcnt(8) lgkmcnt(0)
	s_barrier
	s_setprio 1
	v_mfma_f32_16x16x32_bf16 v[6:9], v[140:143], v[172:175], v[6:9]
	v_mfma_f32_16x16x32_bf16 v[10:13], v[148:151], v[172:175], v[10:13]
	v_mfma_f32_16x16x32_bf16 v[22:25], v[140:143], v[180:183], v[22:25]
	v_mfma_f32_16x16x32_bf16 v[26:29], v[148:151], v[180:183], v[26:29]
	v_mfma_f32_16x16x32_bf16 v[38:41], v[140:143], v[188:191], v[38:41]
	v_mfma_f32_16x16x32_bf16 v[42:45], v[148:151], v[188:191], v[42:45]
	v_mfma_f32_16x16x32_bf16 v[54:57], v[140:143], v[196:199], v[54:57]
	v_mfma_f32_16x16x32_bf16 v[58:61], v[148:151], v[196:199], v[58:61]
	v_mfma_f32_16x16x32_bf16 v[6:9], v[144:147], v[176:179], v[6:9]
	v_mfma_f32_16x16x32_bf16 v[10:13], v[152:155], v[176:179], v[10:13]
	v_mfma_f32_16x16x32_bf16 v[22:25], v[144:147], v[184:187], v[22:25]
	v_mfma_f32_16x16x32_bf16 v[26:29], v[152:155], v[184:187], v[26:29]
	v_mfma_f32_16x16x32_bf16 v[38:41], v[144:147], v[192:195], v[38:41]
	v_mfma_f32_16x16x32_bf16 v[42:45], v[152:155], v[192:195], v[42:45]
	v_mfma_f32_16x16x32_bf16 v[54:57], v[144:147], v[200:203], v[54:57]
	v_mfma_f32_16x16x32_bf16 v[58:61], v[152:155], v[200:203], v[58:61]
	s_setprio 0
	s_setprio 1
	v_mfma_f32_16x16x32_bf16 v[14:17], v[156:159], v[172:175], v[14:17]
	v_mfma_f32_16x16x32_bf16 v[18:21], v[164:167], v[172:175], v[18:21]
	v_mfma_f32_16x16x32_bf16 v[30:33], v[156:159], v[180:183], v[30:33]
	v_mfma_f32_16x16x32_bf16 v[34:37], v[164:167], v[180:183], v[34:37]
	v_mfma_f32_16x16x32_bf16 v[46:49], v[156:159], v[188:191], v[46:49]
	v_mfma_f32_16x16x32_bf16 v[50:53], v[164:167], v[188:191], v[50:53]
	v_mfma_f32_16x16x32_bf16 v[62:65], v[156:159], v[196:199], v[62:65]
	v_mfma_f32_16x16x32_bf16 v[66:69], v[164:167], v[196:199], v[66:69]
	v_mfma_f32_16x16x32_bf16 v[14:17], v[160:163], v[176:179], v[14:17]
	v_mfma_f32_16x16x32_bf16 v[18:21], v[168:171], v[176:179], v[18:21]
	v_mfma_f32_16x16x32_bf16 v[30:33], v[160:163], v[184:187], v[30:33]
	v_mfma_f32_16x16x32_bf16 v[34:37], v[168:171], v[184:187], v[34:37]
	v_mfma_f32_16x16x32_bf16 v[46:49], v[160:163], v[192:195], v[46:49]
	v_mfma_f32_16x16x32_bf16 v[50:53], v[168:171], v[192:195], v[50:53]
	v_mfma_f32_16x16x32_bf16 v[62:65], v[160:163], v[200:203], v[62:65]
	v_mfma_f32_16x16x32_bf16 v[66:69], v[168:171], v[200:203], v[66:69]
	s_setprio 0
	s_barrier
	s_add_i32 s55, s55, s37
	v_lshl_add_u64 v[204:205], s[30:31], 0, v[136:137]
	s_mov_b32 m0, s55
	ds_read_b128 v[172:175], v5 offset:16384
	ds_read_b128 v[176:179], v5 offset:17408
	ds_read_b128 v[180:183], v5 offset:18432
	ds_read_b128 v[184:187], v5 offset:19456
	ds_read_b128 v[188:191], v5 offset:20480
	ds_read_b128 v[192:195], v5 offset:21504
	ds_read_b128 v[196:199], v5 offset:22528
	ds_read_b128 v[200:203], v5 offset:23552
	global_load_lds_dwordx4 v[204:205], off
	s_add_i32 m0, s55, 0x2000
	v_lshl_add_u64 v[204:205], s[30:31], 0, v[2:3]
	s_add_u32 s30, s30, 0x100000
	s_addc_u32 s31, s31, 0
	s_add_i32 s55, s58, s37
	global_load_lds_dwordx4 v[204:205], off
	v_lshl_add_u64 v[204:205], s[30:31], 0, v[136:137]
	s_mov_b32 m0, s55
	s_nop 0
	global_load_lds_dwordx4 v[204:205], off
	v_lshl_add_u64 v[204:205], s[30:31], 0, v[2:3]
	s_add_i32 m0, s55, 0x2000
	s_nop 0
	global_load_lds_dwordx4 v[204:205], off
	v_lshl_add_u64 v[204:205], s[28:29], 0, v[138:139]
	s_mov_b32 m0, s23
	s_nop 0
	global_load_lds_dwordx4 v[204:205], off
	v_lshl_add_u64 v[204:205], s[28:29], 0, v[134:135]
	s_mov_b32 m0, s40
	s_nop 0
	global_load_lds_dwordx4 v[204:205], off
	s_waitcnt vmcnt(8) lgkmcnt(0)
	s_barrier
	s_setprio 1
	v_mfma_f32_16x16x32_bf16 v[70:73], v[140:143], v[172:175], v[70:73]
	v_mfma_f32_16x16x32_bf16 v[74:77], v[148:151], v[172:175], v[74:77]
	v_mfma_f32_16x16x32_bf16 v[86:89], v[140:143], v[180:183], v[86:89]
	v_mfma_f32_16x16x32_bf16 v[90:93], v[148:151], v[180:183], v[90:93]
	v_mfma_f32_16x16x32_bf16 v[102:105], v[140:143], v[188:191], v[102:105]
	v_mfma_f32_16x16x32_bf16 v[106:109], v[148:151], v[188:191], v[106:109]
	v_mfma_f32_16x16x32_bf16 v[130:133], v[140:143], v[196:199], v[130:133]
	v_mfma_f32_16x16x32_bf16 v[126:129], v[148:151], v[196:199], v[126:129]
	v_mfma_f32_16x16x32_bf16 v[70:73], v[144:147], v[176:179], v[70:73]
	v_mfma_f32_16x16x32_bf16 v[74:77], v[152:155], v[176:179], v[74:77]
	v_mfma_f32_16x16x32_bf16 v[86:89], v[144:147], v[184:187], v[86:89]
	v_mfma_f32_16x16x32_bf16 v[90:93], v[152:155], v[184:187], v[90:93]
	v_mfma_f32_16x16x32_bf16 v[102:105], v[144:147], v[192:195], v[102:105]
	v_mfma_f32_16x16x32_bf16 v[106:109], v[152:155], v[192:195], v[106:109]
	v_mfma_f32_16x16x32_bf16 v[130:133], v[144:147], v[200:203], v[130:133]
	v_mfma_f32_16x16x32_bf16 v[126:129], v[152:155], v[200:203], v[126:129]
	s_setprio 0
	s_setprio 1
	v_mfma_f32_16x16x32_bf16 v[78:81], v[156:159], v[172:175], v[78:81]
	v_mfma_f32_16x16x32_bf16 v[82:85], v[164:167], v[172:175], v[82:85]
	v_mfma_f32_16x16x32_bf16 v[94:97], v[156:159], v[180:183], v[94:97]
	v_mfma_f32_16x16x32_bf16 v[98:101], v[164:167], v[180:183], v[98:101]
	v_mfma_f32_16x16x32_bf16 v[110:113], v[156:159], v[188:191], v[110:113]
	v_mfma_f32_16x16x32_bf16 v[114:117], v[164:167], v[188:191], v[114:117]
	v_mfma_f32_16x16x32_bf16 v[122:125], v[156:159], v[196:199], v[122:125]
	v_mfma_f32_16x16x32_bf16 v[118:121], v[164:167], v[196:199], v[118:121]
	v_mfma_f32_16x16x32_bf16 v[78:81], v[160:163], v[176:179], v[78:81]
	v_mfma_f32_16x16x32_bf16 v[82:85], v[168:171], v[176:179], v[82:85]
	v_mfma_f32_16x16x32_bf16 v[94:97], v[160:163], v[184:187], v[94:97]
	v_mfma_f32_16x16x32_bf16 v[98:101], v[168:171], v[184:187], v[98:101]
	v_mfma_f32_16x16x32_bf16 v[110:113], v[160:163], v[192:195], v[110:113]
	v_mfma_f32_16x16x32_bf16 v[114:117], v[168:171], v[192:195], v[114:117]
	v_mfma_f32_16x16x32_bf16 v[122:125], v[160:163], v[200:203], v[122:125]
	v_mfma_f32_16x16x32_bf16 v[118:121], v[168:171], v[200:203], v[118:121]
	s_setprio 0
	s_barrier
	s_add_i32 s30, 0, 0x18000
	s_add_i32 s31, 0, 0x1c000
	v_add_u32_e32 v152, s30, v1
	v_add_u32_e32 v168, s31, v1
	ds_read_b128 v[140:143], v152
	ds_read_b128 v[144:147], v152 offset:1024
	ds_read_b128 v[148:151], v152 offset:2048
	ds_read_b128 v[152:155], v152 offset:3072
	ds_read_b128 v[156:159], v168
	ds_read_b128 v[160:163], v168 offset:1024
	ds_read_b128 v[164:167], v168 offset:2048
	ds_read_b128 v[168:171], v168 offset:3072
	s_add_u32 s28, s28, 0x100000
	s_addc_u32 s29, s29, 0
	s_mov_b32 m0, s41
	v_lshl_add_u64 v[204:205], s[28:29], 0, v[138:139]
	ds_read_b128 v[172:175], v5 offset:32768
	ds_read_b128 v[176:179], v5 offset:33792
	ds_read_b128 v[180:183], v5 offset:34816
	ds_read_b128 v[184:187], v5 offset:35840
	ds_read_b128 v[188:191], v5 offset:36864
	ds_read_b128 v[192:195], v5 offset:37888
	ds_read_b128 v[196:199], v5 offset:38912
	ds_read_b128 v[200:203], v5 offset:39936
	global_load_lds_dwordx4 v[204:205], off
	v_lshl_add_u64 v[204:205], s[28:29], 0, v[134:135]
	s_mov_b32 m0, s42
	s_nop 0
	global_load_lds_dwordx4 v[204:205], off
	s_waitcnt vmcnt(8) lgkmcnt(0)
	s_barrier
	s_setprio 1
	v_mfma_f32_16x16x32_bf16 v[6:9], v[140:143], v[172:175], v[6:9]
	v_mfma_f32_16x16x32_bf16 v[10:13], v[148:151], v[172:175], v[10:13]
	v_mfma_f32_16x16x32_bf16 v[22:25], v[140:143], v[180:183], v[22:25]
	v_mfma_f32_16x16x32_bf16 v[26:29], v[148:151], v[180:183], v[26:29]
	v_mfma_f32_16x16x32_bf16 v[38:41], v[140:143], v[188:191], v[38:41]
	v_mfma_f32_16x16x32_bf16 v[42:45], v[148:151], v[188:191], v[42:45]
	v_mfma_f32_16x16x32_bf16 v[54:57], v[140:143], v[196:199], v[54:57]
	v_mfma_f32_16x16x32_bf16 v[58:61], v[148:151], v[196:199], v[58:61]
	v_mfma_f32_16x16x32_bf16 v[6:9], v[144:147], v[176:179], v[6:9]
	v_mfma_f32_16x16x32_bf16 v[10:13], v[152:155], v[176:179], v[10:13]
	v_mfma_f32_16x16x32_bf16 v[22:25], v[144:147], v[184:187], v[22:25]
	v_mfma_f32_16x16x32_bf16 v[26:29], v[152:155], v[184:187], v[26:29]
	v_mfma_f32_16x16x32_bf16 v[38:41], v[144:147], v[192:195], v[38:41]
	v_mfma_f32_16x16x32_bf16 v[42:45], v[152:155], v[192:195], v[42:45]
	v_mfma_f32_16x16x32_bf16 v[54:57], v[144:147], v[200:203], v[54:57]
	v_mfma_f32_16x16x32_bf16 v[58:61], v[152:155], v[200:203], v[58:61]
	s_setprio 0
	s_setprio 1
	v_mfma_f32_16x16x32_bf16 v[14:17], v[156:159], v[172:175], v[14:17]
	v_mfma_f32_16x16x32_bf16 v[18:21], v[164:167], v[172:175], v[18:21]
	v_mfma_f32_16x16x32_bf16 v[30:33], v[156:159], v[180:183], v[30:33]
	v_mfma_f32_16x16x32_bf16 v[34:37], v[164:167], v[180:183], v[34:37]
	v_mfma_f32_16x16x32_bf16 v[46:49], v[156:159], v[188:191], v[46:49]
	v_mfma_f32_16x16x32_bf16 v[50:53], v[164:167], v[188:191], v[50:53]
	v_mfma_f32_16x16x32_bf16 v[62:65], v[156:159], v[196:199], v[62:65]
	v_mfma_f32_16x16x32_bf16 v[66:69], v[164:167], v[196:199], v[66:69]
	v_mfma_f32_16x16x32_bf16 v[14:17], v[160:163], v[176:179], v[14:17]
	v_mfma_f32_16x16x32_bf16 v[18:21], v[168:171], v[176:179], v[18:21]
	v_mfma_f32_16x16x32_bf16 v[30:33], v[160:163], v[184:187], v[30:33]
	v_mfma_f32_16x16x32_bf16 v[34:37], v[168:171], v[184:187], v[34:37]
	v_mfma_f32_16x16x32_bf16 v[46:49], v[160:163], v[192:195], v[46:49]
	v_mfma_f32_16x16x32_bf16 v[50:53], v[168:171], v[192:195], v[50:53]
	v_mfma_f32_16x16x32_bf16 v[62:65], v[160:163], v[200:203], v[62:65]
	v_mfma_f32_16x16x32_bf16 v[66:69], v[168:171], v[200:203], v[66:69]
	s_setprio 0
	s_barrier
	s_add_i32 s28, s30, s37
	v_lshl_add_u64 v[204:205], s[26:27], 0, v[136:137]
	s_mov_b32 m0, s28
	ds_read_b128 v[172:175], v5 offset:49152
	ds_read_b128 v[176:179], v5 offset:50176
	ds_read_b128 v[180:183], v5 offset:51200
	ds_read_b128 v[184:187], v5 offset:52224
	ds_read_b128 v[188:191], v5 offset:53248
	ds_read_b128 v[192:195], v5 offset:54272
	ds_read_b128 v[196:199], v5 offset:55296
	ds_read_b128 v[200:203], v5 offset:56320
	global_load_lds_dwordx4 v[204:205], off
	s_add_i32 m0, s28, 0x2000
	v_lshl_add_u64 v[204:205], s[26:27], 0, v[2:3]
	s_add_u32 s26, s26, 0x100000
	s_addc_u32 s27, s27, 0
	s_add_i32 s28, s31, s37
	global_load_lds_dwordx4 v[204:205], off
	v_lshl_add_u64 v[204:205], s[26:27], 0, v[136:137]
	s_mov_b32 m0, s28
	s_nop 0
	global_load_lds_dwordx4 v[204:205], off
	v_lshl_add_u64 v[204:205], s[26:27], 0, v[2:3]
	s_add_i32 m0, s28, 0x2000
	s_nop 0
	global_load_lds_dwordx4 v[204:205], off
	v_lshl_add_u64 v[204:205], s[24:25], 0, v[138:139]
	s_mov_b32 m0, s49
	s_nop 0
	global_load_lds_dwordx4 v[204:205], off
	v_lshl_add_u64 v[204:205], s[24:25], 0, v[134:135]
	s_mov_b32 m0, s50
	s_nop 0
	global_load_lds_dwordx4 v[204:205], off
	s_waitcnt vmcnt(8) lgkmcnt(0)
	s_barrier
	s_setprio 1
	v_mfma_f32_16x16x32_bf16 v[70:73], v[140:143], v[172:175], v[70:73]
	v_mfma_f32_16x16x32_bf16 v[74:77], v[148:151], v[172:175], v[74:77]
	v_mfma_f32_16x16x32_bf16 v[86:89], v[140:143], v[180:183], v[86:89]
	v_mfma_f32_16x16x32_bf16 v[90:93], v[148:151], v[180:183], v[90:93]
	v_mfma_f32_16x16x32_bf16 v[102:105], v[140:143], v[188:191], v[102:105]
	v_mfma_f32_16x16x32_bf16 v[106:109], v[148:151], v[188:191], v[106:109]
	v_mfma_f32_16x16x32_bf16 v[130:133], v[140:143], v[196:199], v[130:133]
	v_mfma_f32_16x16x32_bf16 v[126:129], v[148:151], v[196:199], v[126:129]
	v_mfma_f32_16x16x32_bf16 v[70:73], v[144:147], v[176:179], v[70:73]
	v_mfma_f32_16x16x32_bf16 v[74:77], v[152:155], v[176:179], v[74:77]
	v_mfma_f32_16x16x32_bf16 v[86:89], v[144:147], v[184:187], v[86:89]
	v_mfma_f32_16x16x32_bf16 v[90:93], v[152:155], v[184:187], v[90:93]
	v_mfma_f32_16x16x32_bf16 v[102:105], v[144:147], v[192:195], v[102:105]
	v_mfma_f32_16x16x32_bf16 v[106:109], v[152:155], v[192:195], v[106:109]
	v_mfma_f32_16x16x32_bf16 v[130:133], v[144:147], v[200:203], v[130:133]
	v_mfma_f32_16x16x32_bf16 v[126:129], v[152:155], v[200:203], v[126:129]
	s_setprio 0
	s_setprio 1
	v_mfma_f32_16x16x32_bf16 v[78:81], v[156:159], v[172:175], v[78:81]
	v_mfma_f32_16x16x32_bf16 v[82:85], v[164:167], v[172:175], v[82:85]
	v_mfma_f32_16x16x32_bf16 v[94:97], v[156:159], v[180:183], v[94:97]
	v_mfma_f32_16x16x32_bf16 v[98:101], v[164:167], v[180:183], v[98:101]
	v_mfma_f32_16x16x32_bf16 v[110:113], v[156:159], v[188:191], v[110:113]
	v_mfma_f32_16x16x32_bf16 v[114:117], v[164:167], v[188:191], v[114:117]
	v_mfma_f32_16x16x32_bf16 v[122:125], v[156:159], v[196:199], v[122:125]
	v_mfma_f32_16x16x32_bf16 v[118:121], v[164:167], v[196:199], v[118:121]
	v_mfma_f32_16x16x32_bf16 v[78:81], v[160:163], v[176:179], v[78:81]
	v_mfma_f32_16x16x32_bf16 v[82:85], v[168:171], v[176:179], v[82:85]
	v_mfma_f32_16x16x32_bf16 v[94:97], v[160:163], v[184:187], v[94:97]
	v_mfma_f32_16x16x32_bf16 v[98:101], v[168:171], v[184:187], v[98:101]
	v_mfma_f32_16x16x32_bf16 v[110:113], v[160:163], v[192:195], v[110:113]
	v_mfma_f32_16x16x32_bf16 v[114:117], v[168:171], v[192:195], v[114:117]
	v_mfma_f32_16x16x32_bf16 v[122:125], v[160:163], v[200:203], v[122:125]
	v_mfma_f32_16x16x32_bf16 v[118:121], v[168:171], v[200:203], v[118:121]
	s_setprio 0
	s_barrier
	s_add_i32 s54, s54, 2
	s_add_u32 s19, s19, 0x100
	s_addc_u32 s33, s33, 0
	s_add_u32 s52, s52, 0x100
	s_addc_u32 s53, s53, 0
	s_cmp_gt_u32 s54, 61
	s_cbranch_scc0 .LBB0_251
	v_mov_b32_e32 v141, v0
	s_lshl_b32 s1, s0, 8
	s_mov_b64 s[24:25], s[84:85]
	s_add_i32 s1, s1, s43
	v_and_or_b32 v140, v141, 15, s1
	v_lshrrev_b32_e32 v141, 1, v141
	s_add_u32 s26, s24, s6
	v_and_or_b32 v148, v141, 24, s48
	s_addc_u32 s27, s25, s7
	v_ashrrev_i32_e32 v141, 31, v140
	v_lshl_add_u64 v[142:143], v[140:141], 2, s[26:27]
	s_mov_b64 s[26:27], 0x10000
	v_lshl_add_u64 v[144:145], v[142:143], 0, s[26:27]
	v_add_co_u32_e32 v142, vcc, s91, v142
	global_load_dword v146, v[144:145], off offset:512
	s_nop 0
	v_addc_co_u32_e32 v143, vcc, 0, v143, vcc
	global_load_dword v142, v[142:143], off
	s_cmp_lt_i32 s22, 8
	s_mov_b64 s[26:27], -1
	global_load_dword v205, v[144:145], off offset:64
	global_load_dword v204, v[144:145], off offset:128
	global_load_dword v203, v[144:145], off offset:192
	global_load_dword v202, v[144:145], off offset:576
	global_load_dword v201, v[144:145], off offset:640
	global_load_dword v200, v[144:145], off offset:704
	s_waitcnt vmcnt(0)
	v_fmamk_f32 v146, v146, 0x39800000, v246
	v_mul_f32_e32 v147, 0x4b800000, v146
	v_fmamk_f32 v142, v142, 0x39800000, v246
	v_cmp_gt_f32_e32 vcc, s95, v142
	v_mul_f32_e32 v143, 0x4b800000, v142
	s_nop 0
	v_cndmask_b32_e32 v142, v142, v143, vcc
	v_rsq_f32_e32 v142, v142
	s_nop 0
	v_mul_f32_e32 v143, 0x45800000, v142
	v_cndmask_b32_e32 v142, v142, v143, vcc
	v_pk_mul_f32 v[8:9], v[8:9], v[142:143] op_sel_hi:[1,0]
	v_pk_mul_f32 v[6:7], v[6:7], v[142:143] op_sel_hi:[1,0]
	v_pk_mul_f32 v[12:13], v[12:13], v[142:143] op_sel_hi:[1,0]
	v_pk_mul_f32 v[10:11], v[10:11], v[142:143] op_sel_hi:[1,0]
	v_pk_mul_f32 v[16:17], v[16:17], v[142:143] op_sel_hi:[1,0]
	v_pk_mul_f32 v[14:15], v[14:15], v[142:143] op_sel_hi:[1,0]
	v_pk_mul_f32 v[20:21], v[20:21], v[142:143] op_sel_hi:[1,0]
	v_pk_mul_f32 v[18:19], v[18:19], v[142:143] op_sel_hi:[1,0]
	s_waitcnt vmcnt(0)
	v_fmamk_f32 v142, v205, 0x39800000, v246
	v_cmp_gt_f32_e32 vcc, s95, v142
	v_mul_f32_e32 v143, 0x4b800000, v142
	s_nop 0
	v_cndmask_b32_e32 v142, v142, v143, vcc
	v_rsq_f32_e32 v142, v142
	s_nop 0
	v_mul_f32_e32 v143, 0x45800000, v142
	v_cndmask_b32_e32 v142, v142, v143, vcc
	v_pk_mul_f32 v[24:25], v[24:25], v[142:143] op_sel_hi:[1,0]
	v_pk_mul_f32 v[22:23], v[22:23], v[142:143] op_sel_hi:[1,0]
	v_pk_mul_f32 v[28:29], v[28:29], v[142:143] op_sel_hi:[1,0]
	v_pk_mul_f32 v[26:27], v[26:27], v[142:143] op_sel_hi:[1,0]
	v_pk_mul_f32 v[32:33], v[32:33], v[142:143] op_sel_hi:[1,0]
	v_pk_mul_f32 v[30:31], v[30:31], v[142:143] op_sel_hi:[1,0]
	v_pk_mul_f32 v[36:37], v[36:37], v[142:143] op_sel_hi:[1,0]
	v_pk_mul_f32 v[34:35], v[34:35], v[142:143] op_sel_hi:[1,0]
	s_waitcnt vmcnt(0)
	v_fmamk_f32 v142, v204, 0x39800000, v246
	v_cmp_gt_f32_e32 vcc, s95, v142
	v_mul_f32_e32 v143, 0x4b800000, v142
	s_nop 0
	v_cndmask_b32_e32 v142, v142, v143, vcc
	v_rsq_f32_e32 v142, v142
	s_nop 0
	v_mul_f32_e32 v143, 0x45800000, v142
	v_cndmask_b32_e32 v142, v142, v143, vcc
	v_pk_mul_f32 v[40:41], v[40:41], v[142:143] op_sel_hi:[1,0]
	v_pk_mul_f32 v[38:39], v[38:39], v[142:143] op_sel_hi:[1,0]
	v_pk_mul_f32 v[44:45], v[44:45], v[142:143] op_sel_hi:[1,0]
	v_pk_mul_f32 v[42:43], v[42:43], v[142:143] op_sel_hi:[1,0]
	v_pk_mul_f32 v[48:49], v[48:49], v[142:143] op_sel_hi:[1,0]
	v_pk_mul_f32 v[46:47], v[46:47], v[142:143] op_sel_hi:[1,0]
	v_pk_mul_f32 v[52:53], v[52:53], v[142:143] op_sel_hi:[1,0]
	v_pk_mul_f32 v[50:51], v[50:51], v[142:143] op_sel_hi:[1,0]
	s_waitcnt vmcnt(0)
	v_fmamk_f32 v142, v203, 0x39800000, v246
	v_cmp_gt_f32_e32 vcc, s95, v142
	v_mul_f32_e32 v143, 0x4b800000, v142
	s_nop 0
	v_cndmask_b32_e32 v142, v142, v143, vcc
	v_rsq_f32_e32 v142, v142
	s_nop 0
	v_mul_f32_e32 v143, 0x45800000, v142
	v_cndmask_b32_e32 v142, v142, v143, vcc
	v_cmp_gt_f32_e32 vcc, s95, v146
	v_pk_mul_f32 v[56:57], v[56:57], v[142:143] op_sel_hi:[1,0]
	v_pk_mul_f32 v[54:55], v[54:55], v[142:143] op_sel_hi:[1,0]
	v_cndmask_b32_e32 v146, v146, v147, vcc
	v_rsq_f32_e32 v146, v146
	v_pk_mul_f32 v[60:61], v[60:61], v[142:143] op_sel_hi:[1,0]
	v_pk_mul_f32 v[58:59], v[58:59], v[142:143] op_sel_hi:[1,0]
	v_pk_mul_f32 v[64:65], v[64:65], v[142:143] op_sel_hi:[1,0]
	v_mul_f32_e32 v147, 0x45800000, v146
	v_cndmask_b32_e32 v146, v146, v147, vcc
	v_pk_mul_f32 v[72:73], v[72:73], v[146:147] op_sel_hi:[1,0]
	v_pk_mul_f32 v[70:71], v[70:71], v[146:147] op_sel_hi:[1,0]
	v_pk_mul_f32 v[76:77], v[76:77], v[146:147] op_sel_hi:[1,0]
	v_pk_mul_f32 v[74:75], v[74:75], v[146:147] op_sel_hi:[1,0]
	v_pk_mul_f32 v[80:81], v[80:81], v[146:147] op_sel_hi:[1,0]
	v_pk_mul_f32 v[78:79], v[78:79], v[146:147] op_sel_hi:[1,0]
	v_pk_mul_f32 v[84:85], v[84:85], v[146:147] op_sel_hi:[1,0]
	v_pk_mul_f32 v[82:83], v[82:83], v[146:147] op_sel_hi:[1,0]
	v_pk_mul_f32 v[62:63], v[62:63], v[142:143] op_sel_hi:[1,0]
	v_pk_mul_f32 v[68:69], v[68:69], v[142:143] op_sel_hi:[1,0]
	v_pk_mul_f32 v[66:67], v[66:67], v[142:143] op_sel_hi:[1,0]
	v_add_u32_e32 v142, 0x80, v140
	v_ashrrev_i32_e32 v143, 31, v142
	s_waitcnt vmcnt(0)
	v_fmamk_f32 v146, v202, 0x39800000, v246
	v_cmp_gt_f32_e32 vcc, s95, v146
	v_mul_f32_e32 v147, 0x4b800000, v146
	s_nop 0
	v_cndmask_b32_e32 v146, v146, v147, vcc
	v_rsq_f32_e32 v146, v146
	s_nop 0
	v_mul_f32_e32 v147, 0x45800000, v146
	v_cndmask_b32_e32 v146, v146, v147, vcc
	v_pk_mul_f32 v[88:89], v[88:89], v[146:147] op_sel_hi:[1,0]
	v_pk_mul_f32 v[86:87], v[86:87], v[146:147] op_sel_hi:[1,0]
	v_pk_mul_f32 v[92:93], v[92:93], v[146:147] op_sel_hi:[1,0]
	v_pk_mul_f32 v[90:91], v[90:91], v[146:147] op_sel_hi:[1,0]
	v_pk_mul_f32 v[96:97], v[96:97], v[146:147] op_sel_hi:[1,0]
	v_pk_mul_f32 v[94:95], v[94:95], v[146:147] op_sel_hi:[1,0]
	v_pk_mul_f32 v[100:101], v[100:101], v[146:147] op_sel_hi:[1,0]
	v_pk_mul_f32 v[98:99], v[98:99], v[146:147] op_sel_hi:[1,0]
	s_waitcnt vmcnt(0)
	v_fmamk_f32 v146, v201, 0x39800000, v246
	v_cmp_gt_f32_e32 vcc, s95, v146
	v_mul_f32_e32 v147, 0x4b800000, v146
	s_waitcnt vmcnt(0)
	v_fmamk_f32 v144, v200, 0x39800000, v246
	v_cndmask_b32_e32 v146, v146, v147, vcc
	v_rsq_f32_e32 v146, v146
	v_mul_f32_e32 v145, 0x4b800000, v144
	v_mul_f32_e32 v147, 0x45800000, v146
	v_cndmask_b32_e32 v146, v146, v147, vcc
	v_cmp_gt_f32_e32 vcc, s95, v144
	v_pk_mul_f32 v[104:105], v[104:105], v[146:147] op_sel_hi:[1,0]
	v_pk_mul_f32 v[102:103], v[102:103], v[146:147] op_sel_hi:[1,0]
	v_cndmask_b32_e32 v144, v144, v145, vcc
	v_rsq_f32_e32 v144, v144
	v_pk_mul_f32 v[108:109], v[108:109], v[146:147] op_sel_hi:[1,0]
	v_pk_mul_f32 v[106:107], v[106:107], v[146:147] op_sel_hi:[1,0]
	v_pk_mul_f32 v[112:113], v[112:113], v[146:147] op_sel_hi:[1,0]
	v_mul_f32_e32 v145, 0x45800000, v144
	v_cndmask_b32_e32 v144, v144, v145, vcc
	v_pk_mul_f32 v[110:111], v[110:111], v[146:147] op_sel_hi:[1,0]
	v_pk_mul_f32 v[116:117], v[116:117], v[146:147] op_sel_hi:[1,0]
	v_pk_mul_f32 v[114:115], v[114:115], v[146:147] op_sel_hi:[1,0]
	v_pk_mul_f32 v[132:133], v[132:133], v[144:145] op_sel_hi:[1,0]
	v_pk_mul_f32 v[130:131], v[130:131], v[144:145] op_sel_hi:[1,0]
	v_pk_mul_f32 v[128:129], v[128:129], v[144:145] op_sel_hi:[1,0]
	v_pk_mul_f32 v[126:127], v[126:127], v[144:145] op_sel_hi:[1,0]
	v_pk_mul_f32 v[124:125], v[124:125], v[144:145] op_sel_hi:[1,0]
	v_pk_mul_f32 v[122:123], v[122:123], v[144:145] op_sel_hi:[1,0]
	v_pk_mul_f32 v[120:121], v[120:121], v[144:145] op_sel_hi:[1,0]
	v_pk_mul_f32 v[118:119], v[118:119], v[144:145] op_sel_hi:[1,0]
	s_cbranch_scc1 .LBB0_254
	v_mul_f32_e32 v145, 0xbfb8aa3b, v7
	v_mul_f32_e32 v146, 0xbfb8aa3b, v8
	v_exp_f32_e32 v145, v145
	v_exp_f32_e32 v146, v146
	v_mul_f32_e32 v144, 0xbfb8aa3b, v6
	v_exp_f32_e32 v144, v144
	v_add_f32_e32 v145, 1.0, v145
	v_add_f32_e32 v146, 1.0, v146
	v_rcp_f32_e32 v145, v145
	v_rcp_f32_e32 v149, v146
	v_add_f32_e32 v144, 1.0, v144
	v_mul_f32_e32 v146, 0xbfb8aa3b, v9
	v_mul_f32_e32 v147, v7, v145
	v_mul_f32_e32 v195, v8, v149
	v_mul_f32_e32 v145, 0xbfb8aa3b, v10
	v_mul_f32_e32 v149, 0xbfb8aa3b, v11
	v_rcp_f32_e32 v144, v144
	v_exp_f32_e32 v150, v146
	v_exp_f32_e32 v145, v145
	v_exp_f32_e32 v149, v149
	v_mul_f32_e32 v146, v6, v144
	v_add_f32_e32 v144, 1.0, v150
	v_add_f32_e32 v145, 1.0, v145
	v_add_f32_e32 v149, 1.0, v149
	v_mul_f32_e32 v150, 0xbfb8aa3b, v12
	v_rcp_f32_e32 v144, v144
	v_rcp_f32_e32 v145, v145
	v_rcp_f32_e32 v149, v149
	v_exp_f32_e32 v150, v150
	v_mul_f32_e32 v209, v9, v144
	v_mul_f32_e32 v144, v10, v145
	v_mul_f32_e32 v145, v11, v149
	v_add_f32_e32 v149, 1.0, v150
	v_mul_f32_e32 v150, 0xbfb8aa3b, v13
	v_exp_f32_e32 v150, v150
	v_mul_f32_e32 v151, 0xbfb8aa3b, v14
	v_exp_f32_e32 v151, v151
	v_mul_f32_e32 v240, 0xbfb8aa3b, v99
	v_add_f32_e32 v150, 1.0, v150
	v_rcp_f32_e32 v150, v150
	v_add_f32_e32 v151, 1.0, v151
	v_rcp_f32_e32 v151, v151
	v_exp_f32_e32 v240, v240
	v_mul_f32_e32 v206, v13, v150
	v_mul_f32_e32 v150, 0xbfb8aa3b, v16
	v_mul_f32_e32 v194, v14, v151
	v_exp_f32_e32 v150, v150
	v_mul_f32_e32 v151, 0xbfb8aa3b, v17
	v_exp_f32_e32 v151, v151
	v_mul_f32_e32 v152, 0xbfb8aa3b, v15
	v_rcp_f32_e32 v149, v149
	v_exp_f32_e32 v152, v152
	v_add_f32_e32 v150, 1.0, v150
	v_rcp_f32_e32 v150, v150
	v_add_f32_e32 v151, 1.0, v151
	v_add_f32_e32 v242, 1.0, v240
	v_cvt_pk_bf16_f32 v240, v146, v147
	v_mul_f32_e32 v146, 0xbfb8aa3b, v100
	v_rcp_f32_e32 v151, v151
	v_exp_f32_e32 v146, v146
	v_mul_f32_e32 v147, 0xbfb8aa3b, v101
	v_exp_f32_e32 v147, v147
	v_mul_f32_e32 v205, v12, v149
	v_add_f32_e32 v149, 1.0, v152
	v_mul_f32_e32 v152, 0xbfb8aa3b, v18
	s_lshl_b32 s1, s22, 8
	v_rcp_f32_e32 v149, v149
	v_exp_f32_e32 v152, v152
	v_mul_f32_e32 v203, v16, v150
	v_mul_f32_e32 v150, 0xbfb8aa3b, v19
	v_cvt_pk_bf16_f32 v241, v195, v209
	v_rcp_f32_e32 v195, v242
	s_addk_i32 s1, 0xf800
	v_cvt_pk_bf16_f32 v242, v144, v145
	v_cvt_pk_bf16_f32 v243, v205, v206
	v_mul_f32_e32 v205, 0xbfb8aa3b, v102
	v_mul_f32_e32 v204, v17, v151
	v_exp_f32_e32 v150, v150
	v_mul_f32_e32 v151, 0xbfb8aa3b, v20
	v_add_f32_e32 v146, 1.0, v146
	v_or_b32_e32 v144, s1, v148
	v_mov_b32_e32 v145, v4
	v_exp_f32_e32 v205, v205
	v_exp_f32_e32 v151, v151
	v_rcp_f32_e32 v209, v146
	v_add_f32_e32 v146, 1.0, v147
	v_lshl_add_u64 v[144:145], v[144:145], 1, s[24:25]
	s_mov_b64 s[26:27], 0x1b480000
	v_rcp_f32_e32 v244, v146
	v_lshl_add_u64 v[146:147], v[144:145], 0, s[26:27]
	v_lshlrev_b64 v[144:145], 13, v[140:141]
	v_mul_f32_e32 v202, v15, v149
	v_add_f32_e32 v149, 1.0, v152
	v_lshl_add_u64 v[144:145], v[146:147], 0, v[144:145]
	v_rcp_f32_e32 v149, v149
	v_add_f32_e32 v150, 1.0, v150
	global_store_dwordx4 v[144:145], v[240:243], off nt
	v_add_f32_e32 v205, 1.0, v205
	v_rcp_f32_e32 v150, v150
	v_mul_f32_e32 v240, 0xbfb8aa3b, v103
	v_add_f32_e32 v151, 1.0, v151
	v_exp_f32_e32 v240, v240
	v_cvt_pk_bf16_f32 v202, v194, v202
	v_cvt_pk_bf16_f32 v203, v203, v204
	v_rcp_f32_e32 v204, v205
	v_rcp_f32_e32 v151, v151
	v_mul_f32_e32 v152, 0xbfb8aa3b, v21
	v_mul_f32_e32 v200, v18, v149
	v_exp_f32_e32 v152, v152
	v_mul_f32_e32 v201, v19, v150
	v_add_f32_e32 v205, 1.0, v240
	v_mul_f32_e32 v240, 0xbfb8aa3b, v105
	v_mul_f32_e32 v241, v102, v204
	v_cvt_pk_bf16_f32 v204, v200, v201
	v_mul_f32_e32 v200, 0xbfb8aa3b, v106
	v_mul_f32_e32 v192, v20, v151
	v_mul_f32_e32 v151, 0xbfb8aa3b, v23
	v_rcp_f32_e32 v205, v205
	v_exp_f32_e32 v240, v240
	v_exp_f32_e32 v200, v200
	v_exp_f32_e32 v151, v151
	v_mul_f32_e32 v150, 0xbfb8aa3b, v22
	v_add_f32_e32 v149, 1.0, v152
	v_exp_f32_e32 v150, v150
	v_rcp_f32_e32 v149, v149
	v_mul_f32_e32 v242, v103, v205
	v_add_f32_e32 v205, 1.0, v240
	v_mul_f32_e32 v201, 0xbfb8aa3b, v107
	v_add_f32_e32 v200, 1.0, v200
	v_add_f32_e32 v151, 1.0, v151
	v_exp_f32_e32 v201, v201
	v_rcp_f32_e32 v240, v205
	v_rcp_f32_e32 v200, v200
	v_rcp_f32_e32 v151, v151
	v_add_f32_e32 v150, 1.0, v150
	v_rcp_f32_e32 v150, v150
	v_mul_f32_e32 v197, v21, v149
	v_mul_f32_e32 v152, 0xbfb8aa3b, v24
	v_add_f32_e32 v201, 1.0, v201
	v_cvt_pk_bf16_f32 v205, v192, v197
	v_mul_f32_e32 v197, v105, v240
	v_mul_f32_e32 v240, v106, v200
	v_mul_f32_e32 v200, 0xbfb8aa3b, v109
	v_exp_f32_e32 v152, v152
	v_mul_f32_e32 v181, v23, v151
	v_mul_f32_e32 v151, 0xbfb8aa3b, v26
	v_rcp_f32_e32 v201, v201
	v_exp_f32_e32 v200, v200
	v_exp_f32_e32 v151, v151
	v_mul_f32_e32 v179, v22, v150
	v_mul_f32_e32 v150, 0xbfb8aa3b, v25
	v_exp_f32_e32 v150, v150
	v_add_f32_e32 v149, 1.0, v152
	v_mul_f32_e32 v152, 0xbfb8aa3b, v27
	v_mul_f32_e32 v243, v107, v201
	v_mul_f32_e32 v201, 0xbfb8aa3b, v110
	v_add_f32_e32 v200, 1.0, v200
	v_rcp_f32_e32 v149, v149
	v_add_f32_e32 v151, 1.0, v151
	v_exp_f32_e32 v152, v152
	v_exp_f32_e32 v201, v201
	v_rcp_f32_e32 v200, v200
	v_rcp_f32_e32 v151, v151
	v_add_f32_e32 v150, 1.0, v150
	v_rcp_f32_e32 v150, v150
	global_store_dwordx4 v[144:145], v[202:205], off offset:256 nt
	v_mul_f32_e32 v188, v24, v149
	v_add_f32_e32 v149, 1.0, v152
	v_mul_f32_e32 v202, 0xbfb8aa3b, v111
	v_add_f32_e32 v201, 1.0, v201
	v_exp_f32_e32 v202, v202
	v_mul_f32_e32 v204, v109, v200
	v_cvt_pk_bf16_f32 v200, v179, v181
	v_mul_f32_e32 v181, 0xbfb8aa3b, v113
	v_mul_f32_e32 v178, v26, v151
	v_mul_f32_e32 v151, 0xbfb8aa3b, v29
	v_rcp_f32_e32 v149, v149
	v_rcp_f32_e32 v201, v201
	v_exp_f32_e32 v181, v181
	v_exp_f32_e32 v151, v151
	v_mul_f32_e32 v179, 0xbfb8aa3b, v112
	v_mul_f32_e32 v189, v25, v150
	v_mul_f32_e32 v150, 0xbfb8aa3b, v28
	v_exp_f32_e32 v179, v179
	v_exp_f32_e32 v150, v150
	v_add_f32_e32 v202, 1.0, v202
	v_mul_f32_e32 v187, v27, v149
	v_mul_f32_e32 v205, v110, v201
	v_cvt_pk_bf16_f32 v201, v188, v189
	v_rcp_f32_e32 v188, v202
	v_add_f32_e32 v181, 1.0, v181
	v_cvt_pk_bf16_f32 v202, v178, v187
	v_mul_f32_e32 v178, 0xbfb8aa3b, v114
	v_add_f32_e32 v151, 1.0, v151
	v_rcp_f32_e32 v181, v181
	v_exp_f32_e32 v178, v178
	v_rcp_f32_e32 v151, v151
	v_add_f32_e32 v179, 1.0, v179
	v_add_f32_e32 v150, 1.0, v150
	v_rcp_f32_e32 v179, v179
	v_rcp_f32_e32 v150, v150
	v_mul_f32_e32 v245, v113, v181
	v_add_f32_e32 v181, 1.0, v178
	v_mul_f32_e32 v178, 0xbfb8aa3b, v115
	v_mul_f32_e32 v182, v29, v151
	v_mul_f32_e32 v151, 0xbfb8aa3b, v32
	v_exp_f32_e32 v248, v178
	v_or_b32_e32 v178, 16, v140
	v_exp_f32_e32 v151, v151
	v_mul_f32_e32 v206, v100, v209
	v_mul_f32_e32 v209, v101, v244
	v_mul_f32_e32 v244, v112, v179
	v_ashrrev_i32_e32 v179, 31, v178
	v_mul_f32_e32 v152, 0xbfb8aa3b, v30
	v_mul_f32_e32 v180, v28, v150
	v_mul_f32_e32 v150, 0xbfb8aa3b, v31
	v_lshlrev_b64 v[178:179], 13, v[178:179]
	v_exp_f32_e32 v152, v152
	v_exp_f32_e32 v150, v150
	v_mul_f32_e32 v187, v111, v188
	v_lshl_add_u64 v[188:189], v[146:147], 0, v[178:179]
	v_mul_f32_e32 v178, 0xbfb8aa3b, v116
	v_exp_f32_e32 v178, v178
	v_add_f32_e32 v151, 1.0, v151
	v_rcp_f32_e32 v151, v151
	v_add_f32_e32 v149, 1.0, v152
	v_add_f32_e32 v150, 1.0, v150
	v_rcp_f32_e32 v149, v149
	v_rcp_f32_e32 v150, v150
	v_add_f32_e32 v178, 1.0, v178
	v_rcp_f32_e32 v178, v178
	v_mul_f32_e32 v173, v32, v151
	v_mul_f32_e32 v151, 0xbfb8aa3b, v35
	v_exp_f32_e32 v151, v151
	v_mul_f32_e32 v152, 0xbfb8aa3b, v33
	v_mul_f32_e32 v170, v30, v149
	v_mul_f32_e32 v172, v31, v150
	v_mul_f32_e32 v150, 0xbfb8aa3b, v34
	v_exp_f32_e32 v152, v152
	v_exp_f32_e32 v150, v150
	v_cvt_pk_bf16_f32 v203, v180, v182
	global_store_dwordx4 v[188:189], v[200:203], off nt
	v_add_f32_e32 v151, 1.0, v151
	v_rcp_f32_e32 v151, v151
	v_mul_f32_e32 v201, v116, v178
	v_cvt_pk_bf16_f32 v178, v170, v172
	v_mul_f32_e32 v170, 0xbfb8aa3b, v130
	v_exp_f32_e32 v170, v170
	v_add_f32_e32 v149, 1.0, v152
	v_add_f32_e32 v150, 1.0, v150
	v_rcp_f32_e32 v149, v149
	v_rcp_f32_e32 v150, v150
	v_add_f32_e32 v170, 1.0, v170
	v_rcp_f32_e32 v179, v181
	v_rcp_f32_e32 v170, v170
	v_mul_f32_e32 v152, 0xbfb8aa3b, v36
	v_mul_f32_e32 v169, v35, v151
	v_mul_f32_e32 v151, 0xbfb8aa3b, v38
	v_exp_f32_e32 v152, v152
	v_exp_f32_e32 v151, v151
	v_add_f32_e32 v180, 1.0, v248
	v_mul_f32_e32 v181, 0xbfb8aa3b, v117
	v_mul_f32_e32 v183, v33, v149
	v_mul_f32_e32 v168, v34, v150
	v_mul_f32_e32 v150, 0xbfb8aa3b, v37
	v_rcp_f32_e32 v180, v180
	v_exp_f32_e32 v181, v181
	v_exp_f32_e32 v150, v150
	v_mul_f32_e32 v182, v114, v179
	v_cvt_pk_bf16_f32 v179, v173, v183
	v_mul_f32_e32 v183, v130, v170
	v_mul_f32_e32 v170, 0xbfb8aa3b, v126
	v_exp_f32_e32 v170, v170
	v_add_f32_e32 v149, 1.0, v152
	v_add_f32_e32 v151, 1.0, v151
	v_rcp_f32_e32 v149, v149
	v_rcp_f32_e32 v151, v151
	v_mul_f32_e32 v200, v115, v180
	v_add_f32_e32 v180, 1.0, v181
	v_add_f32_e32 v150, 1.0, v150
	v_rcp_f32_e32 v173, v180
	v_cvt_pk_bf16_f32 v180, v168, v169
	v_mul_f32_e32 v168, 0xbfb8aa3b, v132
	v_mul_f32_e32 v169, 0xbfb8aa3b, v133
	v_rcp_f32_e32 v150, v150
	v_exp_f32_e32 v168, v168
	v_exp_f32_e32 v169, v169
	v_add_f32_e32 v170, 1.0, v170
	v_rcp_f32_e32 v170, v170
	v_mul_f32_e32 v171, v36, v149
	v_mul_f32_e32 v149, v38, v151
	v_mul_f32_e32 v151, 0xbfb8aa3b, v40
	v_mul_f32_e32 v152, 0xbfb8aa3b, v39
	v_exp_f32_e32 v151, v151
	v_exp_f32_e32 v152, v152
	v_mul_f32_e32 v174, v37, v150
	v_add_f32_e32 v168, 1.0, v168
	v_cvt_pk_bf16_f32 v181, v171, v174
	v_add_f32_e32 v169, 1.0, v169
	v_mul_f32_e32 v171, 0xbfb8aa3b, v127
	v_rcp_f32_e32 v168, v168
	v_rcp_f32_e32 v169, v169
	v_exp_f32_e32 v171, v171
	v_mul_f32_e32 v203, v126, v170
	v_mul_f32_e32 v170, 0xbfb8aa3b, v129
	v_exp_f32_e32 v170, v170
	v_add_f32_e32 v151, 1.0, v151
	v_add_f32_e32 v150, 1.0, v152
	v_mul_f32_e32 v152, 0xbfb8aa3b, v41
	v_rcp_f32_e32 v151, v151
	v_exp_f32_e32 v152, v152
	v_mul_f32_e32 v174, v132, v168
	v_mul_f32_e32 v202, v133, v169
	v_add_f32_e32 v168, 1.0, v171
	v_mul_f32_e32 v169, 0xbfb8aa3b, v128
	v_exp_f32_e32 v169, v169
	v_rcp_f32_e32 v168, v168
	v_add_f32_e32 v170, 1.0, v170
	v_mul_f32_e32 v171, 0xbfb8aa3b, v122
	v_rcp_f32_e32 v170, v170
	v_exp_f32_e32 v171, v171
	v_mul_f32_e32 v153, 0xbfb8aa3b, v42
	v_mul_f32_e32 v154, v40, v151
	v_mul_f32_e32 v151, 0xbfb8aa3b, v43
	v_rcp_f32_e32 v150, v150
	v_add_f32_e32 v152, 1.0, v152
	v_exp_f32_e32 v156, v153
	v_exp_f32_e32 v151, v151
	v_rcp_f32_e32 v152, v152
	global_store_dwordx4 v[188:189], v[178:181], off offset:256 nt
	v_add_f32_e32 v169, 1.0, v169
	v_rcp_f32_e32 v169, v169
	v_mul_f32_e32 v178, v127, v168
	v_mul_f32_e32 v168, 0xbfb8aa3b, v123
	v_mul_f32_e32 v180, v129, v170
	v_add_f32_e32 v170, 1.0, v171
	v_exp_f32_e32 v171, v168
	v_mul_f32_e32 v153, v39, v150
	v_add_f32_e32 v150, 1.0, v156
	v_add_f32_e32 v151, 1.0, v151
	v_mul_f32_e32 v156, 0xbfb8aa3b, v45
	v_mul_f32_e32 v155, v41, v152
	v_mul_f32_e32 v152, 0xbfb8aa3b, v44
	v_rcp_f32_e32 v150, v150
	v_rcp_f32_e32 v151, v151
	v_exp_f32_e32 v158, v156
	v_exp_f32_e32 v152, v152
	v_mul_f32_e32 v179, v128, v169
	v_cvt_pk_bf16_f32 v168, v149, v153
	v_cvt_pk_bf16_f32 v169, v154, v155
	v_add_f32_e32 v154, 1.0, v171
	v_mul_f32_e32 v155, 0xbfb8aa3b, v125
	v_rcp_f32_e32 v153, v170
	v_rcp_f32_e32 v154, v154
	v_exp_f32_e32 v155, v155
	v_mul_f32_e32 v156, v42, v150
	v_mul_f32_e32 v157, v43, v151
	v_add_f32_e32 v150, 1.0, v158
	v_mul_f32_e32 v151, 0xbfb8aa3b, v46
	v_mul_f32_e32 v158, 0xbfb8aa3b, v47
	v_add_f32_e32 v152, 1.0, v152
	v_exp_f32_e32 v151, v151
	v_exp_f32_e32 v158, v158
	v_rcp_f32_e32 v152, v152
	v_mul_f32_e32 v185, 0xbfb8aa3b, v61
	v_mul_f32_e32 v181, v122, v153
	v_mul_f32_e32 v188, v123, v154
	v_add_f32_e32 v153, 1.0, v155
	v_mul_f32_e32 v154, 0xbfb8aa3b, v118
	v_rcp_f32_e32 v150, v150
	v_exp_f32_e32 v185, v185
	v_mul_f32_e32 v186, 0xbfb8aa3b, v62
	v_rcp_f32_e32 v153, v153
	v_exp_f32_e32 v154, v154
	v_mul_f32_e32 v184, 0xbfb8aa3b, v60
	v_exp_f32_e32 v186, v186
	v_add_f32_e32 v151, 1.0, v151
	v_add_f32_e32 v158, 1.0, v158
	v_mul_f32_e32 v159, 0xbfb8aa3b, v48
	v_exp_f32_e32 v184, v184
	v_mul_f32_e32 v210, 0xbfb8aa3b, v71
	v_mul_f32_e32 v155, 0xbfb8aa3b, v119
	v_mul_f32_e32 v152, v44, v152
	v_rcp_f32_e32 v151, v151
	v_rcp_f32_e32 v158, v158
	v_exp_f32_e32 v159, v159
	v_mul_f32_e32 v207, 0xbfb8aa3b, v69
	v_mul_f32_e32 v208, 0xbfb8aa3b, v70
	v_exp_f32_e32 v210, v210
	v_mul_f32_e32 v226, 0xbfb8aa3b, v85
	v_exp_f32_e32 v155, v155
	v_mul_f32_e32 v161, v45, v150
	v_add_f32_e32 v185, 1.0, v185
	v_exp_f32_e32 v207, v207
	v_exp_f32_e32 v208, v208
	v_exp_f32_e32 v226, v226
	v_mul_f32_e32 v227, 0xbfb8aa3b, v86
	v_cvt_pk_bf16_f32 v170, v156, v157
	v_mul_f32_e32 v156, v125, v153
	v_add_f32_e32 v153, 1.0, v154
	v_cvt_pk_bf16_f32 v171, v152, v161
	v_or_b32_e32 v152, 32, v140
	v_rcp_f32_e32 v190, v185
	v_add_f32_e32 v185, 1.0, v186
	v_mul_f32_e32 v225, 0xbfb8aa3b, v84
	v_exp_f32_e32 v227, v227
	v_mul_f32_e32 v236, 0xbfb8aa3b, v95
	v_rcp_f32_e32 v157, v153
	v_ashrrev_i32_e32 v153, 31, v152
	v_add_f32_e32 v184, 1.0, v184
	v_rcp_f32_e32 v191, v185
	v_mul_f32_e32 v185, 0xbfb8aa3b, v63
	v_exp_f32_e32 v225, v225
	v_mul_f32_e32 v234, 0xbfb8aa3b, v93
	v_mul_f32_e32 v235, 0xbfb8aa3b, v94
	v_exp_f32_e32 v236, v236
	v_lshlrev_b64 v[152:153], 13, v[152:153]
	v_mul_f32_e32 v150, v46, v151
	v_mul_f32_e32 v151, v47, v158
	v_add_f32_e32 v158, 1.0, v159
	v_mul_f32_e32 v159, 0xbfb8aa3b, v49
	v_mul_f32_e32 v160, 0xbfb8aa3b, v50
	v_mul_f32_e32 v162, 0xbfb8aa3b, v51
	v_mul_f32_e32 v163, 0xbfb8aa3b, v52
	v_mul_f32_e32 v164, 0xbfb8aa3b, v53
	v_rcp_f32_e32 v184, v184
	v_exp_f32_e32 v193, v185
	v_add_f32_e32 v210, 1.0, v210
	v_exp_f32_e32 v234, v234
	v_exp_f32_e32 v235, v235
	v_add_f32_e32 v189, 1.0, v155
	v_lshl_add_u64 v[154:155], v[146:147], 0, v[152:153]
	v_mul_f32_e32 v152, 0xbfb8aa3b, v120
	v_mul_f32_e32 v153, 0xbfb8aa3b, v121
	v_exp_f32_e32 v159, v159
	v_exp_f32_e32 v160, v160
	v_exp_f32_e32 v162, v162
	v_exp_f32_e32 v163, v163
	v_exp_f32_e32 v164, v164
	v_add_f32_e32 v207, 1.0, v207
	v_add_f32_e32 v208, 1.0, v208
	v_rcp_f32_e32 v211, v210
	v_mul_f32_e32 v210, 0xbfb8aa3b, v72
	v_add_f32_e32 v226, 1.0, v226
	v_exp_f32_e32 v152, v152
	v_exp_f32_e32 v153, v153
	v_rcp_f32_e32 v207, v207
	v_rcp_f32_e32 v208, v208
	v_exp_f32_e32 v212, v210
	v_rcp_f32_e32 v228, v226
	v_add_f32_e32 v226, 1.0, v227
	v_mul_f32_e32 v165, 0xbfb8aa3b, v54
	v_mul_f32_e32 v166, 0xbfb8aa3b, v55
	v_mul_f32_e32 v167, 0xbfb8aa3b, v56
	v_mul_f32_e32 v175, 0xbfb8aa3b, v57
	v_add_f32_e32 v225, 1.0, v225
	v_rcp_f32_e32 v229, v226
	v_mul_f32_e32 v226, 0xbfb8aa3b, v87
	v_add_f32_e32 v236, 1.0, v236
	v_exp_f32_e32 v165, v165
	v_exp_f32_e32 v166, v166
	v_exp_f32_e32 v167, v167
	v_exp_f32_e32 v175, v175
	v_mul_f32_e32 v176, 0xbfb8aa3b, v58
	v_mul_f32_e32 v177, 0xbfb8aa3b, v59
	v_mul_f32_e32 v185, v60, v184
	v_mul_f32_e32 v186, v61, v190
	v_mul_f32_e32 v184, v62, v191
	v_add_f32_e32 v190, 1.0, v193
	v_mul_f32_e32 v191, 0xbfb8aa3b, v64
	v_mul_f32_e32 v193, 0xbfb8aa3b, v65
	v_rcp_f32_e32 v225, v225
	v_exp_f32_e32 v230, v226
	v_add_f32_e32 v234, 1.0, v234
	v_add_f32_e32 v235, 1.0, v235
	v_rcp_f32_e32 v237, v236
	v_mul_f32_e32 v236, 0xbfb8aa3b, v96
	v_add_f32_e32 v159, 1.0, v159
	v_add_f32_e32 v160, 1.0, v160
	v_add_f32_e32 v162, 1.0, v162
	v_add_f32_e32 v163, 1.0, v163
	v_add_f32_e32 v164, 1.0, v164
	v_exp_f32_e32 v176, v176
	v_exp_f32_e32 v177, v177
	v_exp_f32_e32 v191, v191
	v_exp_f32_e32 v193, v193
	v_mul_f32_e32 v196, 0xbfb8aa3b, v66
	v_mul_f32_e32 v198, 0xbfb8aa3b, v67
	v_mul_f32_e32 v199, 0xbfb8aa3b, v68
	v_rcp_f32_e32 v234, v234
	v_rcp_f32_e32 v235, v235
	v_exp_f32_e32 v238, v236
	v_add_f32_e32 v152, 1.0, v152
	v_add_f32_e32 v153, 1.0, v153
	v_rcp_f32_e32 v158, v158
	v_rcp_f32_e32 v159, v159
	v_rcp_f32_e32 v160, v160
	v_rcp_f32_e32 v162, v162
	v_rcp_f32_e32 v163, v163
	v_rcp_f32_e32 v164, v164
	v_exp_f32_e32 v196, v196
	v_exp_f32_e32 v198, v198
	v_exp_f32_e32 v199, v199
	v_mul_f32_e32 v210, v69, v207
	v_mul_f32_e32 v207, v70, v208
	v_mul_f32_e32 v208, v71, v211
	v_add_f32_e32 v211, 1.0, v212
	v_mul_f32_e32 v212, 0xbfb8aa3b, v73
	v_mul_f32_e32 v213, 0xbfb8aa3b, v74
	v_mul_f32_e32 v216, 0xbfb8aa3b, v75
	v_mul_f32_e32 v217, 0xbfb8aa3b, v76
	v_mul_f32_e32 v218, 0xbfb8aa3b, v77
	v_rcp_f32_e32 v152, v152
	v_rcp_f32_e32 v153, v153
	v_exp_f32_e32 v212, v212
	v_exp_f32_e32 v213, v213
	v_exp_f32_e32 v216, v216
	v_exp_f32_e32 v217, v217
	v_exp_f32_e32 v218, v218
	v_mul_f32_e32 v219, 0xbfb8aa3b, v78
	v_mul_f32_e32 v220, 0xbfb8aa3b, v79
	v_mul_f32_e32 v221, 0xbfb8aa3b, v80
	v_mul_f32_e32 v222, 0xbfb8aa3b, v81
	v_mul_f32_e32 v223, 0xbfb8aa3b, v82
	v_mul_f32_e32 v224, 0xbfb8aa3b, v83
	v_add_f32_e32 v165, 1.0, v165
	v_add_f32_e32 v166, 1.0, v166
	v_add_f32_e32 v167, 1.0, v167
	v_add_f32_e32 v175, 1.0, v175
	v_exp_f32_e32 v219, v219
	v_exp_f32_e32 v220, v220
	v_exp_f32_e32 v221, v221
	v_exp_f32_e32 v222, v222
	v_exp_f32_e32 v223, v223
	v_exp_f32_e32 v224, v224
	v_mul_f32_e32 v226, v84, v225
	v_mul_f32_e32 v227, v85, v228
	v_mul_f32_e32 v225, v86, v229
	v_add_f32_e32 v228, 1.0, v230
	v_mul_f32_e32 v229, 0xbfb8aa3b, v88
	v_mul_f32_e32 v230, 0xbfb8aa3b, v89
	v_mul_f32_e32 v231, 0xbfb8aa3b, v90
	v_mul_f32_e32 v232, 0xbfb8aa3b, v91
	v_mul_f32_e32 v233, 0xbfb8aa3b, v92
	v_rcp_f32_e32 v165, v165
	v_rcp_f32_e32 v166, v166
	v_rcp_f32_e32 v167, v167
	v_rcp_f32_e32 v175, v175
	v_add_f32_e32 v176, 1.0, v176
	v_add_f32_e32 v177, 1.0, v177
	v_add_f32_e32 v191, 1.0, v191
	v_add_f32_e32 v193, 1.0, v193
	v_exp_f32_e32 v229, v229
	v_exp_f32_e32 v230, v230
	v_exp_f32_e32 v231, v231
	v_exp_f32_e32 v232, v232
	v_exp_f32_e32 v233, v233
	v_mul_f32_e32 v236, v93, v234
	v_mul_f32_e32 v234, v94, v235
	v_mul_f32_e32 v235, v95, v237
	v_add_f32_e32 v237, 1.0, v238
	v_mul_f32_e32 v238, 0xbfb8aa3b, v97
	v_mul_f32_e32 v239, 0xbfb8aa3b, v98
	global_store_dwordx4 v[154:155], v[168:171], off nt
	v_cvt_pk_bf16_f32 v150, v150, v151
	v_mul_f32_e32 v158, v48, v158
	v_mul_f32_e32 v159, v49, v159
	v_mul_f32_e32 v160, v50, v160
	v_mul_f32_e32 v162, v51, v162
	v_mul_f32_e32 v163, v52, v163
	v_mul_f32_e32 v164, v53, v164
	v_rcp_f32_e32 v176, v176
	v_rcp_f32_e32 v177, v177
	v_rcp_f32_e32 v190, v190
	v_rcp_f32_e32 v191, v191
	v_rcp_f32_e32 v193, v193
	v_add_f32_e32 v196, 1.0, v196
	v_add_f32_e32 v198, 1.0, v198
	v_add_f32_e32 v199, 1.0, v199
	v_exp_f32_e32 v238, v238
	v_exp_f32_e32 v239, v239
	v_mul_f32_e32 v194, 0xbfb8aa3b, v104
	v_mul_f32_e32 v192, 0xbfb8aa3b, v108
	v_mul_f32_e32 v168, v120, v152
	v_mul_f32_e32 v169, v121, v153
	v_cvt_pk_bf16_f32 v151, v158, v159
	v_cvt_pk_bf16_f32 v152, v160, v162
	v_cvt_pk_bf16_f32 v153, v163, v164
	global_store_dwordx4 v[154:155], v[150:153], off offset:256 nt
	v_rcp_f32_e32 v196, v196
	v_rcp_f32_e32 v198, v198
	v_or_b32_e32 v150, 48, v140
	v_rcp_f32_e32 v199, v199
	v_add_f32_e32 v212, 1.0, v212
	v_add_f32_e32 v213, 1.0, v213
	v_add_f32_e32 v216, 1.0, v216
	v_add_f32_e32 v217, 1.0, v217
	v_add_f32_e32 v218, 1.0, v218
	v_exp_f32_e32 v194, v194
	v_exp_f32_e32 v192, v192
	v_ashrrev_i32_e32 v151, 31, v150
	v_rcp_f32_e32 v211, v211
	v_rcp_f32_e32 v212, v212
	v_rcp_f32_e32 v213, v213
	v_rcp_f32_e32 v216, v216
	v_rcp_f32_e32 v217, v217
	v_rcp_f32_e32 v218, v218
	v_add_f32_e32 v219, 1.0, v219
	v_add_f32_e32 v220, 1.0, v220
	v_add_f32_e32 v221, 1.0, v221
	v_add_f32_e32 v222, 1.0, v222
	v_add_f32_e32 v223, 1.0, v223
	v_add_f32_e32 v224, 1.0, v224
	v_mul_f32_e32 v172, 0xbfb8aa3b, v131
	v_mul_f32_e32 v149, 0xbfb8aa3b, v124
	v_lshlrev_b64 v[150:151], 13, v[150:151]
	v_mul_f32_e32 v165, v54, v165
	v_mul_f32_e32 v166, v55, v166
	v_mul_f32_e32 v167, v56, v167
	v_mul_f32_e32 v175, v57, v175
	v_rcp_f32_e32 v219, v219
	v_rcp_f32_e32 v220, v220
	v_rcp_f32_e32 v221, v221
	v_rcp_f32_e32 v222, v222
	v_rcp_f32_e32 v223, v223
	v_rcp_f32_e32 v224, v224
	v_add_f32_e32 v229, 1.0, v229
	v_add_f32_e32 v230, 1.0, v230
	v_add_f32_e32 v231, 1.0, v231
	v_add_f32_e32 v232, 1.0, v232
	v_add_f32_e32 v233, 1.0, v233
	v_exp_f32_e32 v172, v172
	v_exp_f32_e32 v149, v149
	v_lshl_add_u64 v[154:155], v[146:147], 0, v[150:151]
	v_cvt_pk_bf16_f32 v150, v165, v166
	v_cvt_pk_bf16_f32 v151, v167, v175
	v_mul_f32_e32 v176, v58, v176
	v_mul_f32_e32 v177, v59, v177
	v_mul_f32_e32 v190, v63, v190
	v_mul_f32_e32 v191, v64, v191
	v_mul_f32_e32 v193, v65, v193
	v_rcp_f32_e32 v228, v228
	v_rcp_f32_e32 v229, v229
	v_rcp_f32_e32 v230, v230
	v_rcp_f32_e32 v231, v231
	v_rcp_f32_e32 v232, v232
	v_rcp_f32_e32 v233, v233
	v_add_f32_e32 v238, 1.0, v238
	v_add_f32_e32 v239, 1.0, v239
	v_cvt_pk_bf16_f32 v152, v176, v177
	v_cvt_pk_bf16_f32 v153, v185, v186
	global_store_dwordx4 v[154:155], v[150:153], off nt
	v_mul_f32_e32 v196, v66, v196
	v_mul_f32_e32 v198, v67, v198
	v_cvt_pk_bf16_f32 v150, v184, v190
	v_cvt_pk_bf16_f32 v151, v191, v193
	v_mul_f32_e32 v199, v68, v199
	v_rcp_f32_e32 v237, v237
	v_rcp_f32_e32 v238, v238
	v_rcp_f32_e32 v239, v239
	v_add_f32_e32 v194, 1.0, v194
	v_add_f32_e32 v192, 1.0, v192
	v_cvt_pk_bf16_f32 v152, v196, v198
	v_cvt_pk_bf16_f32 v153, v199, v210
	global_store_dwordx4 v[154:155], v[150:153], off offset:256 nt
	v_mul_f32_e32 v211, v72, v211
	v_mul_f32_e32 v212, v73, v212
	v_lshlrev_b64 v[150:151], 13, v[142:143]
	v_mul_f32_e32 v213, v74, v213
	v_mul_f32_e32 v216, v75, v216
	v_mul_f32_e32 v217, v76, v217
	v_mul_f32_e32 v218, v77, v218
	v_rcp_f32_e32 v194, v194
	v_rcp_f32_e32 v192, v192
	v_lshl_add_u64 v[146:147], v[146:147], 0, v[150:151]
	v_cvt_pk_bf16_f32 v150, v207, v208
	v_cvt_pk_bf16_f32 v151, v211, v212
	v_cvt_pk_bf16_f32 v152, v213, v216
	v_cvt_pk_bf16_f32 v153, v217, v218
	v_add_co_u32_e32 v154, vcc, s72, v144
	v_mul_f32_e32 v219, v78, v219
	v_mul_f32_e32 v220, v79, v220
	v_mul_f32_e32 v221, v80, v221
	v_mul_f32_e32 v222, v81, v222
	v_mul_f32_e32 v223, v82, v223
	v_mul_f32_e32 v224, v83, v224
	v_add_f32_e32 v172, 1.0, v172
	v_add_f32_e32 v149, 1.0, v149
	global_store_dwordx4 v[146:147], v[150:153], off nt
	s_mov_b64 s[26:27], 0x120000
	v_addc_co_u32_e32 v155, vcc, 0, v145, vcc
	v_cvt_pk_bf16_f32 v150, v219, v220
	v_cvt_pk_bf16_f32 v151, v221, v222
	v_cvt_pk_bf16_f32 v152, v223, v224
	v_cvt_pk_bf16_f32 v153, v226, v227
	global_store_dwordx4 v[146:147], v[150:153], off offset:256 nt
	v_mul_f32_e32 v228, v87, v228
	v_mul_f32_e32 v229, v88, v229
	v_mul_f32_e32 v230, v89, v230
	v_mul_f32_e32 v231, v90, v231
	v_mul_f32_e32 v232, v91, v232
	v_mul_f32_e32 v233, v92, v233
	v_rcp_f32_e32 v172, v172
	v_rcp_f32_e32 v149, v149
	v_rcp_f32_e32 v161, v189
	v_lshl_add_u64 v[146:147], v[144:145], 0, s[26:27]
	v_cvt_pk_bf16_f32 v150, v225, v228
	v_cvt_pk_bf16_f32 v151, v229, v230
	v_cvt_pk_bf16_f32 v152, v231, v232
	v_cvt_pk_bf16_f32 v153, v233, v236
	global_store_dwordx4 v[154:155], v[150:153], off nt
	s_mov_b64 s[26:27], 0x140000
	v_add_co_u32_e32 v154, vcc, s73, v144
	v_mul_f32_e32 v237, v96, v237
	v_mul_f32_e32 v238, v97, v238
	v_mul_f32_e32 v239, v98, v239
	v_mul_f32_e32 v195, v99, v195
	v_cvt_pk_bf16_f32 v150, v234, v235
	v_cvt_pk_bf16_f32 v151, v237, v238
	v_cvt_pk_bf16_f32 v152, v239, v195
	v_cvt_pk_bf16_f32 v153, v206, v209
	global_store_dwordx4 v[146:147], v[150:153], off offset:256 nt
	v_lshl_add_u64 v[146:147], v[144:145], 0, s[26:27]
	v_addc_co_u32_e32 v155, vcc, 0, v145, vcc
	s_mov_b64 s[26:27], 0x160000
	v_mul_f32_e32 v194, v104, v194
	v_mul_f32_e32 v192, v108, v192
	v_cvt_pk_bf16_f32 v150, v241, v242
	v_cvt_pk_bf16_f32 v151, v194, v197
	v_cvt_pk_bf16_f32 v152, v240, v243
	v_cvt_pk_bf16_f32 v153, v192, v204
	global_store_dwordx4 v[154:155], v[150:153], off nt
	v_lshl_add_u64 v[154:155], v[144:145], 0, s[26:27]
	v_add_co_u32_e32 v144, vcc, 0x160000, v144
	v_mul_f32_e32 v173, v117, v173
	v_cvt_pk_bf16_f32 v150, v205, v187
	v_cvt_pk_bf16_f32 v151, v244, v245
	v_cvt_pk_bf16_f32 v152, v182, v200
	v_cvt_pk_bf16_f32 v153, v201, v173
	global_store_dwordx4 v[146:147], v[150:153], off offset:256 nt
	v_addc_co_u32_e32 v145, vcc, 0, v145, vcc
	v_mul_f32_e32 v172, v131, v172
	v_mul_f32_e32 v149, v124, v149
	v_mul_f32_e32 v157, v118, v157
	v_mul_f32_e32 v161, v119, v161
	v_cvt_pk_bf16_f32 v150, v183, v172
	v_cvt_pk_bf16_f32 v151, v174, v202
	v_cvt_pk_bf16_f32 v152, v203, v178
	v_cvt_pk_bf16_f32 v153, v179, v180
	global_store_dwordx4 v[144:145], v[150:153], off nt
	v_cvt_pk_bf16_f32 v144, v181, v188
	v_cvt_pk_bf16_f32 v145, v149, v156
	v_cvt_pk_bf16_f32 v146, v157, v161
	v_cvt_pk_bf16_f32 v147, v168, v169
	global_store_dwordx4 v[154:155], v[144:147], off offset:256 nt
	s_mov_b64 s[26:27], 0

.LBB0_346:
	s_add_u32 s54, s33, 0xffffff80
	s_addc_u32 s55, s52, -1
	s_cmp_eq_u32 s53, 60
	s_cselect_b32 s28, s2, s33
	s_cselect_b32 s29, s1, s52
	s_cselect_b32 s31, s11, s23
	s_cselect_b32 s30, s15, s19
	s_add_u32 s24, s28, 0x80
	s_addc_u32 s25, s29, 0
	s_add_u32 s26, s30, 0x80
	s_addc_u32 s27, s31, 0
	s_add_i32 s56, 0, 0x10000
	s_add_i32 s57, 0, 0x14000
	v_add_u32_e32 v152, s56, v1
	v_add_u32_e32 v168, s57, v1
	ds_read_b128 v[140:143], v152
	ds_read_b128 v[144:147], v152 offset:1024
	ds_read_b128 v[148:151], v152 offset:2048
	ds_read_b128 v[152:155], v152 offset:3072
	ds_read_b128 v[156:159], v168
	ds_read_b128 v[160:163], v168 offset:1024
	ds_read_b128 v[164:167], v168 offset:2048
	ds_read_b128 v[168:171], v168 offset:3072
	s_add_u32 s54, s54, 0x100000
	s_addc_u32 s55, s55, 0
	v_lshl_add_u64 v[204:205], s[54:55], 0, v[2:3]
	s_add_i32 m0, s41, 0xc000
	ds_read_b128 v[172:175], v5
	ds_read_b128 v[176:179], v5 offset:1024
	ds_read_b128 v[180:183], v5 offset:2048
	ds_read_b128 v[184:187], v5 offset:3072
	ds_read_b128 v[188:191], v5 offset:4096
	ds_read_b128 v[192:195], v5 offset:5120
	ds_read_b128 v[196:199], v5 offset:6144
	ds_read_b128 v[200:203], v5 offset:7168
	global_load_lds_dwordx4 v[204:205], off
	v_lshl_add_u64 v[204:205], s[54:55], 0, v[136:137]
	s_add_i32 m0, s41, 0xe000
	s_nop 0
	global_load_lds_dwordx4 v[204:205], off
	s_waitcnt vmcnt(8) lgkmcnt(0)
	s_barrier
	s_setprio 1
	v_mfma_f32_16x16x32_bf16 v[130:133], v[140:143], v[172:175], v[130:133]
	v_mfma_f32_16x16x32_bf16 v[126:129], v[148:151], v[172:175], v[126:129]
	v_mfma_f32_16x16x32_bf16 v[114:117], v[140:143], v[180:183], v[114:117]
	v_mfma_f32_16x16x32_bf16 v[110:113], v[148:151], v[180:183], v[110:113]
	v_mfma_f32_16x16x32_bf16 v[98:101], v[140:143], v[188:191], v[98:101]
	v_mfma_f32_16x16x32_bf16 v[94:97], v[148:151], v[188:191], v[94:97]
	v_mfma_f32_16x16x32_bf16 v[82:85], v[140:143], v[196:199], v[82:85]
	v_mfma_f32_16x16x32_bf16 v[78:81], v[148:151], v[196:199], v[78:81]
	v_mfma_f32_16x16x32_bf16 v[130:133], v[144:147], v[176:179], v[130:133]
	v_mfma_f32_16x16x32_bf16 v[126:129], v[152:155], v[176:179], v[126:129]
	v_mfma_f32_16x16x32_bf16 v[114:117], v[144:147], v[184:187], v[114:117]
	v_mfma_f32_16x16x32_bf16 v[110:113], v[152:155], v[184:187], v[110:113]
	v_mfma_f32_16x16x32_bf16 v[98:101], v[144:147], v[192:195], v[98:101]
	v_mfma_f32_16x16x32_bf16 v[94:97], v[152:155], v[192:195], v[94:97]
	v_mfma_f32_16x16x32_bf16 v[82:85], v[144:147], v[200:203], v[82:85]
	v_mfma_f32_16x16x32_bf16 v[78:81], v[152:155], v[200:203], v[78:81]
	s_setprio 0
	s_setprio 1
	v_mfma_f32_16x16x32_bf16 v[122:125], v[156:159], v[172:175], v[122:125]
	v_mfma_f32_16x16x32_bf16 v[118:121], v[164:167], v[172:175], v[118:121]
	v_mfma_f32_16x16x32_bf16 v[106:109], v[156:159], v[180:183], v[106:109]
	v_mfma_f32_16x16x32_bf16 v[102:105], v[164:167], v[180:183], v[102:105]
	v_mfma_f32_16x16x32_bf16 v[90:93], v[156:159], v[188:191], v[90:93]
	v_mfma_f32_16x16x32_bf16 v[86:89], v[164:167], v[188:191], v[86:89]
	v_mfma_f32_16x16x32_bf16 v[74:77], v[156:159], v[196:199], v[74:77]
	v_mfma_f32_16x16x32_bf16 v[70:73], v[164:167], v[196:199], v[70:73]
	v_mfma_f32_16x16x32_bf16 v[122:125], v[160:163], v[176:179], v[122:125]
	v_mfma_f32_16x16x32_bf16 v[118:121], v[168:171], v[176:179], v[118:121]
	v_mfma_f32_16x16x32_bf16 v[106:109], v[160:163], v[184:187], v[106:109]
	v_mfma_f32_16x16x32_bf16 v[102:105], v[168:171], v[184:187], v[102:105]
	v_mfma_f32_16x16x32_bf16 v[90:93], v[160:163], v[192:195], v[90:93]
	v_mfma_f32_16x16x32_bf16 v[86:89], v[168:171], v[192:195], v[86:89]
	v_mfma_f32_16x16x32_bf16 v[74:77], v[160:163], v[200:203], v[74:77]
	v_mfma_f32_16x16x32_bf16 v[70:73], v[168:171], v[200:203], v[70:73]
	s_setprio 0
	s_barrier
	s_add_i32 s54, s56, s38
	v_lshl_add_u64 v[204:205], s[30:31], 0, v[134:135]
	s_mov_b32 m0, s54
	ds_read_b128 v[172:175], v5 offset:16384
	ds_read_b128 v[176:179], v5 offset:17408
	ds_read_b128 v[180:183], v5 offset:18432
	ds_read_b128 v[184:187], v5 offset:19456
	ds_read_b128 v[188:191], v5 offset:20480
	ds_read_b128 v[192:195], v5 offset:21504
	ds_read_b128 v[196:199], v5 offset:22528
	ds_read_b128 v[200:203], v5 offset:23552
	global_load_lds_dwordx4 v[204:205], off
	s_add_i32 m0, s54, 0x2000
	v_lshl_add_u64 v[204:205], s[30:31], 0, v[138:139]
	s_add_u32 s30, s30, 0x100000
	s_addc_u32 s31, s31, 0
	s_add_i32 s54, s57, s38
	global_load_lds_dwordx4 v[204:205], off
	v_lshl_add_u64 v[204:205], s[30:31], 0, v[134:135]
	s_mov_b32 m0, s54
	s_nop 0
	global_load_lds_dwordx4 v[204:205], off
	v_lshl_add_u64 v[204:205], s[30:31], 0, v[138:139]
	s_add_i32 m0, s54, 0x2000
	s_nop 0
	global_load_lds_dwordx4 v[204:205], off
	v_lshl_add_u64 v[204:205], s[28:29], 0, v[2:3]
	s_mov_b32 m0, s41
	s_nop 0
	global_load_lds_dwordx4 v[204:205], off
	v_lshl_add_u64 v[204:205], s[28:29], 0, v[136:137]
	s_mov_b32 m0, s3
	s_nop 0
	global_load_lds_dwordx4 v[204:205], off
	s_waitcnt vmcnt(8) lgkmcnt(0)
	s_barrier
	s_setprio 1
	v_mfma_f32_16x16x32_bf16 v[66:69], v[140:143], v[172:175], v[66:69]
	v_mfma_f32_16x16x32_bf16 v[62:65], v[148:151], v[172:175], v[62:65]
	v_mfma_f32_16x16x32_bf16 v[50:53], v[140:143], v[180:183], v[50:53]
	v_mfma_f32_16x16x32_bf16 v[46:49], v[148:151], v[180:183], v[46:49]
	v_mfma_f32_16x16x32_bf16 v[34:37], v[140:143], v[188:191], v[34:37]
	v_mfma_f32_16x16x32_bf16 v[30:33], v[148:151], v[188:191], v[30:33]
	v_mfma_f32_16x16x32_bf16 v[18:21], v[140:143], v[196:199], v[18:21]
	v_mfma_f32_16x16x32_bf16 v[14:17], v[148:151], v[196:199], v[14:17]
	v_mfma_f32_16x16x32_bf16 v[66:69], v[144:147], v[176:179], v[66:69]
	v_mfma_f32_16x16x32_bf16 v[62:65], v[152:155], v[176:179], v[62:65]
	v_mfma_f32_16x16x32_bf16 v[50:53], v[144:147], v[184:187], v[50:53]
	v_mfma_f32_16x16x32_bf16 v[46:49], v[152:155], v[184:187], v[46:49]
	v_mfma_f32_16x16x32_bf16 v[34:37], v[144:147], v[192:195], v[34:37]
	v_mfma_f32_16x16x32_bf16 v[30:33], v[152:155], v[192:195], v[30:33]
	v_mfma_f32_16x16x32_bf16 v[18:21], v[144:147], v[200:203], v[18:21]
	v_mfma_f32_16x16x32_bf16 v[14:17], v[152:155], v[200:203], v[14:17]
	s_setprio 0
	s_setprio 1
	v_mfma_f32_16x16x32_bf16 v[58:61], v[156:159], v[172:175], v[58:61]
	v_mfma_f32_16x16x32_bf16 v[54:57], v[164:167], v[172:175], v[54:57]
	v_mfma_f32_16x16x32_bf16 v[42:45], v[156:159], v[180:183], v[42:45]
	v_mfma_f32_16x16x32_bf16 v[38:41], v[164:167], v[180:183], v[38:41]
	v_mfma_f32_16x16x32_bf16 v[26:29], v[156:159], v[188:191], v[26:29]
	v_mfma_f32_16x16x32_bf16 v[22:25], v[164:167], v[188:191], v[22:25]
	v_mfma_f32_16x16x32_bf16 v[10:13], v[156:159], v[196:199], v[10:13]
	v_mfma_f32_16x16x32_bf16 v[6:9], v[164:167], v[196:199], v[6:9]
	v_mfma_f32_16x16x32_bf16 v[58:61], v[160:163], v[176:179], v[58:61]
	v_mfma_f32_16x16x32_bf16 v[54:57], v[168:171], v[176:179], v[54:57]
	v_mfma_f32_16x16x32_bf16 v[42:45], v[160:163], v[184:187], v[42:45]
	v_mfma_f32_16x16x32_bf16 v[38:41], v[168:171], v[184:187], v[38:41]
	v_mfma_f32_16x16x32_bf16 v[26:29], v[160:163], v[192:195], v[26:29]
	v_mfma_f32_16x16x32_bf16 v[22:25], v[168:171], v[192:195], v[22:25]
	v_mfma_f32_16x16x32_bf16 v[10:13], v[160:163], v[200:203], v[10:13]
	v_mfma_f32_16x16x32_bf16 v[6:9], v[168:171], v[200:203], v[6:9]
	s_setprio 0
	s_barrier
	s_add_i32 s30, 0, 0x18000
	s_add_i32 s31, 0, 0x1c000
	v_add_u32_e32 v152, s30, v1
	v_add_u32_e32 v168, s31, v1
	ds_read_b128 v[140:143], v152
	ds_read_b128 v[144:147], v152 offset:1024
	ds_read_b128 v[148:151], v152 offset:2048
	ds_read_b128 v[152:155], v152 offset:3072
	ds_read_b128 v[156:159], v168
	ds_read_b128 v[160:163], v168 offset:1024
	ds_read_b128 v[164:167], v168 offset:2048
	ds_read_b128 v[168:171], v168 offset:3072
	s_add_u32 s28, s28, 0x100000
	s_addc_u32 s29, s29, 0
	s_mov_b32 m0, s43
	v_lshl_add_u64 v[204:205], s[28:29], 0, v[2:3]
	ds_read_b128 v[172:175], v5 offset:32768
	ds_read_b128 v[176:179], v5 offset:33792
	ds_read_b128 v[180:183], v5 offset:34816
	ds_read_b128 v[184:187], v5 offset:35840
	ds_read_b128 v[188:191], v5 offset:36864
	ds_read_b128 v[192:195], v5 offset:37888
	ds_read_b128 v[196:199], v5 offset:38912
	ds_read_b128 v[200:203], v5 offset:39936
	global_load_lds_dwordx4 v[204:205], off
	v_lshl_add_u64 v[204:205], s[28:29], 0, v[136:137]
	s_mov_b32 m0, s46
	s_nop 0
	global_load_lds_dwordx4 v[204:205], off
	s_waitcnt vmcnt(8) lgkmcnt(0)
	s_barrier
	s_setprio 1
	v_mfma_f32_16x16x32_bf16 v[130:133], v[140:143], v[172:175], v[130:133]
	v_mfma_f32_16x16x32_bf16 v[126:129], v[148:151], v[172:175], v[126:129]
	v_mfma_f32_16x16x32_bf16 v[114:117], v[140:143], v[180:183], v[114:117]
	v_mfma_f32_16x16x32_bf16 v[110:113], v[148:151], v[180:183], v[110:113]
	v_mfma_f32_16x16x32_bf16 v[98:101], v[140:143], v[188:191], v[98:101]
	v_mfma_f32_16x16x32_bf16 v[94:97], v[148:151], v[188:191], v[94:97]
	v_mfma_f32_16x16x32_bf16 v[82:85], v[140:143], v[196:199], v[82:85]
	v_mfma_f32_16x16x32_bf16 v[78:81], v[148:151], v[196:199], v[78:81]
	v_mfma_f32_16x16x32_bf16 v[130:133], v[144:147], v[176:179], v[130:133]
	v_mfma_f32_16x16x32_bf16 v[126:129], v[152:155], v[176:179], v[126:129]
	v_mfma_f32_16x16x32_bf16 v[114:117], v[144:147], v[184:187], v[114:117]
	v_mfma_f32_16x16x32_bf16 v[110:113], v[152:155], v[184:187], v[110:113]
	v_mfma_f32_16x16x32_bf16 v[98:101], v[144:147], v[192:195], v[98:101]
	v_mfma_f32_16x16x32_bf16 v[94:97], v[152:155], v[192:195], v[94:97]
	v_mfma_f32_16x16x32_bf16 v[82:85], v[144:147], v[200:203], v[82:85]
	v_mfma_f32_16x16x32_bf16 v[78:81], v[152:155], v[200:203], v[78:81]
	s_setprio 0
	s_setprio 1
	v_mfma_f32_16x16x32_bf16 v[122:125], v[156:159], v[172:175], v[122:125]
	v_mfma_f32_16x16x32_bf16 v[118:121], v[164:167], v[172:175], v[118:121]
	v_mfma_f32_16x16x32_bf16 v[106:109], v[156:159], v[180:183], v[106:109]
	v_mfma_f32_16x16x32_bf16 v[102:105], v[164:167], v[180:183], v[102:105]
	v_mfma_f32_16x16x32_bf16 v[90:93], v[156:159], v[188:191], v[90:93]
	v_mfma_f32_16x16x32_bf16 v[86:89], v[164:167], v[188:191], v[86:89]
	v_mfma_f32_16x16x32_bf16 v[74:77], v[156:159], v[196:199], v[74:77]
	v_mfma_f32_16x16x32_bf16 v[70:73], v[164:167], v[196:199], v[70:73]
	v_mfma_f32_16x16x32_bf16 v[122:125], v[160:163], v[176:179], v[122:125]
	v_mfma_f32_16x16x32_bf16 v[118:121], v[168:171], v[176:179], v[118:121]
	v_mfma_f32_16x16x32_bf16 v[106:109], v[160:163], v[184:187], v[106:109]
	v_mfma_f32_16x16x32_bf16 v[102:105], v[168:171], v[184:187], v[102:105]
	v_mfma_f32_16x16x32_bf16 v[90:93], v[160:163], v[192:195], v[90:93]
	v_mfma_f32_16x16x32_bf16 v[86:89], v[168:171], v[192:195], v[86:89]
	v_mfma_f32_16x16x32_bf16 v[74:77], v[160:163], v[200:203], v[74:77]
	v_mfma_f32_16x16x32_bf16 v[70:73], v[168:171], v[200:203], v[70:73]
	s_setprio 0
	s_barrier
	s_add_i32 s28, s30, s38
	v_lshl_add_u64 v[204:205], s[26:27], 0, v[134:135]
	s_mov_b32 m0, s28
	ds_read_b128 v[172:175], v5 offset:49152
	ds_read_b128 v[176:179], v5 offset:50176
	ds_read_b128 v[180:183], v5 offset:51200
	ds_read_b128 v[184:187], v5 offset:52224
	ds_read_b128 v[188:191], v5 offset:53248
	ds_read_b128 v[192:195], v5 offset:54272
	ds_read_b128 v[196:199], v5 offset:55296
	ds_read_b128 v[200:203], v5 offset:56320
	global_load_lds_dwordx4 v[204:205], off
	s_add_i32 m0, s28, 0x2000
	v_lshl_add_u64 v[204:205], s[26:27], 0, v[138:139]
	s_add_u32 s26, s26, 0x100000
	s_addc_u32 s27, s27, 0
	s_add_i32 s28, s31, s38
	global_load_lds_dwordx4 v[204:205], off
	v_lshl_add_u64 v[204:205], s[26:27], 0, v[134:135]
	s_mov_b32 m0, s28
	s_nop 0
	global_load_lds_dwordx4 v[204:205], off
	v_lshl_add_u64 v[204:205], s[26:27], 0, v[138:139]
	s_add_i32 m0, s28, 0x2000
	s_nop 0
	global_load_lds_dwordx4 v[204:205], off
	v_lshl_add_u64 v[204:205], s[24:25], 0, v[2:3]
	s_mov_b32 m0, s49
	s_nop 0
	global_load_lds_dwordx4 v[204:205], off
	v_lshl_add_u64 v[204:205], s[24:25], 0, v[136:137]
	s_mov_b32 m0, s50
	s_nop 0
	global_load_lds_dwordx4 v[204:205], off
	s_waitcnt vmcnt(8) lgkmcnt(0)
	s_barrier
	s_setprio 1
	v_mfma_f32_16x16x32_bf16 v[66:69], v[140:143], v[172:175], v[66:69]
	v_mfma_f32_16x16x32_bf16 v[62:65], v[148:151], v[172:175], v[62:65]
	v_mfma_f32_16x16x32_bf16 v[50:53], v[140:143], v[180:183], v[50:53]
	v_mfma_f32_16x16x32_bf16 v[46:49], v[148:151], v[180:183], v[46:49]
	v_mfma_f32_16x16x32_bf16 v[34:37], v[140:143], v[188:191], v[34:37]
	v_mfma_f32_16x16x32_bf16 v[30:33], v[148:151], v[188:191], v[30:33]
	v_mfma_f32_16x16x32_bf16 v[18:21], v[140:143], v[196:199], v[18:21]
	v_mfma_f32_16x16x32_bf16 v[14:17], v[148:151], v[196:199], v[14:17]
	v_mfma_f32_16x16x32_bf16 v[66:69], v[144:147], v[176:179], v[66:69]
	v_mfma_f32_16x16x32_bf16 v[62:65], v[152:155], v[176:179], v[62:65]
	v_mfma_f32_16x16x32_bf16 v[50:53], v[144:147], v[184:187], v[50:53]
	v_mfma_f32_16x16x32_bf16 v[46:49], v[152:155], v[184:187], v[46:49]
	v_mfma_f32_16x16x32_bf16 v[34:37], v[144:147], v[192:195], v[34:37]
	v_mfma_f32_16x16x32_bf16 v[30:33], v[152:155], v[192:195], v[30:33]
	v_mfma_f32_16x16x32_bf16 v[18:21], v[144:147], v[200:203], v[18:21]
	v_mfma_f32_16x16x32_bf16 v[14:17], v[152:155], v[200:203], v[14:17]
	s_setprio 0
	s_setprio 1
	v_mfma_f32_16x16x32_bf16 v[58:61], v[156:159], v[172:175], v[58:61]
	v_mfma_f32_16x16x32_bf16 v[54:57], v[164:167], v[172:175], v[54:57]
	v_mfma_f32_16x16x32_bf16 v[42:45], v[156:159], v[180:183], v[42:45]
	v_mfma_f32_16x16x32_bf16 v[38:41], v[164:167], v[180:183], v[38:41]
	v_mfma_f32_16x16x32_bf16 v[26:29], v[156:159], v[188:191], v[26:29]
	v_mfma_f32_16x16x32_bf16 v[22:25], v[164:167], v[188:191], v[22:25]
	v_mfma_f32_16x16x32_bf16 v[10:13], v[156:159], v[196:199], v[10:13]
	v_mfma_f32_16x16x32_bf16 v[6:9], v[164:167], v[196:199], v[6:9]
	v_mfma_f32_16x16x32_bf16 v[58:61], v[160:163], v[176:179], v[58:61]
	v_mfma_f32_16x16x32_bf16 v[54:57], v[168:171], v[176:179], v[54:57]
	v_mfma_f32_16x16x32_bf16 v[42:45], v[160:163], v[184:187], v[42:45]
	v_mfma_f32_16x16x32_bf16 v[38:41], v[168:171], v[184:187], v[38:41]
	v_mfma_f32_16x16x32_bf16 v[26:29], v[160:163], v[192:195], v[26:29]
	v_mfma_f32_16x16x32_bf16 v[22:25], v[168:171], v[192:195], v[22:25]
	v_mfma_f32_16x16x32_bf16 v[10:13], v[160:163], v[200:203], v[10:13]
	v_mfma_f32_16x16x32_bf16 v[6:9], v[168:171], v[200:203], v[6:9]
	s_setprio 0
	s_barrier
	s_add_i32 s53, s53, 2
	s_add_u32 s19, s19, 0x100
	s_addc_u32 s23, s23, 0
	s_add_u32 s33, s33, 0x100
	s_addc_u32 s52, s52, 0
	s_cmp_gt_u32 s53, 61
	s_cbranch_scc0 .LBB0_346
	v_mov_b32_e32 v140, v0
	s_lshl_b32 s1, s0, 8
	s_mov_b64 s[24:25], s[84:85]
	s_add_i32 s1, s1, s47
	v_bfe_u32 v210, v140, 4, 2
	v_and_or_b32 v140, v140, 15, s1
	s_add_u32 s26, s24, s6
	s_addc_u32 s27, s25, s7
	v_ashrrev_i32_e32 v141, 31, v140
	v_lshl_add_u64 v[142:143], v[140:141], 2, s[26:27]
	s_mov_b64 s[26:27], 0x10000
	v_lshl_add_u64 v[154:155], v[142:143], 0, s[26:27]
	v_add_co_u32_e32 v142, vcc, s91, v142
	s_cmp_gt_i32 s22, 3
	s_nop 0
	v_addc_co_u32_e32 v143, vcc, 0, v143, vcc
	global_load_dword v142, v[142:143], off
	s_cselect_b64 s[28:29], -1, 0
	s_cmp_lt_i32 s22, 4
	s_cselect_b64 s[26:27], -1, 0
	global_load_dword v205, v[154:155], off offset:64
	global_load_dword v204, v[154:155], off offset:128
	global_load_dword v203, v[154:155], off offset:192
	global_load_dword v202, v[154:155], off offset:512
	global_load_dword v201, v[154:155], off offset:576
	global_load_dword v200, v[154:155], off offset:640
	global_load_dword v199, v[154:155], off offset:704
	s_waitcnt vmcnt(0)
	v_fmamk_f32 v142, v142, 0x39800000, v246
	v_cmp_gt_f32_e32 vcc, s95, v142
	v_mul_f32_e32 v143, 0x4b800000, v142
	s_nop 0
	v_cndmask_b32_e32 v142, v142, v143, vcc
	v_rsq_f32_e32 v142, v142
	s_nop 0
	v_mul_f32_e32 v143, 0x45800000, v142
	v_cndmask_b32_e32 v142, v142, v143, vcc
	v_pk_mul_f32 v[132:133], v[132:133], v[142:143] op_sel_hi:[1,0]
	v_pk_mul_f32 v[130:131], v[130:131], v[142:143] op_sel_hi:[1,0]
	v_pk_mul_f32 v[128:129], v[128:129], v[142:143] op_sel_hi:[1,0]
	v_pk_mul_f32 v[126:127], v[126:127], v[142:143] op_sel_hi:[1,0]
	v_pk_mul_f32 v[124:125], v[124:125], v[142:143] op_sel_hi:[1,0]
	v_pk_mul_f32 v[122:123], v[122:123], v[142:143] op_sel_hi:[1,0]
	v_pk_mul_f32 v[120:121], v[120:121], v[142:143] op_sel_hi:[1,0]
	v_pk_mul_f32 v[118:119], v[118:119], v[142:143] op_sel_hi:[1,0]
	s_waitcnt vmcnt(0)
	v_fmamk_f32 v142, v205, 0x39800000, v246
	v_cmp_gt_f32_e32 vcc, s95, v142
	v_mul_f32_e32 v143, 0x4b800000, v142
	s_nop 0
	v_cndmask_b32_e32 v142, v142, v143, vcc
	v_rsq_f32_e32 v142, v142
	s_nop 0
	v_mul_f32_e32 v143, 0x45800000, v142
	v_cndmask_b32_e32 v142, v142, v143, vcc
	v_pk_mul_f32 v[116:117], v[116:117], v[142:143] op_sel_hi:[1,0]
	v_pk_mul_f32 v[114:115], v[114:115], v[142:143] op_sel_hi:[1,0]
	v_pk_mul_f32 v[112:113], v[112:113], v[142:143] op_sel_hi:[1,0]
	v_pk_mul_f32 v[110:111], v[110:111], v[142:143] op_sel_hi:[1,0]
	v_pk_mul_f32 v[108:109], v[108:109], v[142:143] op_sel_hi:[1,0]
	v_pk_mul_f32 v[106:107], v[106:107], v[142:143] op_sel_hi:[1,0]
	v_pk_mul_f32 v[104:105], v[104:105], v[142:143] op_sel_hi:[1,0]
	v_pk_mul_f32 v[102:103], v[102:103], v[142:143] op_sel_hi:[1,0]
	s_waitcnt vmcnt(0)
	v_fmamk_f32 v142, v204, 0x39800000, v246
	v_cmp_gt_f32_e32 vcc, s95, v142
	v_mul_f32_e32 v143, 0x4b800000, v142
	s_nop 0
	v_cndmask_b32_e32 v142, v142, v143, vcc
	v_rsq_f32_e32 v142, v142
	s_nop 0
	v_mul_f32_e32 v143, 0x45800000, v142
	v_cndmask_b32_e32 v142, v142, v143, vcc
	v_pk_mul_f32 v[150:151], v[94:95], v[142:143] op_sel_hi:[1,0]
	v_pk_mul_f32 v[152:153], v[98:99], v[142:143] op_sel_hi:[1,0]
	v_pk_mul_f32 v[100:101], v[100:101], v[142:143] op_sel_hi:[1,0]
	v_pk_mul_f32 v[92:93], v[92:93], v[142:143] op_sel_hi:[1,0]
	v_pk_mul_f32 v[90:91], v[90:91], v[142:143] op_sel_hi:[1,0]
	v_pk_mul_f32 v[86:87], v[86:87], v[142:143] op_sel_hi:[1,0]
	v_pk_mul_f32 v[96:97], v[96:97], v[142:143] op_sel_hi:[1,0]
	v_pk_mul_f32 v[88:89], v[88:89], v[142:143] op_sel_hi:[1,0]
	s_waitcnt vmcnt(0)
	v_fmamk_f32 v94, v203, 0x39800000, v246
	v_cmp_gt_f32_e32 vcc, s95, v94
	v_mul_f32_e32 v95, 0x4b800000, v94
	s_nop 0
	v_cndmask_b32_e32 v94, v94, v95, vcc
	v_rsq_f32_e32 v94, v94
	s_nop 0
	v_mul_f32_e32 v95, 0x45800000, v94
	v_cndmask_b32_e32 v94, v94, v95, vcc
	v_pk_mul_f32 v[164:165], v[80:81], v[94:95] op_sel_hi:[1,0]
	v_pk_mul_f32 v[80:81], v[74:75], v[94:95] op_sel_hi:[1,0]
	v_pk_mul_f32 v[166:167], v[84:85], v[94:95] op_sel_hi:[1,0]
	v_pk_mul_f32 v[170:171], v[82:83], v[94:95] op_sel_hi:[1,0]
	v_pk_mul_f32 v[168:169], v[78:79], v[94:95] op_sel_hi:[1,0]
	v_pk_mul_f32 v[78:79], v[76:77], v[94:95] op_sel_hi:[1,0]
	v_pk_mul_f32 v[72:73], v[72:73], v[94:95] op_sel_hi:[1,0]
	v_pk_mul_f32 v[70:71], v[70:71], v[94:95] op_sel_hi:[1,0]
	s_waitcnt vmcnt(0)
	v_fmamk_f32 v74, v202, 0x39800000, v246
	v_cmp_gt_f32_e32 vcc, s95, v74
	v_mul_f32_e32 v75, 0x4b800000, v74
	s_nop 0
	v_cndmask_b32_e32 v74, v74, v75, vcc
	v_rsq_f32_e32 v74, v74
	s_nop 0
	v_mul_f32_e32 v75, 0x45800000, v74
	v_cndmask_b32_e32 v98, v74, v75, vcc
	v_pk_mul_f32 v[76:77], v[68:69], v[98:99] op_sel_hi:[1,0]
	v_pk_mul_f32 v[176:177], v[66:67], v[98:99] op_sel_hi:[1,0]
	v_pk_mul_f32 v[74:75], v[64:65], v[98:99] op_sel_hi:[1,0]
	v_pk_mul_f32 v[174:175], v[62:63], v[98:99] op_sel_hi:[1,0]
	v_pk_mul_f32 v[84:85], v[60:61], v[98:99] op_sel_hi:[1,0]
	v_pk_mul_f32 v[94:95], v[58:59], v[98:99] op_sel_hi:[1,0]
	v_pk_mul_f32 v[82:83], v[56:57], v[98:99] op_sel_hi:[1,0]
	v_pk_mul_f32 v[98:99], v[54:55], v[98:99] op_sel_hi:[1,0]
	s_waitcnt vmcnt(0)
	v_fmamk_f32 v54, v201, 0x39800000, v246
	v_cmp_gt_f32_e32 vcc, s95, v54
	v_mul_f32_e32 v55, 0x4b800000, v54
	s_nop 0
	v_cndmask_b32_e32 v54, v54, v55, vcc
	v_rsq_f32_e32 v54, v54
	s_nop 0
	v_mul_f32_e32 v55, 0x45800000, v54
	v_cndmask_b32_e32 v54, v54, v55, vcc
	v_pk_mul_f32 v[146:147], v[38:39], v[54:55] op_sel_hi:[1,0]
	v_pk_mul_f32 v[180:181], v[52:53], v[54:55] op_sel_hi:[1,0]
	v_pk_mul_f32 v[184:185], v[50:51], v[54:55] op_sel_hi:[1,0]
	v_pk_mul_f32 v[144:145], v[44:45], v[54:55] op_sel_hi:[1,0]
	v_pk_mul_f32 v[148:149], v[42:43], v[54:55] op_sel_hi:[1,0]
	v_pk_mul_f32 v[182:183], v[46:47], v[54:55] op_sel_hi:[1,0]
	v_pk_mul_f32 v[178:179], v[48:49], v[54:55] op_sel_hi:[1,0]
	v_pk_mul_f32 v[142:143], v[40:41], v[54:55] op_sel_hi:[1,0]
	s_waitcnt vmcnt(0)
	v_fmamk_f32 v38, v200, 0x39800000, v246
	v_cmp_gt_f32_e32 vcc, s95, v38
	v_mul_f32_e32 v39, 0x4b800000, v38
	s_nop 0
	v_cndmask_b32_e32 v38, v38, v39, vcc
	v_rsq_f32_e32 v38, v38
	s_nop 0
	v_mul_f32_e32 v39, 0x45800000, v38
	v_cndmask_b32_e32 v38, v38, v39, vcc
	v_pk_mul_f32 v[160:161], v[22:23], v[38:39] op_sel_hi:[1,0]
	v_pk_mul_f32 v[188:189], v[36:37], v[38:39] op_sel_hi:[1,0]
	v_pk_mul_f32 v[192:193], v[34:35], v[38:39] op_sel_hi:[1,0]
	v_pk_mul_f32 v[158:159], v[28:29], v[38:39] op_sel_hi:[1,0]
	v_pk_mul_f32 v[162:163], v[26:27], v[38:39] op_sel_hi:[1,0]
	v_pk_mul_f32 v[186:187], v[32:33], v[38:39] op_sel_hi:[1,0]
	v_pk_mul_f32 v[190:191], v[30:31], v[38:39] op_sel_hi:[1,0]
	v_pk_mul_f32 v[156:157], v[24:25], v[38:39] op_sel_hi:[1,0]
	v_mul_f32_e32 v24, v95, v95
	v_mul_f32_e32 v25, v85, v85
	v_mul_f32_e32 v26, v185, v185
	v_mul_f32_e32 v27, v181, v181
	v_mul_f32_e32 v28, v149, v149
	v_mul_f32_e32 v29, v145, v145
	v_mul_f32_e32 v30, v193, v193
	v_mul_f32_e32 v31, v189, v189
	v_mul_f32_e32 v32, v163, v163
	v_mul_f32_e32 v33, v159, v159
	v_fmac_f32_e32 v24, v94, v94
	v_fmac_f32_e32 v25, v84, v84
	v_fmac_f32_e32 v26, v184, v184
	v_fmac_f32_e32 v27, v180, v180
	v_fmac_f32_e32 v28, v148, v148
	v_fmac_f32_e32 v29, v144, v144
	v_fmac_f32_e32 v30, v192, v192
	v_fmac_f32_e32 v31, v188, v188
	v_fmac_f32_e32 v32, v162, v162
	v_fmac_f32_e32 v33, v158, v158
	v_add_f32_e32 v24, v24, v25
	v_mul_f32_e32 v25, v99, v99
	v_add_f32_e32 v26, v26, v27
	v_mul_f32_e32 v27, v183, v183
	v_add_f32_e32 v28, v28, v29
	v_mul_f32_e32 v29, v147, v147
	v_add_f32_e32 v30, v30, v31
	v_mul_f32_e32 v31, v191, v191
	v_add_f32_e32 v32, v32, v33
	v_mul_f32_e32 v33, v161, v161
	v_fmac_f32_e32 v25, v98, v98
	v_fmac_f32_e32 v27, v182, v182
	v_fmac_f32_e32 v29, v146, v146
	v_fmac_f32_e32 v31, v190, v190
	v_fmac_f32_e32 v33, v160, v160
	v_add_f32_e32 v24, v25, v24
	v_mul_f32_e32 v25, v83, v83
	v_add_f32_e32 v26, v27, v26
	v_mul_f32_e32 v27, v179, v179
	v_add_f32_e32 v28, v29, v28
	v_mul_f32_e32 v29, v143, v143
	v_add_f32_e32 v30, v31, v30
	v_mul_f32_e32 v31, v187, v187
	v_add_f32_e32 v32, v33, v32
	v_mul_f32_e32 v33, v157, v157
	v_fmac_f32_e32 v25, v82, v82
	v_fmac_f32_e32 v27, v178, v178
	v_fmac_f32_e32 v29, v142, v142
	v_fmac_f32_e32 v31, v186, v186
	v_fmac_f32_e32 v33, v156, v156
	v_add_f32_e32 v24, v25, v24
	v_add_f32_e32 v26, v27, v26
	v_add_f32_e32 v28, v29, v28
	v_add_f32_e32 v30, v31, v30
	v_add_f32_e32 v32, v33, v32
	ds_swizzle_b32 v25, v24 offset:swizzle(SWAP,16)
	ds_swizzle_b32 v27, v26 offset:swizzle(SWAP,16)
	ds_swizzle_b32 v29, v28 offset:swizzle(SWAP,16)
	ds_swizzle_b32 v31, v30 offset:swizzle(SWAP,16)
	ds_swizzle_b32 v33, v32 offset:swizzle(SWAP,16)
	s_waitcnt lgkmcnt(4)
	v_add_f32_e32 v24, v24, v25
	s_waitcnt lgkmcnt(3)
	v_add_f32_e32 v26, v26, v27
	s_waitcnt lgkmcnt(2)
	v_add_f32_e32 v28, v28, v29
	s_waitcnt lgkmcnt(1)
	v_add_f32_e32 v30, v30, v31
	s_waitcnt lgkmcnt(0)
	v_add_f32_e32 v32, v32, v33
	v_mov_b32_e32 v25, v24
	v_mov_b32_e32 v27, v26
	v_mov_b32_e32 v29, v28
	v_mov_b32_e32 v31, v30
	v_mov_b32_e32 v33, v32
	v_permlane32_swap_b32_e32 v24, v25
	s_waitcnt vmcnt(0)
	v_fmamk_f32 v22, v199, 0x39800000, v246
	v_cmp_gt_f32_e32 vcc, s95, v22
	v_mul_f32_e32 v23, 0x4b800000, v22
	v_permlane32_swap_b32_e32 v26, v27
	v_cndmask_b32_e32 v22, v22, v23, vcc
	v_rsq_f32_e32 v22, v22
	v_permlane32_swap_b32_e32 v28, v29
	v_permlane32_swap_b32_e32 v30, v31
	v_mul_f32_e32 v23, 0x45800000, v22
	v_cndmask_b32_e32 v22, v22, v23, vcc
	v_pk_mul_f32 v[202:203], v[20:21], v[22:23] op_sel_hi:[1,0]
	v_pk_mul_f32 v[204:205], v[18:19], v[22:23] op_sel_hi:[1,0]
	v_pk_mul_f32 v[194:195], v[12:13], v[22:23] op_sel_hi:[1,0]
	v_pk_mul_f32 v[196:197], v[10:11], v[22:23] op_sel_hi:[1,0]
	v_pk_mul_f32 v[206:207], v[16:17], v[22:23] op_sel_hi:[1,0]
	v_pk_mul_f32 v[208:209], v[14:15], v[22:23] op_sel_hi:[1,0]
	v_pk_mul_f32 v[198:199], v[8:9], v[22:23] op_sel_hi:[1,0]
	v_pk_mul_f32 v[200:201], v[6:7], v[22:23] op_sel_hi:[1,0]
	v_mul_f32_e32 v6, v131, v131
	v_mul_f32_e32 v7, v133, v133
	v_mul_f32_e32 v8, v123, v123
	v_mul_f32_e32 v9, v125, v125
	v_mul_f32_e32 v10, v115, v115
	v_mul_f32_e32 v11, v117, v117
	v_mul_f32_e32 v12, v107, v107
	v_mul_f32_e32 v13, v109, v109
	v_mul_f32_e32 v14, v153, v153
	v_mul_f32_e32 v15, v101, v101
	v_mul_f32_e32 v16, v91, v91
	v_mul_f32_e32 v17, v93, v93
	v_mul_f32_e32 v18, v171, v171
	v_mul_f32_e32 v19, v167, v167
	v_mul_f32_e32 v20, v81, v81
	v_mul_f32_e32 v21, v79, v79
	v_mul_f32_e32 v22, v177, v177
	v_mul_f32_e32 v23, v77, v77
	v_mul_f32_e32 v34, v205, v205
	v_mul_f32_e32 v35, v203, v203
	v_mul_f32_e32 v36, v197, v197
	v_mul_f32_e32 v37, v195, v195
	v_fmac_f32_e32 v6, v130, v130
	v_fmac_f32_e32 v7, v132, v132
	v_fmac_f32_e32 v8, v122, v122
	v_fmac_f32_e32 v9, v124, v124
	v_fmac_f32_e32 v10, v114, v114
	v_fmac_f32_e32 v11, v116, v116
	v_fmac_f32_e32 v12, v106, v106
	v_fmac_f32_e32 v13, v108, v108
	v_fmac_f32_e32 v14, v152, v152
	v_fmac_f32_e32 v15, v100, v100
	v_fmac_f32_e32 v16, v90, v90
	v_fmac_f32_e32 v17, v92, v92
	v_fmac_f32_e32 v18, v170, v170
	v_fmac_f32_e32 v19, v166, v166
	v_fmac_f32_e32 v20, v80, v80
	v_fmac_f32_e32 v21, v78, v78
	v_fmac_f32_e32 v22, v176, v176
	v_fmac_f32_e32 v23, v76, v76
	v_fmac_f32_e32 v34, v204, v204
	v_fmac_f32_e32 v35, v202, v202
	v_fmac_f32_e32 v36, v196, v196
	v_fmac_f32_e32 v37, v194, v194
	v_add_f32_e32 v6, v6, v7
	v_mul_f32_e32 v7, v127, v127
	v_add_f32_e32 v8, v8, v9
	v_mul_f32_e32 v9, v119, v119
	v_add_f32_e32 v10, v10, v11
	v_mul_f32_e32 v11, v111, v111
	v_add_f32_e32 v12, v12, v13
	v_mul_f32_e32 v13, v103, v103
	v_add_f32_e32 v14, v14, v15
	v_mul_f32_e32 v15, v151, v151
	v_add_f32_e32 v16, v16, v17
	v_mul_f32_e32 v17, v87, v87
	v_add_f32_e32 v18, v18, v19
	v_mul_f32_e32 v19, v169, v169
	v_add_f32_e32 v20, v20, v21
	v_mul_f32_e32 v21, v71, v71
	v_add_f32_e32 v22, v22, v23
	v_mul_f32_e32 v23, v175, v175
	v_add_f32_e32 v34, v34, v35
	v_mul_f32_e32 v35, v209, v209
	v_add_f32_e32 v36, v36, v37
	v_mul_f32_e32 v37, v201, v201
	v_fmac_f32_e32 v7, v126, v126
	v_fmac_f32_e32 v9, v118, v118
	v_fmac_f32_e32 v11, v110, v110
	v_fmac_f32_e32 v13, v102, v102
	v_fmac_f32_e32 v15, v150, v150
	v_fmac_f32_e32 v17, v86, v86
	v_fmac_f32_e32 v19, v168, v168
	v_fmac_f32_e32 v21, v70, v70
	v_fmac_f32_e32 v23, v174, v174
	v_fmac_f32_e32 v35, v208, v208
	v_fmac_f32_e32 v37, v200, v200
	v_add_f32_e32 v6, v7, v6
	v_mul_f32_e32 v7, v129, v129
	v_add_f32_e32 v8, v9, v8
	v_mul_f32_e32 v9, v121, v121
	v_add_f32_e32 v10, v11, v10
	v_mul_f32_e32 v11, v113, v113
	v_add_f32_e32 v12, v13, v12
	v_mul_f32_e32 v13, v105, v105
	v_add_f32_e32 v14, v15, v14
	v_mul_f32_e32 v15, v97, v97
	v_add_f32_e32 v16, v17, v16
	v_mul_f32_e32 v17, v89, v89
	v_add_f32_e32 v18, v19, v18
	v_mul_f32_e32 v19, v165, v165
	v_add_f32_e32 v20, v21, v20
	v_mul_f32_e32 v21, v73, v73
	v_add_f32_e32 v22, v23, v22
	v_mul_f32_e32 v23, v75, v75
	v_add_f32_e32 v34, v35, v34
	v_mul_f32_e32 v35, v207, v207
	v_add_f32_e32 v36, v37, v36
	v_mul_f32_e32 v37, v199, v199
	v_fmac_f32_e32 v7, v128, v128
	v_fmac_f32_e32 v9, v120, v120
	v_fmac_f32_e32 v11, v112, v112
	v_fmac_f32_e32 v13, v104, v104
	v_fmac_f32_e32 v15, v96, v96
	v_fmac_f32_e32 v17, v88, v88
	v_fmac_f32_e32 v19, v164, v164
	v_fmac_f32_e32 v21, v72, v72
	v_fmac_f32_e32 v23, v74, v74
	v_fmac_f32_e32 v35, v206, v206
	v_fmac_f32_e32 v37, v198, v198
	v_add_f32_e32 v6, v7, v6
	v_add_f32_e32 v8, v9, v8
	v_add_f32_e32 v10, v11, v10
	v_add_f32_e32 v12, v13, v12
	v_add_f32_e32 v14, v15, v14
	v_add_f32_e32 v16, v17, v16
	v_add_f32_e32 v18, v19, v18
	v_add_f32_e32 v20, v21, v20
	v_add_f32_e32 v22, v23, v22
	v_add_f32_e32 v34, v35, v34
	v_add_f32_e32 v36, v37, v36
	ds_swizzle_b32 v7, v6 offset:swizzle(SWAP,16)
	ds_swizzle_b32 v9, v8 offset:swizzle(SWAP,16)
	ds_swizzle_b32 v11, v10 offset:swizzle(SWAP,16)
	ds_swizzle_b32 v13, v12 offset:swizzle(SWAP,16)
	ds_swizzle_b32 v15, v14 offset:swizzle(SWAP,16)
	ds_swizzle_b32 v17, v16 offset:swizzle(SWAP,16)
	ds_swizzle_b32 v19, v18 offset:swizzle(SWAP,16)
	ds_swizzle_b32 v21, v20 offset:swizzle(SWAP,16)
	ds_swizzle_b32 v23, v22 offset:swizzle(SWAP,16)
	ds_swizzle_b32 v35, v34 offset:swizzle(SWAP,16)
	ds_swizzle_b32 v37, v36 offset:swizzle(SWAP,16)
	s_waitcnt lgkmcnt(10)
	v_add_f32_e32 v6, v6, v7
	s_waitcnt lgkmcnt(9)
	v_add_f32_e32 v8, v8, v9
	s_waitcnt lgkmcnt(8)
	v_add_f32_e32 v10, v10, v11
	s_waitcnt lgkmcnt(7)
	v_add_f32_e32 v12, v12, v13
	s_waitcnt lgkmcnt(6)
	v_add_f32_e32 v14, v14, v15
	s_waitcnt lgkmcnt(5)
	v_add_f32_e32 v16, v16, v17
	s_waitcnt lgkmcnt(4)
	v_add_f32_e32 v18, v18, v19
	s_waitcnt lgkmcnt(3)
	v_add_f32_e32 v20, v20, v21
	s_waitcnt lgkmcnt(2)
	v_add_f32_e32 v22, v22, v23
	s_waitcnt lgkmcnt(1)
	v_add_f32_e32 v34, v34, v35
	s_waitcnt lgkmcnt(0)
	v_add_f32_e32 v36, v36, v37
	v_mov_b32_e32 v7, v6
	v_mov_b32_e32 v9, v8
	v_mov_b32_e32 v11, v10
	v_mov_b32_e32 v13, v12
	v_mov_b32_e32 v15, v14
	v_mov_b32_e32 v17, v16
	v_mov_b32_e32 v19, v18
	v_mov_b32_e32 v21, v20
	v_mov_b32_e32 v23, v22
	v_mov_b32_e32 v35, v34
	v_mov_b32_e32 v37, v36
	v_permlane32_swap_b32_e32 v6, v7
	v_permlane32_swap_b32_e32 v8, v9
	v_permlane32_swap_b32_e32 v10, v11
	v_permlane32_swap_b32_e32 v12, v13
	v_permlane32_swap_b32_e32 v14, v15
	v_permlane32_swap_b32_e32 v16, v17
	v_permlane32_swap_b32_e32 v18, v19
	v_permlane32_swap_b32_e32 v20, v21
	v_permlane32_swap_b32_e32 v22, v23
	v_permlane32_swap_b32_e32 v32, v33
	v_permlane32_swap_b32_e32 v34, v35
	v_permlane32_swap_b32_e32 v36, v37
	v_cmp_eq_u32_e32 vcc, 0, v210
	s_and_saveexec_b64 s[30:31], vcc
	s_cbranch_execz .LBB0_349
	s_and_b64 s[52:53], s[28:29], exec
	s_mov_b32 s1, 0x31000
	s_cselect_b32 s1, s1, 0x20800
	s_add_u32 s1, s24, s1
	s_addc_u32 s2, s25, 0
	s_add_u32 s52, s1, s6
	v_add_f32_e32 v8, v8, v9
	v_add_f32_e32 v9, v6, v7
	s_addc_u32 s53, s2, s7
	v_add_f32_e32 v12, v12, v13
	v_add_f32_e32 v10, v10, v11
	v_lshl_add_u64 v[6:7], v[140:141], 2, s[52:53]
	v_add_f32_e32 v8, v9, v8
	v_add_f32_e32 v16, v16, v17
	v_add_f32_e32 v14, v14, v15
	global_atomic_add_f32 v[6:7], v8, off
	v_add_f32_e32 v8, v10, v12
	v_add_f32_e32 v20, v20, v21
	v_add_f32_e32 v18, v18, v19
	global_atomic_add_f32 v[6:7], v8, off offset:64
	v_add_f32_e32 v8, v14, v16
	v_add_f32_e32 v24, v24, v25
	v_add_f32_e32 v22, v22, v23
	global_atomic_add_f32 v[6:7], v8, off offset:128
	v_add_f32_e32 v8, v18, v20
	v_add_f32_e32 v28, v28, v29
	v_add_f32_e32 v26, v26, v27
	global_atomic_add_f32 v[6:7], v8, off offset:192
	v_add_f32_e32 v8, v22, v24
	v_add_f32_e32 v32, v32, v33
	v_add_f32_e32 v30, v30, v31
	global_atomic_add_f32 v[6:7], v8, off offset:512
	v_add_f32_e32 v8, v26, v28
	v_add_f32_e32 v36, v36, v37
	v_add_f32_e32 v34, v34, v35
	global_atomic_add_f32 v[6:7], v8, off offset:576
	v_add_f32_e32 v8, v30, v32
	global_atomic_add_f32 v[6:7], v8, off offset:640
	v_add_f32_e32 v8, v34, v36
	global_atomic_add_f32 v[6:7], v8, off offset:704

.LBB0_454:
	s_add_u32 s66, s62, 0xffffff80
	s_addc_u32 s67, s63, -1
	s_cmp_eq_u32 s64, 12
	s_cselect_b32 s38, s21, s62
	s_cselect_b32 s39, s3, s63
	s_cselect_b32 s41, s23, s61
	s_cselect_b32 s40, s31, s33
	s_add_u32 s34, s38, 0x80
	s_addc_u32 s35, s39, 0
	s_add_u32 s36, s40, 0x80
	s_addc_u32 s37, s41, 0
	s_add_i32 s65, 0, 0x10000
	s_add_i32 s68, 0, 0x14000
	v_add_u32_e32 v152, s65, v1
	v_add_u32_e32 v168, s68, v1
	ds_read_b128 v[140:143], v152
	ds_read_b128 v[144:147], v152 offset:1024
	ds_read_b128 v[148:151], v152 offset:2048
	ds_read_b128 v[152:155], v152 offset:3072
	ds_read_b128 v[156:159], v168
	ds_read_b128 v[160:163], v168 offset:1024
	ds_read_b128 v[164:167], v168 offset:2048
	ds_read_b128 v[168:171], v168 offset:3072
	s_add_u32 s66, s66, 0x40000
	s_addc_u32 s67, s67, 0
	v_lshl_add_u64 v[204:205], s[66:67], 0, v[2:3]
	s_add_i32 m0, s29, 0xc000
	ds_read_b128 v[172:175], v5
	ds_read_b128 v[176:179], v5 offset:1024
	ds_read_b128 v[180:183], v5 offset:2048
	ds_read_b128 v[184:187], v5 offset:3072
	ds_read_b128 v[188:191], v5 offset:4096
	ds_read_b128 v[192:195], v5 offset:5120
	ds_read_b128 v[196:199], v5 offset:6144
	ds_read_b128 v[200:203], v5 offset:7168
	global_load_lds_dwordx4 v[204:205], off
	v_lshl_add_u64 v[204:205], s[66:67], 0, v[136:137]
	s_add_i32 m0, s29, 0xe000
	s_nop 0
	global_load_lds_dwordx4 v[204:205], off
	s_waitcnt vmcnt(8) lgkmcnt(0)
	s_barrier
	s_setprio 1
	v_mfma_f32_16x16x32_bf16 v[130:133], v[140:143], v[172:175], v[130:133]
	v_mfma_f32_16x16x32_bf16 v[126:129], v[148:151], v[172:175], v[126:129]
	v_mfma_f32_16x16x32_bf16 v[114:117], v[140:143], v[180:183], v[114:117]
	v_mfma_f32_16x16x32_bf16 v[110:113], v[148:151], v[180:183], v[110:113]
	v_mfma_f32_16x16x32_bf16 v[98:101], v[140:143], v[188:191], v[98:101]
	v_mfma_f32_16x16x32_bf16 v[94:97], v[148:151], v[188:191], v[94:97]
	v_mfma_f32_16x16x32_bf16 v[82:85], v[140:143], v[196:199], v[82:85]
	v_mfma_f32_16x16x32_bf16 v[78:81], v[148:151], v[196:199], v[78:81]
	v_mfma_f32_16x16x32_bf16 v[130:133], v[144:147], v[176:179], v[130:133]
	v_mfma_f32_16x16x32_bf16 v[126:129], v[152:155], v[176:179], v[126:129]
	v_mfma_f32_16x16x32_bf16 v[114:117], v[144:147], v[184:187], v[114:117]
	v_mfma_f32_16x16x32_bf16 v[110:113], v[152:155], v[184:187], v[110:113]
	v_mfma_f32_16x16x32_bf16 v[98:101], v[144:147], v[192:195], v[98:101]
	v_mfma_f32_16x16x32_bf16 v[94:97], v[152:155], v[192:195], v[94:97]
	v_mfma_f32_16x16x32_bf16 v[82:85], v[144:147], v[200:203], v[82:85]
	v_mfma_f32_16x16x32_bf16 v[78:81], v[152:155], v[200:203], v[78:81]
	s_setprio 0
	s_setprio 1
	v_mfma_f32_16x16x32_bf16 v[122:125], v[156:159], v[172:175], v[122:125]
	v_mfma_f32_16x16x32_bf16 v[118:121], v[164:167], v[172:175], v[118:121]
	v_mfma_f32_16x16x32_bf16 v[106:109], v[156:159], v[180:183], v[106:109]
	v_mfma_f32_16x16x32_bf16 v[102:105], v[164:167], v[180:183], v[102:105]
	v_mfma_f32_16x16x32_bf16 v[90:93], v[156:159], v[188:191], v[90:93]
	v_mfma_f32_16x16x32_bf16 v[86:89], v[164:167], v[188:191], v[86:89]
	v_mfma_f32_16x16x32_bf16 v[74:77], v[156:159], v[196:199], v[74:77]
	v_mfma_f32_16x16x32_bf16 v[70:73], v[164:167], v[196:199], v[70:73]
	v_mfma_f32_16x16x32_bf16 v[122:125], v[160:163], v[176:179], v[122:125]
	v_mfma_f32_16x16x32_bf16 v[118:121], v[168:171], v[176:179], v[118:121]
	v_mfma_f32_16x16x32_bf16 v[106:109], v[160:163], v[184:187], v[106:109]
	v_mfma_f32_16x16x32_bf16 v[102:105], v[168:171], v[184:187], v[102:105]
	v_mfma_f32_16x16x32_bf16 v[90:93], v[160:163], v[192:195], v[90:93]
	v_mfma_f32_16x16x32_bf16 v[86:89], v[168:171], v[192:195], v[86:89]
	v_mfma_f32_16x16x32_bf16 v[74:77], v[160:163], v[200:203], v[74:77]
	v_mfma_f32_16x16x32_bf16 v[70:73], v[168:171], v[200:203], v[70:73]
	s_setprio 0
	s_barrier
	s_add_i32 s65, s65, s46
	v_lshl_add_u64 v[204:205], s[40:41], 0, v[134:135]
	s_mov_b32 m0, s65
	ds_read_b128 v[172:175], v5 offset:16384
	ds_read_b128 v[176:179], v5 offset:17408
	ds_read_b128 v[180:183], v5 offset:18432
	ds_read_b128 v[184:187], v5 offset:19456
	ds_read_b128 v[188:191], v5 offset:20480
	ds_read_b128 v[192:195], v5 offset:21504
	ds_read_b128 v[196:199], v5 offset:22528
	ds_read_b128 v[200:203], v5 offset:23552
	global_load_lds_dwordx4 v[204:205], off
	s_add_i32 m0, s65, 0x2000
	v_lshl_add_u64 v[204:205], s[40:41], 0, v[138:139]
	s_add_u32 s40, s40, 0x40000
	s_addc_u32 s41, s41, 0
	s_add_i32 s65, s68, s46
	global_load_lds_dwordx4 v[204:205], off
	v_lshl_add_u64 v[204:205], s[40:41], 0, v[134:135]
	s_mov_b32 m0, s65
	s_nop 0
	global_load_lds_dwordx4 v[204:205], off
	v_lshl_add_u64 v[204:205], s[40:41], 0, v[138:139]
	s_add_i32 m0, s65, 0x2000
	s_nop 0
	global_load_lds_dwordx4 v[204:205], off
	v_lshl_add_u64 v[204:205], s[38:39], 0, v[2:3]
	s_mov_b32 m0, s29
	s_nop 0
	global_load_lds_dwordx4 v[204:205], off
	v_lshl_add_u64 v[204:205], s[38:39], 0, v[136:137]
	s_mov_b32 m0, s51
	s_nop 0
	global_load_lds_dwordx4 v[204:205], off
	s_waitcnt vmcnt(8) lgkmcnt(0)
	s_barrier
	s_setprio 1
	v_mfma_f32_16x16x32_bf16 v[66:69], v[140:143], v[172:175], v[66:69]
	v_mfma_f32_16x16x32_bf16 v[62:65], v[148:151], v[172:175], v[62:65]
	v_mfma_f32_16x16x32_bf16 v[50:53], v[140:143], v[180:183], v[50:53]
	v_mfma_f32_16x16x32_bf16 v[46:49], v[148:151], v[180:183], v[46:49]
	v_mfma_f32_16x16x32_bf16 v[34:37], v[140:143], v[188:191], v[34:37]
	v_mfma_f32_16x16x32_bf16 v[30:33], v[148:151], v[188:191], v[30:33]
	v_mfma_f32_16x16x32_bf16 v[18:21], v[140:143], v[196:199], v[18:21]
	v_mfma_f32_16x16x32_bf16 v[14:17], v[148:151], v[196:199], v[14:17]
	v_mfma_f32_16x16x32_bf16 v[66:69], v[144:147], v[176:179], v[66:69]
	v_mfma_f32_16x16x32_bf16 v[62:65], v[152:155], v[176:179], v[62:65]
	v_mfma_f32_16x16x32_bf16 v[50:53], v[144:147], v[184:187], v[50:53]
	v_mfma_f32_16x16x32_bf16 v[46:49], v[152:155], v[184:187], v[46:49]
	v_mfma_f32_16x16x32_bf16 v[34:37], v[144:147], v[192:195], v[34:37]
	v_mfma_f32_16x16x32_bf16 v[30:33], v[152:155], v[192:195], v[30:33]
	v_mfma_f32_16x16x32_bf16 v[18:21], v[144:147], v[200:203], v[18:21]
	v_mfma_f32_16x16x32_bf16 v[14:17], v[152:155], v[200:203], v[14:17]
	s_setprio 0
	s_setprio 1
	v_mfma_f32_16x16x32_bf16 v[58:61], v[156:159], v[172:175], v[58:61]
	v_mfma_f32_16x16x32_bf16 v[54:57], v[164:167], v[172:175], v[54:57]
	v_mfma_f32_16x16x32_bf16 v[42:45], v[156:159], v[180:183], v[42:45]
	v_mfma_f32_16x16x32_bf16 v[38:41], v[164:167], v[180:183], v[38:41]
	v_mfma_f32_16x16x32_bf16 v[26:29], v[156:159], v[188:191], v[26:29]
	v_mfma_f32_16x16x32_bf16 v[22:25], v[164:167], v[188:191], v[22:25]
	v_mfma_f32_16x16x32_bf16 v[10:13], v[156:159], v[196:199], v[10:13]
	v_mfma_f32_16x16x32_bf16 v[6:9], v[164:167], v[196:199], v[6:9]
	v_mfma_f32_16x16x32_bf16 v[58:61], v[160:163], v[176:179], v[58:61]
	v_mfma_f32_16x16x32_bf16 v[54:57], v[168:171], v[176:179], v[54:57]
	v_mfma_f32_16x16x32_bf16 v[42:45], v[160:163], v[184:187], v[42:45]
	v_mfma_f32_16x16x32_bf16 v[38:41], v[168:171], v[184:187], v[38:41]
	v_mfma_f32_16x16x32_bf16 v[26:29], v[160:163], v[192:195], v[26:29]
	v_mfma_f32_16x16x32_bf16 v[22:25], v[168:171], v[192:195], v[22:25]
	v_mfma_f32_16x16x32_bf16 v[10:13], v[160:163], v[200:203], v[10:13]
	v_mfma_f32_16x16x32_bf16 v[6:9], v[168:171], v[200:203], v[6:9]
	s_setprio 0
	s_barrier
	s_add_i32 s40, 0, 0x18000
	s_add_i32 s41, 0, 0x1c000
	v_add_u32_e32 v152, s40, v1
	v_add_u32_e32 v168, s41, v1
	ds_read_b128 v[140:143], v152
	ds_read_b128 v[144:147], v152 offset:1024
	ds_read_b128 v[148:151], v152 offset:2048
	ds_read_b128 v[152:155], v152 offset:3072
	ds_read_b128 v[156:159], v168
	ds_read_b128 v[160:163], v168 offset:1024
	ds_read_b128 v[164:167], v168 offset:2048
	ds_read_b128 v[168:171], v168 offset:3072
	s_add_u32 s38, s38, 0x40000
	s_addc_u32 s39, s39, 0
	s_mov_b32 m0, s52
	v_lshl_add_u64 v[204:205], s[38:39], 0, v[2:3]
	ds_read_b128 v[172:175], v5 offset:32768
	ds_read_b128 v[176:179], v5 offset:33792
	ds_read_b128 v[180:183], v5 offset:34816
	ds_read_b128 v[184:187], v5 offset:35840
	ds_read_b128 v[188:191], v5 offset:36864
	ds_read_b128 v[192:195], v5 offset:37888
	ds_read_b128 v[196:199], v5 offset:38912
	ds_read_b128 v[200:203], v5 offset:39936
	global_load_lds_dwordx4 v[204:205], off
	v_lshl_add_u64 v[204:205], s[38:39], 0, v[136:137]
	s_mov_b32 m0, s53
	s_nop 0
	global_load_lds_dwordx4 v[204:205], off
	s_waitcnt vmcnt(8) lgkmcnt(0)
	s_barrier
	s_setprio 1
	v_mfma_f32_16x16x32_bf16 v[130:133], v[140:143], v[172:175], v[130:133]
	v_mfma_f32_16x16x32_bf16 v[126:129], v[148:151], v[172:175], v[126:129]
	v_mfma_f32_16x16x32_bf16 v[114:117], v[140:143], v[180:183], v[114:117]
	v_mfma_f32_16x16x32_bf16 v[110:113], v[148:151], v[180:183], v[110:113]
	v_mfma_f32_16x16x32_bf16 v[98:101], v[140:143], v[188:191], v[98:101]
	v_mfma_f32_16x16x32_bf16 v[94:97], v[148:151], v[188:191], v[94:97]
	v_mfma_f32_16x16x32_bf16 v[82:85], v[140:143], v[196:199], v[82:85]
	v_mfma_f32_16x16x32_bf16 v[78:81], v[148:151], v[196:199], v[78:81]
	v_mfma_f32_16x16x32_bf16 v[130:133], v[144:147], v[176:179], v[130:133]
	v_mfma_f32_16x16x32_bf16 v[126:129], v[152:155], v[176:179], v[126:129]
	v_mfma_f32_16x16x32_bf16 v[114:117], v[144:147], v[184:187], v[114:117]
	v_mfma_f32_16x16x32_bf16 v[110:113], v[152:155], v[184:187], v[110:113]
	v_mfma_f32_16x16x32_bf16 v[98:101], v[144:147], v[192:195], v[98:101]
	v_mfma_f32_16x16x32_bf16 v[94:97], v[152:155], v[192:195], v[94:97]
	v_mfma_f32_16x16x32_bf16 v[82:85], v[144:147], v[200:203], v[82:85]
	v_mfma_f32_16x16x32_bf16 v[78:81], v[152:155], v[200:203], v[78:81]
	s_setprio 0
	s_setprio 1
	v_mfma_f32_16x16x32_bf16 v[122:125], v[156:159], v[172:175], v[122:125]
	v_mfma_f32_16x16x32_bf16 v[118:121], v[164:167], v[172:175], v[118:121]
	v_mfma_f32_16x16x32_bf16 v[106:109], v[156:159], v[180:183], v[106:109]
	v_mfma_f32_16x16x32_bf16 v[102:105], v[164:167], v[180:183], v[102:105]
	v_mfma_f32_16x16x32_bf16 v[90:93], v[156:159], v[188:191], v[90:93]
	v_mfma_f32_16x16x32_bf16 v[86:89], v[164:167], v[188:191], v[86:89]
	v_mfma_f32_16x16x32_bf16 v[74:77], v[156:159], v[196:199], v[74:77]
	v_mfma_f32_16x16x32_bf16 v[70:73], v[164:167], v[196:199], v[70:73]
	v_mfma_f32_16x16x32_bf16 v[122:125], v[160:163], v[176:179], v[122:125]
	v_mfma_f32_16x16x32_bf16 v[118:121], v[168:171], v[176:179], v[118:121]
	v_mfma_f32_16x16x32_bf16 v[106:109], v[160:163], v[184:187], v[106:109]
	v_mfma_f32_16x16x32_bf16 v[102:105], v[168:171], v[184:187], v[102:105]
	v_mfma_f32_16x16x32_bf16 v[90:93], v[160:163], v[192:195], v[90:93]
	v_mfma_f32_16x16x32_bf16 v[86:89], v[168:171], v[192:195], v[86:89]
	v_mfma_f32_16x16x32_bf16 v[74:77], v[160:163], v[200:203], v[74:77]
	v_mfma_f32_16x16x32_bf16 v[70:73], v[168:171], v[200:203], v[70:73]
	s_setprio 0
	s_barrier
	s_add_i32 s38, s40, s46
	v_lshl_add_u64 v[204:205], s[36:37], 0, v[134:135]
	s_mov_b32 m0, s38
	ds_read_b128 v[172:175], v5 offset:49152
	ds_read_b128 v[176:179], v5 offset:50176
	ds_read_b128 v[180:183], v5 offset:51200
	ds_read_b128 v[184:187], v5 offset:52224
	ds_read_b128 v[188:191], v5 offset:53248
	ds_read_b128 v[192:195], v5 offset:54272
	ds_read_b128 v[196:199], v5 offset:55296
	ds_read_b128 v[200:203], v5 offset:56320
	global_load_lds_dwordx4 v[204:205], off
	s_add_i32 m0, s38, 0x2000
	v_lshl_add_u64 v[204:205], s[36:37], 0, v[138:139]
	s_add_u32 s36, s36, 0x40000
	s_addc_u32 s37, s37, 0
	s_add_i32 s38, s41, s46
	global_load_lds_dwordx4 v[204:205], off
	v_lshl_add_u64 v[204:205], s[36:37], 0, v[134:135]
	s_mov_b32 m0, s38
	s_nop 0
	global_load_lds_dwordx4 v[204:205], off
	v_lshl_add_u64 v[204:205], s[36:37], 0, v[138:139]
	s_add_i32 m0, s38, 0x2000
	s_nop 0
	global_load_lds_dwordx4 v[204:205], off
	v_lshl_add_u64 v[204:205], s[34:35], 0, v[2:3]
	s_mov_b32 m0, s56
	s_nop 0
	global_load_lds_dwordx4 v[204:205], off
	v_lshl_add_u64 v[204:205], s[34:35], 0, v[136:137]
	s_mov_b32 m0, s57
	s_nop 0
	global_load_lds_dwordx4 v[204:205], off
	s_waitcnt vmcnt(8) lgkmcnt(0)
	s_barrier
	s_setprio 1
	v_mfma_f32_16x16x32_bf16 v[66:69], v[140:143], v[172:175], v[66:69]
	v_mfma_f32_16x16x32_bf16 v[62:65], v[148:151], v[172:175], v[62:65]
	v_mfma_f32_16x16x32_bf16 v[50:53], v[140:143], v[180:183], v[50:53]
	v_mfma_f32_16x16x32_bf16 v[46:49], v[148:151], v[180:183], v[46:49]
	v_mfma_f32_16x16x32_bf16 v[34:37], v[140:143], v[188:191], v[34:37]
	v_mfma_f32_16x16x32_bf16 v[30:33], v[148:151], v[188:191], v[30:33]
	v_mfma_f32_16x16x32_bf16 v[18:21], v[140:143], v[196:199], v[18:21]
	v_mfma_f32_16x16x32_bf16 v[14:17], v[148:151], v[196:199], v[14:17]
	v_mfma_f32_16x16x32_bf16 v[66:69], v[144:147], v[176:179], v[66:69]
	v_mfma_f32_16x16x32_bf16 v[62:65], v[152:155], v[176:179], v[62:65]
	v_mfma_f32_16x16x32_bf16 v[50:53], v[144:147], v[184:187], v[50:53]
	v_mfma_f32_16x16x32_bf16 v[46:49], v[152:155], v[184:187], v[46:49]
	v_mfma_f32_16x16x32_bf16 v[34:37], v[144:147], v[192:195], v[34:37]
	v_mfma_f32_16x16x32_bf16 v[30:33], v[152:155], v[192:195], v[30:33]
	v_mfma_f32_16x16x32_bf16 v[18:21], v[144:147], v[200:203], v[18:21]
	v_mfma_f32_16x16x32_bf16 v[14:17], v[152:155], v[200:203], v[14:17]
	s_setprio 0
	s_setprio 1
	v_mfma_f32_16x16x32_bf16 v[58:61], v[156:159], v[172:175], v[58:61]
	v_mfma_f32_16x16x32_bf16 v[54:57], v[164:167], v[172:175], v[54:57]
	v_mfma_f32_16x16x32_bf16 v[42:45], v[156:159], v[180:183], v[42:45]
	v_mfma_f32_16x16x32_bf16 v[38:41], v[164:167], v[180:183], v[38:41]
	v_mfma_f32_16x16x32_bf16 v[26:29], v[156:159], v[188:191], v[26:29]
	v_mfma_f32_16x16x32_bf16 v[22:25], v[164:167], v[188:191], v[22:25]
	v_mfma_f32_16x16x32_bf16 v[10:13], v[156:159], v[196:199], v[10:13]
	v_mfma_f32_16x16x32_bf16 v[6:9], v[164:167], v[196:199], v[6:9]
	v_mfma_f32_16x16x32_bf16 v[58:61], v[160:163], v[176:179], v[58:61]
	v_mfma_f32_16x16x32_bf16 v[54:57], v[168:171], v[176:179], v[54:57]
	v_mfma_f32_16x16x32_bf16 v[42:45], v[160:163], v[184:187], v[42:45]
	v_mfma_f32_16x16x32_bf16 v[38:41], v[168:171], v[184:187], v[38:41]
	v_mfma_f32_16x16x32_bf16 v[26:29], v[160:163], v[192:195], v[26:29]
	v_mfma_f32_16x16x32_bf16 v[22:25], v[168:171], v[192:195], v[22:25]
	v_mfma_f32_16x16x32_bf16 v[10:13], v[160:163], v[200:203], v[10:13]
	v_mfma_f32_16x16x32_bf16 v[6:9], v[168:171], v[200:203], v[6:9]
	s_setprio 0
	s_barrier
	s_add_i32 s64, s64, 2
	s_add_u32 s33, s33, 0x100
	s_addc_u32 s61, s61, 0
	s_add_u32 s62, s62, 0x100
	s_addc_u32 s63, s63, 0
	s_cmp_gt_u32 s64, 13
	s_cbranch_scc0 .LBB0_454
	s_and_b64 vcc, exec, s[8:9]
	s_cbranch_vccz .LBB0_457
	s_barrier

.LBB0_480:
	s_add_u32 s58, s54, 0xffffff80
	s_addc_u32 s59, s55, -1
	s_cmp_eq_u32 s56, 4
	s_cselect_b32 s30, s25, s54
	s_cselect_b32 s31, s15, s55
	s_cselect_b32 s35, s17, s53
	s_cselect_b32 s34, s33, s52
	s_add_u32 s26, s30, 0x80
	s_addc_u32 s27, s31, 0
	s_add_u32 s28, s34, 0x80
	s_addc_u32 s29, s35, 0
	s_add_i32 s57, 0, 0x10000
	s_add_i32 s60, 0, 0x14000
	v_add_u32_e32 v152, s57, v1
	v_add_u32_e32 v168, s60, v1
	ds_read_b128 v[140:143], v152
	ds_read_b128 v[144:147], v152 offset:1024
	ds_read_b128 v[148:151], v152 offset:2048
	ds_read_b128 v[152:155], v152 offset:3072
	ds_read_b128 v[156:159], v168
	ds_read_b128 v[160:163], v168 offset:1024
	ds_read_b128 v[164:167], v168 offset:2048
	ds_read_b128 v[168:171], v168 offset:3072
	s_add_u32 s58, s58, 0x20000
	s_addc_u32 s59, s59, 0
	v_lshl_add_u64 v[204:205], s[58:59], 0, v[2:3]
	s_add_i32 m0, s43, 0xc000
	ds_read_b128 v[172:175], v5
	ds_read_b128 v[176:179], v5 offset:1024
	ds_read_b128 v[180:183], v5 offset:2048
	ds_read_b128 v[184:187], v5 offset:3072
	ds_read_b128 v[188:191], v5 offset:4096
	ds_read_b128 v[192:195], v5 offset:5120
	ds_read_b128 v[196:199], v5 offset:6144
	ds_read_b128 v[200:203], v5 offset:7168
	global_load_lds_dwordx4 v[204:205], off
	v_lshl_add_u64 v[204:205], s[58:59], 0, v[136:137]
	s_add_i32 m0, s43, 0xe000
	s_nop 0
	global_load_lds_dwordx4 v[204:205], off
	s_waitcnt vmcnt(8) lgkmcnt(0)
	s_barrier
	s_setprio 1
	v_mfma_f32_16x16x32_bf16 v[130:133], v[140:143], v[172:175], v[130:133]
	v_mfma_f32_16x16x32_bf16 v[126:129], v[148:151], v[172:175], v[126:129]
	v_mfma_f32_16x16x32_bf16 v[114:117], v[140:143], v[180:183], v[114:117]
	v_mfma_f32_16x16x32_bf16 v[110:113], v[148:151], v[180:183], v[110:113]
	v_mfma_f32_16x16x32_bf16 v[98:101], v[140:143], v[188:191], v[98:101]
	v_mfma_f32_16x16x32_bf16 v[94:97], v[148:151], v[188:191], v[94:97]
	v_mfma_f32_16x16x32_bf16 v[82:85], v[140:143], v[196:199], v[82:85]
	v_mfma_f32_16x16x32_bf16 v[78:81], v[148:151], v[196:199], v[78:81]
	v_mfma_f32_16x16x32_bf16 v[130:133], v[144:147], v[176:179], v[130:133]
	v_mfma_f32_16x16x32_bf16 v[126:129], v[152:155], v[176:179], v[126:129]
	v_mfma_f32_16x16x32_bf16 v[114:117], v[144:147], v[184:187], v[114:117]
	v_mfma_f32_16x16x32_bf16 v[110:113], v[152:155], v[184:187], v[110:113]
	v_mfma_f32_16x16x32_bf16 v[98:101], v[144:147], v[192:195], v[98:101]
	v_mfma_f32_16x16x32_bf16 v[94:97], v[152:155], v[192:195], v[94:97]
	v_mfma_f32_16x16x32_bf16 v[82:85], v[144:147], v[200:203], v[82:85]
	v_mfma_f32_16x16x32_bf16 v[78:81], v[152:155], v[200:203], v[78:81]
	s_setprio 0
	s_setprio 1
	v_mfma_f32_16x16x32_bf16 v[122:125], v[156:159], v[172:175], v[122:125]
	v_mfma_f32_16x16x32_bf16 v[118:121], v[164:167], v[172:175], v[118:121]
	v_mfma_f32_16x16x32_bf16 v[106:109], v[156:159], v[180:183], v[106:109]
	v_mfma_f32_16x16x32_bf16 v[102:105], v[164:167], v[180:183], v[102:105]
	v_mfma_f32_16x16x32_bf16 v[90:93], v[156:159], v[188:191], v[90:93]
	v_mfma_f32_16x16x32_bf16 v[86:89], v[164:167], v[188:191], v[86:89]
	v_mfma_f32_16x16x32_bf16 v[74:77], v[156:159], v[196:199], v[74:77]
	v_mfma_f32_16x16x32_bf16 v[70:73], v[164:167], v[196:199], v[70:73]
	v_mfma_f32_16x16x32_bf16 v[122:125], v[160:163], v[176:179], v[122:125]
	v_mfma_f32_16x16x32_bf16 v[118:121], v[168:171], v[176:179], v[118:121]
	v_mfma_f32_16x16x32_bf16 v[106:109], v[160:163], v[184:187], v[106:109]
	v_mfma_f32_16x16x32_bf16 v[102:105], v[168:171], v[184:187], v[102:105]
	v_mfma_f32_16x16x32_bf16 v[90:93], v[160:163], v[192:195], v[90:93]
	v_mfma_f32_16x16x32_bf16 v[86:89], v[168:171], v[192:195], v[86:89]
	v_mfma_f32_16x16x32_bf16 v[74:77], v[160:163], v[200:203], v[74:77]
	v_mfma_f32_16x16x32_bf16 v[70:73], v[168:171], v[200:203], v[70:73]
	s_setprio 0
	s_barrier
	s_add_i32 s57, s57, s42
	v_lshl_add_u64 v[204:205], s[34:35], 0, v[134:135]
	s_mov_b32 m0, s57
	ds_read_b128 v[172:175], v5 offset:16384
	ds_read_b128 v[176:179], v5 offset:17408
	ds_read_b128 v[180:183], v5 offset:18432
	ds_read_b128 v[184:187], v5 offset:19456
	ds_read_b128 v[188:191], v5 offset:20480
	ds_read_b128 v[192:195], v5 offset:21504
	ds_read_b128 v[196:199], v5 offset:22528
	ds_read_b128 v[200:203], v5 offset:23552
	global_load_lds_dwordx4 v[204:205], off
	s_add_i32 m0, s57, 0x2000
	v_lshl_add_u64 v[204:205], s[34:35], 0, v[138:139]
	s_add_u32 s34, s34, 0x20000
	s_addc_u32 s35, s35, 0
	s_add_i32 s57, s60, s42
	global_load_lds_dwordx4 v[204:205], off
	v_lshl_add_u64 v[204:205], s[34:35], 0, v[134:135]
	s_mov_b32 m0, s57
	s_nop 0
	global_load_lds_dwordx4 v[204:205], off
	v_lshl_add_u64 v[204:205], s[34:35], 0, v[138:139]
	s_add_i32 m0, s57, 0x2000
	s_nop 0
	global_load_lds_dwordx4 v[204:205], off
	v_lshl_add_u64 v[204:205], s[30:31], 0, v[2:3]
	s_mov_b32 m0, s43
	s_nop 0
	global_load_lds_dwordx4 v[204:205], off
	v_lshl_add_u64 v[204:205], s[30:31], 0, v[136:137]
	s_mov_b32 m0, s44
	s_nop 0
	global_load_lds_dwordx4 v[204:205], off
	s_waitcnt vmcnt(8) lgkmcnt(0)
	s_barrier
	s_setprio 1
	v_mfma_f32_16x16x32_bf16 v[66:69], v[140:143], v[172:175], v[66:69]
	v_mfma_f32_16x16x32_bf16 v[62:65], v[148:151], v[172:175], v[62:65]
	v_mfma_f32_16x16x32_bf16 v[50:53], v[140:143], v[180:183], v[50:53]
	v_mfma_f32_16x16x32_bf16 v[46:49], v[148:151], v[180:183], v[46:49]
	v_mfma_f32_16x16x32_bf16 v[34:37], v[140:143], v[188:191], v[34:37]
	v_mfma_f32_16x16x32_bf16 v[30:33], v[148:151], v[188:191], v[30:33]
	v_mfma_f32_16x16x32_bf16 v[18:21], v[140:143], v[196:199], v[18:21]
	v_mfma_f32_16x16x32_bf16 v[14:17], v[148:151], v[196:199], v[14:17]
	v_mfma_f32_16x16x32_bf16 v[66:69], v[144:147], v[176:179], v[66:69]
	v_mfma_f32_16x16x32_bf16 v[62:65], v[152:155], v[176:179], v[62:65]
	v_mfma_f32_16x16x32_bf16 v[50:53], v[144:147], v[184:187], v[50:53]
	v_mfma_f32_16x16x32_bf16 v[46:49], v[152:155], v[184:187], v[46:49]
	v_mfma_f32_16x16x32_bf16 v[34:37], v[144:147], v[192:195], v[34:37]
	v_mfma_f32_16x16x32_bf16 v[30:33], v[152:155], v[192:195], v[30:33]
	v_mfma_f32_16x16x32_bf16 v[18:21], v[144:147], v[200:203], v[18:21]
	v_mfma_f32_16x16x32_bf16 v[14:17], v[152:155], v[200:203], v[14:17]
	s_setprio 0
	s_setprio 1
	v_mfma_f32_16x16x32_bf16 v[58:61], v[156:159], v[172:175], v[58:61]
	v_mfma_f32_16x16x32_bf16 v[54:57], v[164:167], v[172:175], v[54:57]
	v_mfma_f32_16x16x32_bf16 v[42:45], v[156:159], v[180:183], v[42:45]
	v_mfma_f32_16x16x32_bf16 v[38:41], v[164:167], v[180:183], v[38:41]
	v_mfma_f32_16x16x32_bf16 v[26:29], v[156:159], v[188:191], v[26:29]
	v_mfma_f32_16x16x32_bf16 v[22:25], v[164:167], v[188:191], v[22:25]
	v_mfma_f32_16x16x32_bf16 v[10:13], v[156:159], v[196:199], v[10:13]
	v_mfma_f32_16x16x32_bf16 v[6:9], v[164:167], v[196:199], v[6:9]
	v_mfma_f32_16x16x32_bf16 v[58:61], v[160:163], v[176:179], v[58:61]
	v_mfma_f32_16x16x32_bf16 v[54:57], v[168:171], v[176:179], v[54:57]
	v_mfma_f32_16x16x32_bf16 v[42:45], v[160:163], v[184:187], v[42:45]
	v_mfma_f32_16x16x32_bf16 v[38:41], v[168:171], v[184:187], v[38:41]
	v_mfma_f32_16x16x32_bf16 v[26:29], v[160:163], v[192:195], v[26:29]
	v_mfma_f32_16x16x32_bf16 v[22:25], v[168:171], v[192:195], v[22:25]
	v_mfma_f32_16x16x32_bf16 v[10:13], v[160:163], v[200:203], v[10:13]
	v_mfma_f32_16x16x32_bf16 v[6:9], v[168:171], v[200:203], v[6:9]
	s_setprio 0
	s_barrier
	s_add_i32 s34, 0, 0x18000
	s_add_i32 s35, 0, 0x1c000
	v_add_u32_e32 v152, s34, v1
	v_add_u32_e32 v168, s35, v1
	ds_read_b128 v[140:143], v152
	ds_read_b128 v[144:147], v152 offset:1024
	ds_read_b128 v[148:151], v152 offset:2048
	ds_read_b128 v[152:155], v152 offset:3072
	ds_read_b128 v[156:159], v168
	ds_read_b128 v[160:163], v168 offset:1024
	ds_read_b128 v[164:167], v168 offset:2048
	ds_read_b128 v[168:171], v168 offset:3072
	s_add_u32 s30, s30, 0x20000
	s_addc_u32 s31, s31, 0
	s_mov_b32 m0, s45
	v_lshl_add_u64 v[204:205], s[30:31], 0, v[2:3]
	ds_read_b128 v[172:175], v5 offset:32768
	ds_read_b128 v[176:179], v5 offset:33792
	ds_read_b128 v[180:183], v5 offset:34816
	ds_read_b128 v[184:187], v5 offset:35840
	ds_read_b128 v[188:191], v5 offset:36864
	ds_read_b128 v[192:195], v5 offset:37888
	ds_read_b128 v[196:199], v5 offset:38912
	ds_read_b128 v[200:203], v5 offset:39936
	global_load_lds_dwordx4 v[204:205], off
	v_lshl_add_u64 v[204:205], s[30:31], 0, v[136:137]
	s_mov_b32 m0, s46
	s_nop 0
	global_load_lds_dwordx4 v[204:205], off
	s_waitcnt vmcnt(8) lgkmcnt(0)
	s_barrier
	s_setprio 1
	v_mfma_f32_16x16x32_bf16 v[130:133], v[140:143], v[172:175], v[130:133]
	v_mfma_f32_16x16x32_bf16 v[126:129], v[148:151], v[172:175], v[126:129]
	v_mfma_f32_16x16x32_bf16 v[114:117], v[140:143], v[180:183], v[114:117]
	v_mfma_f32_16x16x32_bf16 v[110:113], v[148:151], v[180:183], v[110:113]
	v_mfma_f32_16x16x32_bf16 v[98:101], v[140:143], v[188:191], v[98:101]
	v_mfma_f32_16x16x32_bf16 v[94:97], v[148:151], v[188:191], v[94:97]
	v_mfma_f32_16x16x32_bf16 v[82:85], v[140:143], v[196:199], v[82:85]
	v_mfma_f32_16x16x32_bf16 v[78:81], v[148:151], v[196:199], v[78:81]
	v_mfma_f32_16x16x32_bf16 v[130:133], v[144:147], v[176:179], v[130:133]
	v_mfma_f32_16x16x32_bf16 v[126:129], v[152:155], v[176:179], v[126:129]
	v_mfma_f32_16x16x32_bf16 v[114:117], v[144:147], v[184:187], v[114:117]
	v_mfma_f32_16x16x32_bf16 v[110:113], v[152:155], v[184:187], v[110:113]
	v_mfma_f32_16x16x32_bf16 v[98:101], v[144:147], v[192:195], v[98:101]
	v_mfma_f32_16x16x32_bf16 v[94:97], v[152:155], v[192:195], v[94:97]
	v_mfma_f32_16x16x32_bf16 v[82:85], v[144:147], v[200:203], v[82:85]
	v_mfma_f32_16x16x32_bf16 v[78:81], v[152:155], v[200:203], v[78:81]
	s_setprio 0
	s_setprio 1
	v_mfma_f32_16x16x32_bf16 v[122:125], v[156:159], v[172:175], v[122:125]
	v_mfma_f32_16x16x32_bf16 v[118:121], v[164:167], v[172:175], v[118:121]
	v_mfma_f32_16x16x32_bf16 v[106:109], v[156:159], v[180:183], v[106:109]
	v_mfma_f32_16x16x32_bf16 v[102:105], v[164:167], v[180:183], v[102:105]
	v_mfma_f32_16x16x32_bf16 v[90:93], v[156:159], v[188:191], v[90:93]
	v_mfma_f32_16x16x32_bf16 v[86:89], v[164:167], v[188:191], v[86:89]
	v_mfma_f32_16x16x32_bf16 v[74:77], v[156:159], v[196:199], v[74:77]
	v_mfma_f32_16x16x32_bf16 v[70:73], v[164:167], v[196:199], v[70:73]
	v_mfma_f32_16x16x32_bf16 v[122:125], v[160:163], v[176:179], v[122:125]
	v_mfma_f32_16x16x32_bf16 v[118:121], v[168:171], v[176:179], v[118:121]
	v_mfma_f32_16x16x32_bf16 v[106:109], v[160:163], v[184:187], v[106:109]
	v_mfma_f32_16x16x32_bf16 v[102:105], v[168:171], v[184:187], v[102:105]
	v_mfma_f32_16x16x32_bf16 v[90:93], v[160:163], v[192:195], v[90:93]
	v_mfma_f32_16x16x32_bf16 v[86:89], v[168:171], v[192:195], v[86:89]
	v_mfma_f32_16x16x32_bf16 v[74:77], v[160:163], v[200:203], v[74:77]
	v_mfma_f32_16x16x32_bf16 v[70:73], v[168:171], v[200:203], v[70:73]
	s_setprio 0
	s_barrier
	s_add_i32 s30, s34, s42
	v_lshl_add_u64 v[204:205], s[28:29], 0, v[134:135]
	s_mov_b32 m0, s30
	ds_read_b128 v[172:175], v5 offset:49152
	ds_read_b128 v[176:179], v5 offset:50176
	ds_read_b128 v[180:183], v5 offset:51200
	ds_read_b128 v[184:187], v5 offset:52224
	ds_read_b128 v[188:191], v5 offset:53248
	ds_read_b128 v[192:195], v5 offset:54272
	ds_read_b128 v[196:199], v5 offset:55296
	ds_read_b128 v[200:203], v5 offset:56320
	global_load_lds_dwordx4 v[204:205], off
	s_add_i32 m0, s30, 0x2000
	v_lshl_add_u64 v[204:205], s[28:29], 0, v[138:139]
	s_add_u32 s28, s28, 0x20000
	s_addc_u32 s29, s29, 0
	s_add_i32 s30, s35, s42
	global_load_lds_dwordx4 v[204:205], off
	v_lshl_add_u64 v[204:205], s[28:29], 0, v[134:135]
	s_mov_b32 m0, s30
	s_nop 0
	global_load_lds_dwordx4 v[204:205], off
	v_lshl_add_u64 v[204:205], s[28:29], 0, v[138:139]
	s_add_i32 m0, s30, 0x2000
	s_nop 0
	global_load_lds_dwordx4 v[204:205], off
	v_lshl_add_u64 v[204:205], s[26:27], 0, v[2:3]
	s_mov_b32 m0, s49
	s_nop 0
	global_load_lds_dwordx4 v[204:205], off
	v_lshl_add_u64 v[204:205], s[26:27], 0, v[136:137]
	s_mov_b32 m0, s50
	s_nop 0
	global_load_lds_dwordx4 v[204:205], off
	s_waitcnt vmcnt(8) lgkmcnt(0)
	s_barrier
	s_setprio 1
	v_mfma_f32_16x16x32_bf16 v[66:69], v[140:143], v[172:175], v[66:69]
	v_mfma_f32_16x16x32_bf16 v[62:65], v[148:151], v[172:175], v[62:65]
	v_mfma_f32_16x16x32_bf16 v[50:53], v[140:143], v[180:183], v[50:53]
	v_mfma_f32_16x16x32_bf16 v[46:49], v[148:151], v[180:183], v[46:49]
	v_mfma_f32_16x16x32_bf16 v[34:37], v[140:143], v[188:191], v[34:37]
	v_mfma_f32_16x16x32_bf16 v[30:33], v[148:151], v[188:191], v[30:33]
	v_mfma_f32_16x16x32_bf16 v[18:21], v[140:143], v[196:199], v[18:21]
	v_mfma_f32_16x16x32_bf16 v[14:17], v[148:151], v[196:199], v[14:17]
	v_mfma_f32_16x16x32_bf16 v[66:69], v[144:147], v[176:179], v[66:69]
	v_mfma_f32_16x16x32_bf16 v[62:65], v[152:155], v[176:179], v[62:65]
	v_mfma_f32_16x16x32_bf16 v[50:53], v[144:147], v[184:187], v[50:53]
	v_mfma_f32_16x16x32_bf16 v[46:49], v[152:155], v[184:187], v[46:49]
	v_mfma_f32_16x16x32_bf16 v[34:37], v[144:147], v[192:195], v[34:37]
	v_mfma_f32_16x16x32_bf16 v[30:33], v[152:155], v[192:195], v[30:33]
	v_mfma_f32_16x16x32_bf16 v[18:21], v[144:147], v[200:203], v[18:21]
	v_mfma_f32_16x16x32_bf16 v[14:17], v[152:155], v[200:203], v[14:17]
	s_setprio 0
	s_setprio 1
	v_mfma_f32_16x16x32_bf16 v[58:61], v[156:159], v[172:175], v[58:61]
	v_mfma_f32_16x16x32_bf16 v[54:57], v[164:167], v[172:175], v[54:57]
	v_mfma_f32_16x16x32_bf16 v[42:45], v[156:159], v[180:183], v[42:45]
	v_mfma_f32_16x16x32_bf16 v[38:41], v[164:167], v[180:183], v[38:41]
	v_mfma_f32_16x16x32_bf16 v[26:29], v[156:159], v[188:191], v[26:29]
	v_mfma_f32_16x16x32_bf16 v[22:25], v[164:167], v[188:191], v[22:25]
	v_mfma_f32_16x16x32_bf16 v[10:13], v[156:159], v[196:199], v[10:13]
	v_mfma_f32_16x16x32_bf16 v[6:9], v[164:167], v[196:199], v[6:9]
	v_mfma_f32_16x16x32_bf16 v[58:61], v[160:163], v[176:179], v[58:61]
	v_mfma_f32_16x16x32_bf16 v[54:57], v[168:171], v[176:179], v[54:57]
	v_mfma_f32_16x16x32_bf16 v[42:45], v[160:163], v[184:187], v[42:45]
	v_mfma_f32_16x16x32_bf16 v[38:41], v[168:171], v[184:187], v[38:41]
	v_mfma_f32_16x16x32_bf16 v[26:29], v[160:163], v[192:195], v[26:29]
	v_mfma_f32_16x16x32_bf16 v[22:25], v[168:171], v[192:195], v[22:25]
	v_mfma_f32_16x16x32_bf16 v[10:13], v[160:163], v[200:203], v[10:13]
	v_mfma_f32_16x16x32_bf16 v[6:9], v[168:171], v[200:203], v[6:9]
	s_setprio 0
	s_barrier
	s_add_i32 s56, s56, 2
	s_add_u32 s52, s52, 0x100
	s_addc_u32 s53, s53, 0
	s_add_u32 s54, s54, 0x100
	s_addc_u32 s55, s55, 0
	s_cmp_gt_u32 s56, 5
	s_cbranch_scc0 .LBB0_480
	s_and_b64 vcc, exec, s[8:9]
	s_cbranch_vccz .LBB0_483
	s_barrier

.LBB0_536:
	s_add_u32 s48, s45, 0xffffff80
	s_addc_u32 s49, s46, -1
	s_cmp_eq_u32 s47, 4
	s_cselect_b32 s22, s41, s45
	s_cselect_b32 s23, s7, s46
	s_cselect_b32 s25, s9, s44
	s_cselect_b32 s24, s42, s43
	s_add_u32 s18, s22, 0x80
	s_addc_u32 s19, s23, 0
	s_add_u32 s20, s24, 0x80
	s_addc_u32 s21, s25, 0
	s_add_i32 s50, 0, 0x10000
	s_add_i32 s51, 0, 0x14000
	v_add_u32_e32 v152, s50, v1
	v_add_u32_e32 v168, s51, v1
	ds_read_b128 v[140:143], v152
	ds_read_b128 v[144:147], v152 offset:1024
	ds_read_b128 v[148:151], v152 offset:2048
	ds_read_b128 v[152:155], v152 offset:3072
	ds_read_b128 v[156:159], v168
	ds_read_b128 v[160:163], v168 offset:1024
	ds_read_b128 v[164:167], v168 offset:2048
	ds_read_b128 v[168:171], v168 offset:3072
	s_add_u32 s48, s48, 0x20000
	s_addc_u32 s49, s49, 0
	v_lshl_add_u64 v[204:205], s[48:49], 0, v[2:3]
	s_add_i32 m0, s15, 0xc000
	ds_read_b128 v[172:175], v5
	ds_read_b128 v[176:179], v5 offset:1024
	ds_read_b128 v[180:183], v5 offset:2048
	ds_read_b128 v[184:187], v5 offset:3072
	ds_read_b128 v[188:191], v5 offset:4096
	ds_read_b128 v[192:195], v5 offset:5120
	ds_read_b128 v[196:199], v5 offset:6144
	ds_read_b128 v[200:203], v5 offset:7168
	global_load_lds_dwordx4 v[204:205], off
	v_lshl_add_u64 v[204:205], s[48:49], 0, v[136:137]
	s_add_i32 m0, s15, 0xe000
	s_nop 0
	global_load_lds_dwordx4 v[204:205], off
	s_waitcnt vmcnt(8) lgkmcnt(0)
	s_barrier
	s_setprio 1
	v_mfma_f32_16x16x32_bf16 v[130:133], v[140:143], v[172:175], v[130:133]
	v_mfma_f32_16x16x32_bf16 v[126:129], v[148:151], v[172:175], v[126:129]
	v_mfma_f32_16x16x32_bf16 v[122:125], v[140:143], v[180:183], v[122:125]
	v_mfma_f32_16x16x32_bf16 v[114:117], v[148:151], v[180:183], v[114:117]
	v_mfma_f32_16x16x32_bf16 v[106:109], v[140:143], v[188:191], v[106:109]
	v_mfma_f32_16x16x32_bf16 v[98:101], v[148:151], v[188:191], v[98:101]
	v_mfma_f32_16x16x32_bf16 v[90:93], v[140:143], v[196:199], v[90:93]
	v_mfma_f32_16x16x32_bf16 v[82:85], v[148:151], v[196:199], v[82:85]
	v_mfma_f32_16x16x32_bf16 v[130:133], v[144:147], v[176:179], v[130:133]
	v_mfma_f32_16x16x32_bf16 v[126:129], v[152:155], v[176:179], v[126:129]
	v_mfma_f32_16x16x32_bf16 v[122:125], v[144:147], v[184:187], v[122:125]
	v_mfma_f32_16x16x32_bf16 v[114:117], v[152:155], v[184:187], v[114:117]
	v_mfma_f32_16x16x32_bf16 v[106:109], v[144:147], v[192:195], v[106:109]
	v_mfma_f32_16x16x32_bf16 v[98:101], v[152:155], v[192:195], v[98:101]
	v_mfma_f32_16x16x32_bf16 v[90:93], v[144:147], v[200:203], v[90:93]
	v_mfma_f32_16x16x32_bf16 v[82:85], v[152:155], v[200:203], v[82:85]
	s_setprio 0
	s_setprio 1
	v_mfma_f32_16x16x32_bf16 v[118:121], v[156:159], v[172:175], v[118:121]
	v_mfma_f32_16x16x32_bf16 v[110:113], v[164:167], v[172:175], v[110:113]
	v_mfma_f32_16x16x32_bf16 v[102:105], v[156:159], v[180:183], v[102:105]
	v_mfma_f32_16x16x32_bf16 v[94:97], v[164:167], v[180:183], v[94:97]
	v_mfma_f32_16x16x32_bf16 v[86:89], v[156:159], v[188:191], v[86:89]
	v_mfma_f32_16x16x32_bf16 v[78:81], v[164:167], v[188:191], v[78:81]
	v_mfma_f32_16x16x32_bf16 v[74:77], v[156:159], v[196:199], v[74:77]
	v_mfma_f32_16x16x32_bf16 v[70:73], v[164:167], v[196:199], v[70:73]
	v_mfma_f32_16x16x32_bf16 v[118:121], v[160:163], v[176:179], v[118:121]
	v_mfma_f32_16x16x32_bf16 v[110:113], v[168:171], v[176:179], v[110:113]
	v_mfma_f32_16x16x32_bf16 v[102:105], v[160:163], v[184:187], v[102:105]
	v_mfma_f32_16x16x32_bf16 v[94:97], v[168:171], v[184:187], v[94:97]
	v_mfma_f32_16x16x32_bf16 v[86:89], v[160:163], v[192:195], v[86:89]
	v_mfma_f32_16x16x32_bf16 v[78:81], v[168:171], v[192:195], v[78:81]
	v_mfma_f32_16x16x32_bf16 v[74:77], v[160:163], v[200:203], v[74:77]
	v_mfma_f32_16x16x32_bf16 v[70:73], v[168:171], v[200:203], v[70:73]
	s_setprio 0
	s_barrier
	s_add_i32 s48, s50, s29
	v_lshl_add_u64 v[204:205], s[24:25], 0, v[134:135]
	s_mov_b32 m0, s48
	ds_read_b128 v[172:175], v5 offset:16384
	ds_read_b128 v[176:179], v5 offset:17408
	ds_read_b128 v[180:183], v5 offset:18432
	ds_read_b128 v[184:187], v5 offset:19456
	ds_read_b128 v[188:191], v5 offset:20480
	ds_read_b128 v[192:195], v5 offset:21504
	ds_read_b128 v[196:199], v5 offset:22528
	ds_read_b128 v[200:203], v5 offset:23552
	global_load_lds_dwordx4 v[204:205], off
	s_add_i32 m0, s48, 0x2000
	v_lshl_add_u64 v[204:205], s[24:25], 0, v[138:139]
	s_add_u32 s24, s24, 0x20000
	s_addc_u32 s25, s25, 0
	s_add_i32 s48, s51, s29
	global_load_lds_dwordx4 v[204:205], off
	v_lshl_add_u64 v[204:205], s[24:25], 0, v[134:135]
	s_mov_b32 m0, s48
	s_nop 0
	global_load_lds_dwordx4 v[204:205], off
	v_lshl_add_u64 v[204:205], s[24:25], 0, v[138:139]
	s_add_i32 m0, s48, 0x2000
	s_nop 0
	global_load_lds_dwordx4 v[204:205], off
	v_lshl_add_u64 v[204:205], s[22:23], 0, v[2:3]
	s_mov_b32 m0, s15
	s_nop 0
	global_load_lds_dwordx4 v[204:205], off
	v_lshl_add_u64 v[204:205], s[22:23], 0, v[136:137]
	s_mov_b32 m0, s17
	s_nop 0
	global_load_lds_dwordx4 v[204:205], off
	s_waitcnt vmcnt(8) lgkmcnt(0)
	s_barrier
	s_setprio 1
	v_mfma_f32_16x16x32_bf16 v[66:69], v[140:143], v[172:175], v[66:69]
	v_mfma_f32_16x16x32_bf16 v[62:65], v[148:151], v[172:175], v[62:65]
	v_mfma_f32_16x16x32_bf16 v[58:61], v[140:143], v[180:183], v[58:61]
	v_mfma_f32_16x16x32_bf16 v[50:53], v[148:151], v[180:183], v[50:53]
	v_mfma_f32_16x16x32_bf16 v[42:45], v[140:143], v[188:191], v[42:45]
	v_mfma_f32_16x16x32_bf16 v[34:37], v[148:151], v[188:191], v[34:37]
	v_mfma_f32_16x16x32_bf16 v[26:29], v[140:143], v[196:199], v[26:29]
	v_mfma_f32_16x16x32_bf16 v[18:21], v[148:151], v[196:199], v[18:21]
	v_mfma_f32_16x16x32_bf16 v[66:69], v[144:147], v[176:179], v[66:69]
	v_mfma_f32_16x16x32_bf16 v[62:65], v[152:155], v[176:179], v[62:65]
	v_mfma_f32_16x16x32_bf16 v[58:61], v[144:147], v[184:187], v[58:61]
	v_mfma_f32_16x16x32_bf16 v[50:53], v[152:155], v[184:187], v[50:53]
	v_mfma_f32_16x16x32_bf16 v[42:45], v[144:147], v[192:195], v[42:45]
	v_mfma_f32_16x16x32_bf16 v[34:37], v[152:155], v[192:195], v[34:37]
	v_mfma_f32_16x16x32_bf16 v[26:29], v[144:147], v[200:203], v[26:29]
	v_mfma_f32_16x16x32_bf16 v[18:21], v[152:155], v[200:203], v[18:21]
	s_setprio 0
	s_setprio 1
	v_mfma_f32_16x16x32_bf16 v[54:57], v[156:159], v[172:175], v[54:57]
	v_mfma_f32_16x16x32_bf16 v[46:49], v[164:167], v[172:175], v[46:49]
	v_mfma_f32_16x16x32_bf16 v[38:41], v[156:159], v[180:183], v[38:41]
	v_mfma_f32_16x16x32_bf16 v[30:33], v[164:167], v[180:183], v[30:33]
	v_mfma_f32_16x16x32_bf16 v[22:25], v[156:159], v[188:191], v[22:25]
	v_mfma_f32_16x16x32_bf16 v[14:17], v[164:167], v[188:191], v[14:17]
	v_mfma_f32_16x16x32_bf16 v[10:13], v[156:159], v[196:199], v[10:13]
	v_mfma_f32_16x16x32_bf16 v[6:9], v[164:167], v[196:199], v[6:9]
	v_mfma_f32_16x16x32_bf16 v[54:57], v[160:163], v[176:179], v[54:57]
	v_mfma_f32_16x16x32_bf16 v[46:49], v[168:171], v[176:179], v[46:49]
	v_mfma_f32_16x16x32_bf16 v[38:41], v[160:163], v[184:187], v[38:41]
	v_mfma_f32_16x16x32_bf16 v[30:33], v[168:171], v[184:187], v[30:33]
	v_mfma_f32_16x16x32_bf16 v[22:25], v[160:163], v[192:195], v[22:25]
	v_mfma_f32_16x16x32_bf16 v[14:17], v[168:171], v[192:195], v[14:17]
	v_mfma_f32_16x16x32_bf16 v[10:13], v[160:163], v[200:203], v[10:13]
	v_mfma_f32_16x16x32_bf16 v[6:9], v[168:171], v[200:203], v[6:9]
	s_setprio 0
	s_barrier
	s_add_i32 s24, 0, 0x18000
	s_add_i32 s25, 0, 0x1c000
	v_add_u32_e32 v152, s24, v1
	v_add_u32_e32 v168, s25, v1
	ds_read_b128 v[140:143], v152
	ds_read_b128 v[144:147], v152 offset:1024
	ds_read_b128 v[148:151], v152 offset:2048
	ds_read_b128 v[152:155], v152 offset:3072
	ds_read_b128 v[156:159], v168
	ds_read_b128 v[160:163], v168 offset:1024
	ds_read_b128 v[164:167], v168 offset:2048
	ds_read_b128 v[168:171], v168 offset:3072
	s_add_u32 s22, s22, 0x20000
	s_addc_u32 s23, s23, 0
	s_mov_b32 m0, s31
	v_lshl_add_u64 v[204:205], s[22:23], 0, v[2:3]
	ds_read_b128 v[172:175], v5 offset:32768
	ds_read_b128 v[176:179], v5 offset:33792
	ds_read_b128 v[180:183], v5 offset:34816
	ds_read_b128 v[184:187], v5 offset:35840
	ds_read_b128 v[188:191], v5 offset:36864
	ds_read_b128 v[192:195], v5 offset:37888
	ds_read_b128 v[196:199], v5 offset:38912
	ds_read_b128 v[200:203], v5 offset:39936
	global_load_lds_dwordx4 v[204:205], off
	v_lshl_add_u64 v[204:205], s[22:23], 0, v[136:137]
	s_mov_b32 m0, s33
	s_nop 0
	global_load_lds_dwordx4 v[204:205], off
	s_waitcnt vmcnt(8) lgkmcnt(0)
	s_barrier
	s_setprio 1
	v_mfma_f32_16x16x32_bf16 v[130:133], v[140:143], v[172:175], v[130:133]
	v_mfma_f32_16x16x32_bf16 v[126:129], v[148:151], v[172:175], v[126:129]
	v_mfma_f32_16x16x32_bf16 v[122:125], v[140:143], v[180:183], v[122:125]
	v_mfma_f32_16x16x32_bf16 v[114:117], v[148:151], v[180:183], v[114:117]
	v_mfma_f32_16x16x32_bf16 v[106:109], v[140:143], v[188:191], v[106:109]
	v_mfma_f32_16x16x32_bf16 v[98:101], v[148:151], v[188:191], v[98:101]
	v_mfma_f32_16x16x32_bf16 v[90:93], v[140:143], v[196:199], v[90:93]
	v_mfma_f32_16x16x32_bf16 v[82:85], v[148:151], v[196:199], v[82:85]
	v_mfma_f32_16x16x32_bf16 v[130:133], v[144:147], v[176:179], v[130:133]
	v_mfma_f32_16x16x32_bf16 v[126:129], v[152:155], v[176:179], v[126:129]
	v_mfma_f32_16x16x32_bf16 v[122:125], v[144:147], v[184:187], v[122:125]
	v_mfma_f32_16x16x32_bf16 v[114:117], v[152:155], v[184:187], v[114:117]
	v_mfma_f32_16x16x32_bf16 v[106:109], v[144:147], v[192:195], v[106:109]
	v_mfma_f32_16x16x32_bf16 v[98:101], v[152:155], v[192:195], v[98:101]
	v_mfma_f32_16x16x32_bf16 v[90:93], v[144:147], v[200:203], v[90:93]
	v_mfma_f32_16x16x32_bf16 v[82:85], v[152:155], v[200:203], v[82:85]
	s_setprio 0
	s_setprio 1
	v_mfma_f32_16x16x32_bf16 v[118:121], v[156:159], v[172:175], v[118:121]
	v_mfma_f32_16x16x32_bf16 v[110:113], v[164:167], v[172:175], v[110:113]
	v_mfma_f32_16x16x32_bf16 v[102:105], v[156:159], v[180:183], v[102:105]
	v_mfma_f32_16x16x32_bf16 v[94:97], v[164:167], v[180:183], v[94:97]
	v_mfma_f32_16x16x32_bf16 v[86:89], v[156:159], v[188:191], v[86:89]
	v_mfma_f32_16x16x32_bf16 v[78:81], v[164:167], v[188:191], v[78:81]
	v_mfma_f32_16x16x32_bf16 v[74:77], v[156:159], v[196:199], v[74:77]
	v_mfma_f32_16x16x32_bf16 v[70:73], v[164:167], v[196:199], v[70:73]
	v_mfma_f32_16x16x32_bf16 v[118:121], v[160:163], v[176:179], v[118:121]
	v_mfma_f32_16x16x32_bf16 v[110:113], v[168:171], v[176:179], v[110:113]
	v_mfma_f32_16x16x32_bf16 v[102:105], v[160:163], v[184:187], v[102:105]
	v_mfma_f32_16x16x32_bf16 v[94:97], v[168:171], v[184:187], v[94:97]
	v_mfma_f32_16x16x32_bf16 v[86:89], v[160:163], v[192:195], v[86:89]
	v_mfma_f32_16x16x32_bf16 v[78:81], v[168:171], v[192:195], v[78:81]
	v_mfma_f32_16x16x32_bf16 v[74:77], v[160:163], v[200:203], v[74:77]
	v_mfma_f32_16x16x32_bf16 v[70:73], v[168:171], v[200:203], v[70:73]
	s_setprio 0
	s_barrier
	s_add_i32 s22, s24, s29
	v_lshl_add_u64 v[204:205], s[20:21], 0, v[134:135]
	s_mov_b32 m0, s22
	ds_read_b128 v[172:175], v5 offset:49152
	ds_read_b128 v[176:179], v5 offset:50176
	ds_read_b128 v[180:183], v5 offset:51200
	ds_read_b128 v[184:187], v5 offset:52224
	ds_read_b128 v[188:191], v5 offset:53248
	ds_read_b128 v[192:195], v5 offset:54272
	ds_read_b128 v[196:199], v5 offset:55296
	ds_read_b128 v[200:203], v5 offset:56320
	global_load_lds_dwordx4 v[204:205], off
	s_add_i32 m0, s22, 0x2000
	v_lshl_add_u64 v[204:205], s[20:21], 0, v[138:139]
	s_add_u32 s20, s20, 0x20000
	s_addc_u32 s21, s21, 0
	s_add_i32 s22, s25, s29
	global_load_lds_dwordx4 v[204:205], off
	v_lshl_add_u64 v[204:205], s[20:21], 0, v[134:135]
	s_mov_b32 m0, s22
	s_nop 0
	global_load_lds_dwordx4 v[204:205], off
	v_lshl_add_u64 v[204:205], s[20:21], 0, v[138:139]
	s_add_i32 m0, s22, 0x2000
	s_nop 0
	global_load_lds_dwordx4 v[204:205], off
	v_lshl_add_u64 v[204:205], s[18:19], 0, v[2:3]
	s_mov_b32 m0, s38
	s_nop 0
	global_load_lds_dwordx4 v[204:205], off
	v_lshl_add_u64 v[204:205], s[18:19], 0, v[136:137]
	s_mov_b32 m0, s39
	s_nop 0
	global_load_lds_dwordx4 v[204:205], off
	s_waitcnt vmcnt(8) lgkmcnt(0)
	s_barrier
	s_setprio 1
	v_mfma_f32_16x16x32_bf16 v[66:69], v[140:143], v[172:175], v[66:69]
	v_mfma_f32_16x16x32_bf16 v[62:65], v[148:151], v[172:175], v[62:65]
	v_mfma_f32_16x16x32_bf16 v[58:61], v[140:143], v[180:183], v[58:61]
	v_mfma_f32_16x16x32_bf16 v[50:53], v[148:151], v[180:183], v[50:53]
	v_mfma_f32_16x16x32_bf16 v[42:45], v[140:143], v[188:191], v[42:45]
	v_mfma_f32_16x16x32_bf16 v[34:37], v[148:151], v[188:191], v[34:37]
	v_mfma_f32_16x16x32_bf16 v[26:29], v[140:143], v[196:199], v[26:29]
	v_mfma_f32_16x16x32_bf16 v[18:21], v[148:151], v[196:199], v[18:21]
	v_mfma_f32_16x16x32_bf16 v[66:69], v[144:147], v[176:179], v[66:69]
	v_mfma_f32_16x16x32_bf16 v[62:65], v[152:155], v[176:179], v[62:65]
	v_mfma_f32_16x16x32_bf16 v[58:61], v[144:147], v[184:187], v[58:61]
	v_mfma_f32_16x16x32_bf16 v[50:53], v[152:155], v[184:187], v[50:53]
	v_mfma_f32_16x16x32_bf16 v[42:45], v[144:147], v[192:195], v[42:45]
	v_mfma_f32_16x16x32_bf16 v[34:37], v[152:155], v[192:195], v[34:37]
	v_mfma_f32_16x16x32_bf16 v[26:29], v[144:147], v[200:203], v[26:29]
	v_mfma_f32_16x16x32_bf16 v[18:21], v[152:155], v[200:203], v[18:21]
	s_setprio 0
	s_setprio 1
	v_mfma_f32_16x16x32_bf16 v[54:57], v[156:159], v[172:175], v[54:57]
	v_mfma_f32_16x16x32_bf16 v[46:49], v[164:167], v[172:175], v[46:49]
	v_mfma_f32_16x16x32_bf16 v[38:41], v[156:159], v[180:183], v[38:41]
	v_mfma_f32_16x16x32_bf16 v[30:33], v[164:167], v[180:183], v[30:33]
	v_mfma_f32_16x16x32_bf16 v[22:25], v[156:159], v[188:191], v[22:25]
	v_mfma_f32_16x16x32_bf16 v[14:17], v[164:167], v[188:191], v[14:17]
	v_mfma_f32_16x16x32_bf16 v[10:13], v[156:159], v[196:199], v[10:13]
	v_mfma_f32_16x16x32_bf16 v[6:9], v[164:167], v[196:199], v[6:9]
	v_mfma_f32_16x16x32_bf16 v[54:57], v[160:163], v[176:179], v[54:57]
	v_mfma_f32_16x16x32_bf16 v[46:49], v[168:171], v[176:179], v[46:49]
	v_mfma_f32_16x16x32_bf16 v[38:41], v[160:163], v[184:187], v[38:41]
	v_mfma_f32_16x16x32_bf16 v[30:33], v[168:171], v[184:187], v[30:33]
	v_mfma_f32_16x16x32_bf16 v[22:25], v[160:163], v[192:195], v[22:25]
	v_mfma_f32_16x16x32_bf16 v[14:17], v[168:171], v[192:195], v[14:17]
	v_mfma_f32_16x16x32_bf16 v[10:13], v[160:163], v[200:203], v[10:13]
	v_mfma_f32_16x16x32_bf16 v[6:9], v[168:171], v[200:203], v[6:9]
	s_setprio 0
	s_barrier
	s_add_i32 s47, s47, 2
	s_add_u32 s43, s43, 0x100
	s_addc_u32 s44, s44, 0
	s_add_u32 s45, s45, 0x100
	s_addc_u32 s46, s46, 0
	s_cmp_gt_u32 s47, 5
	s_cbranch_scc0 .LBB0_536
	s_lshl_b32 s20, s16, 8
	v_mov_b32_e32 v140, v0
	s_mov_b64 s[18:19], s[84:85]
	s_lshl_b32 s7, s14, 8
	s_ashr_i32 s21, s20, 31
	s_add_i32 s7, s7, s34
	s_lshl_b64 s[20:21], s[20:21], 1
	v_and_b32_e32 v142, 15, v140
	s_add_u32 s18, s18, s20
	v_or_b32_e32 v146, s7, v142
	v_lshrrev_b32_e32 v140, 1, v140
	s_addc_u32 s19, s19, s21
	s_ashr_i32 s9, s7, 11
	v_mov_b32_e32 v143, s7
	s_movk_i32 s7, 0x7cf
	v_and_or_b32 v140, v140, 24, s35
	s_mulk_i32 s9, 0x810
	v_bitop3_b32 v142, v142, s7, v143 bitop3:0xc8
	v_lshlrev_b32_e32 v140, 1, v140
	v_mov_b32_e32 v141, v4
	v_add_u32_e32 v142, s9, v142
	v_lshl_add_u64 v[140:141], s[18:19], 0, v[140:141]
	s_mov_b64 s[18:19], 0x2c900000
	v_ashrrev_i32_e32 v143, 31, v142
	v_lshl_add_u64 v[140:141], v[140:141], 0, s[18:19]
	v_lshlrev_b64 v[144:145], 13, v[142:143]
	v_lshl_add_u64 v[144:145], v[140:141], 0, v[144:145]
	v_cvt_pk_bf16_f32 v130, v130, v131
	v_cvt_pk_bf16_f32 v131, v132, v133
	v_cvt_pk_bf16_f32 v132, v126, v127
	v_cvt_pk_bf16_f32 v133, v128, v129
	global_store_dwordx4 v[144:145], v[130:133], off nt
	v_cvt_pk_bf16_f32 v118, v118, v119
	v_cvt_pk_bf16_f32 v119, v120, v121
	v_cvt_pk_bf16_f32 v120, v110, v111
	v_add_u32_e32 v110, 16, v142
	v_ashrrev_i32_e32 v111, 31, v110
	v_lshlrev_b64 v[110:111], 13, v[110:111]
	v_cvt_pk_bf16_f32 v121, v112, v113
	global_store_dwordx4 v[144:145], v[118:121], off offset:256 nt
	s_movk_i32 s7, 0x810
	s_and_b64 vcc, exec, s[0:1]
	v_lshl_add_u64 v[118:119], v[140:141], 0, v[110:111]
	v_cvt_pk_bf16_f32 v110, v122, v123
	v_cvt_pk_bf16_f32 v111, v124, v125
	v_cvt_pk_bf16_f32 v112, v114, v115
	v_cvt_pk_bf16_f32 v113, v116, v117
	global_store_dwordx4 v[118:119], v[110:113], off nt
	v_cvt_pk_bf16_f32 v102, v102, v103
	v_cvt_pk_bf16_f32 v103, v104, v105
	v_cvt_pk_bf16_f32 v104, v94, v95
	v_add_u32_e32 v94, 32, v142
	v_ashrrev_i32_e32 v95, 31, v94
	v_lshlrev_b64 v[94:95], 13, v[94:95]
	v_cvt_pk_bf16_f32 v105, v96, v97
	global_store_dwordx4 v[118:119], v[102:105], off offset:256 nt
	s_mov_b32 s16, s8
	s_mov_b32 s14, s6
	v_lshl_add_u64 v[102:103], v[140:141], 0, v[94:95]
	v_cvt_pk_bf16_f32 v94, v106, v107
	v_cvt_pk_bf16_f32 v95, v108, v109
	v_cvt_pk_bf16_f32 v96, v98, v99
	v_cvt_pk_bf16_f32 v97, v100, v101
	global_store_dwordx4 v[102:103], v[94:97], off nt
	v_cvt_pk_bf16_f32 v86, v86, v87
	v_cvt_pk_bf16_f32 v87, v88, v89
	v_cvt_pk_bf16_f32 v88, v78, v79
	v_add_u32_e32 v78, 48, v142
	v_ashrrev_i32_e32 v79, 31, v78
	v_lshlrev_b64 v[78:79], 13, v[78:79]
	v_cvt_pk_bf16_f32 v89, v80, v81
	global_store_dwordx4 v[102:103], v[86:89], off offset:256 nt
	s_mov_b64 s[20:21], s[10:11]
	s_mov_b64 s[18:19], s[12:13]
	v_lshl_add_u64 v[86:87], v[140:141], 0, v[78:79]
	v_cvt_pk_bf16_f32 v78, v90, v91
	v_cvt_pk_bf16_f32 v79, v92, v93
	v_cvt_pk_bf16_f32 v80, v82, v83
	v_cvt_pk_bf16_f32 v81, v84, v85
	global_store_dwordx4 v[86:87], v[78:81], off nt
	v_cvt_pk_bf16_f32 v74, v74, v75
	v_cvt_pk_bf16_f32 v75, v76, v77
	v_cvt_pk_bf16_f32 v76, v70, v71
	v_add_u32_e32 v70, 0x80, v146
	v_ashrrev_i32_e32 v71, 11, v70
	v_and_b32_e32 v70, 0x7cf, v70
	v_mad_i32_i24 v70, v71, s7, v70
	v_ashrrev_i32_e32 v71, 31, v70
	v_cvt_pk_bf16_f32 v77, v72, v73
	v_lshlrev_b64 v[72:73], 13, v[70:71]
	global_store_dwordx4 v[86:87], v[74:77], off offset:256 nt
	v_lshl_add_u64 v[72:73], v[140:141], 0, v[72:73]
	v_cvt_pk_bf16_f32 v66, v66, v67
	v_cvt_pk_bf16_f32 v67, v68, v69
	v_cvt_pk_bf16_f32 v68, v62, v63
	v_cvt_pk_bf16_f32 v69, v64, v65
	global_store_dwordx4 v[72:73], v[66:69], off nt
	v_cvt_pk_bf16_f32 v54, v54, v55
	v_cvt_pk_bf16_f32 v55, v56, v57
	v_cvt_pk_bf16_f32 v56, v46, v47
	v_add_u32_e32 v46, 16, v70
	v_ashrrev_i32_e32 v47, 31, v46
	v_lshlrev_b64 v[46:47], 13, v[46:47]
	v_cvt_pk_bf16_f32 v57, v48, v49
	global_store_dwordx4 v[72:73], v[54:57], off offset:256 nt
	s_mov_b32 s51, 0x40c000
	s_mov_b32 s47, 0x120000
	v_lshl_add_u64 v[54:55], v[140:141], 0, v[46:47]
	v_cvt_pk_bf16_f32 v46, v58, v59
	v_cvt_pk_bf16_f32 v47, v60, v61
	v_cvt_pk_bf16_f32 v48, v50, v51
	v_cvt_pk_bf16_f32 v49, v52, v53
	global_store_dwordx4 v[54:55], v[46:49], off nt
	v_cvt_pk_bf16_f32 v38, v38, v39
	v_cvt_pk_bf16_f32 v39, v40, v41
	v_cvt_pk_bf16_f32 v40, v30, v31
	v_add_u32_e32 v30, 32, v70
	v_ashrrev_i32_e32 v31, 31, v30
	v_lshlrev_b64 v[30:31], 13, v[30:31]
	v_cvt_pk_bf16_f32 v41, v32, v33
	global_store_dwordx4 v[54:55], v[38:41], off offset:256 nt
	s_mov_b64 s[48:49], 0x7ffff
	s_nop 0
	v_lshl_add_u64 v[38:39], v[140:141], 0, v[30:31]
	v_cvt_pk_bf16_f32 v30, v42, v43
	v_cvt_pk_bf16_f32 v31, v44, v45
	v_cvt_pk_bf16_f32 v32, v34, v35
	v_cvt_pk_bf16_f32 v33, v36, v37
	global_store_dwordx4 v[38:39], v[30:33], off nt
	v_cvt_pk_bf16_f32 v22, v22, v23
	v_cvt_pk_bf16_f32 v23, v24, v25
	v_cvt_pk_bf16_f32 v24, v14, v15
	v_add_u32_e32 v14, 48, v70
	v_ashrrev_i32_e32 v15, 31, v14
	v_lshlrev_b64 v[14:15], 13, v[14:15]
	v_cvt_pk_bf16_f32 v25, v16, v17
	global_store_dwordx4 v[38:39], v[22:25], off offset:256 nt
	s_nop 1
	v_lshl_add_u64 v[22:23], v[140:141], 0, v[14:15]
	v_cvt_pk_bf16_f32 v14, v26, v27
	v_cvt_pk_bf16_f32 v15, v28, v29
	v_cvt_pk_bf16_f32 v16, v18, v19
	v_cvt_pk_bf16_f32 v17, v20, v21
	global_store_dwordx4 v[22:23], v[14:17], off nt
	v_cvt_pk_bf16_f32 v10, v10, v11
	v_cvt_pk_bf16_f32 v11, v12, v13
	v_cvt_pk_bf16_f32 v12, v6, v7
	v_cvt_pk_bf16_f32 v13, v8, v9
	global_store_dwordx4 v[22:23], v[10:13], off offset:256 nt
	s_cbranch_vccz .LBB0_529
	s_waitcnt vmcnt(0)
	s_cmpk_gt_u32 s28, 0xff
	s_cbranch_scc1 .LBB0_540
	s_barrier

.LBB0_924:
	s_add_u32 s48, s45, 0xffffff80
	s_addc_u32 s49, s46, -1
	s_cmp_eq_u32 s47, 60
	s_cselect_b32 s22, s9, s45
	s_cselect_b32 s23, s7, s46
	s_cselect_b32 s25, s11, s44
	s_cselect_b32 s24, s13, s33
	s_add_u32 s18, s22, 0x80
	s_addc_u32 s19, s23, 0
	s_add_u32 s20, s24, 0x80
	s_addc_u32 s21, s25, 0
	s_add_i32 s50, 0, 0x10000
	s_add_i32 s51, 0, 0x14000
	v_add_u32_e32 v90, s50, v1
	v_add_u32_e32 v162, s51, v1
	ds_read_b128 v[78:81], v90
	ds_read_b128 v[82:85], v90 offset:1024
	ds_read_b128 v[86:89], v90 offset:2048
	ds_read_b128 v[90:93], v90 offset:3072
	ds_read_b128 v[142:145], v162
	ds_read_b128 v[146:149], v162 offset:1024
	ds_read_b128 v[158:161], v162 offset:2048
	ds_read_b128 v[162:165], v162 offset:3072
	s_add_u32 s48, s48, 0x100000
	s_addc_u32 s49, s49, 0
	v_lshl_add_u64 v[198:199], s[48:49], 0, v[2:3]
	s_add_i32 m0, s35, 0xc000
	ds_read_b128 v[166:169], v5
	ds_read_b128 v[170:173], v5 offset:1024
	ds_read_b128 v[174:177], v5 offset:2048
	ds_read_b128 v[178:181], v5 offset:3072
	ds_read_b128 v[182:185], v5 offset:4096
	ds_read_b128 v[186:189], v5 offset:5120
	ds_read_b128 v[190:193], v5 offset:6144
	ds_read_b128 v[194:197], v5 offset:7168
	global_load_lds_dwordx4 v[198:199], off
	v_lshl_add_u64 v[198:199], s[48:49], 0, v[218:219]
	s_add_i32 m0, s35, 0xe000
	s_nop 0
	global_load_lds_dwordx4 v[198:199], off
	s_waitcnt vmcnt(8) lgkmcnt(0)
	s_barrier
	s_setprio 1
	v_mfma_f32_16x16x32_bf16 v[154:157], v[78:81], v[166:169], v[154:157]
	v_mfma_f32_16x16x32_bf16 v[150:153], v[86:89], v[166:169], v[150:153]
	v_mfma_f32_16x16x32_bf16 v[134:137], v[78:81], v[174:177], v[134:137]
	v_mfma_f32_16x16x32_bf16 v[126:129], v[86:89], v[174:177], v[126:129]
	v_mfma_f32_16x16x32_bf16 v[118:121], v[78:81], v[182:185], v[118:121]
	v_mfma_f32_16x16x32_bf16 v[110:113], v[86:89], v[182:185], v[110:113]
	v_mfma_f32_16x16x32_bf16 v[102:105], v[78:81], v[190:193], v[102:105]
	v_mfma_f32_16x16x32_bf16 v[94:97], v[86:89], v[190:193], v[94:97]
	v_mfma_f32_16x16x32_bf16 v[154:157], v[82:85], v[170:173], v[154:157]
	v_mfma_f32_16x16x32_bf16 v[150:153], v[90:93], v[170:173], v[150:153]
	v_mfma_f32_16x16x32_bf16 v[134:137], v[82:85], v[178:181], v[134:137]
	v_mfma_f32_16x16x32_bf16 v[126:129], v[90:93], v[178:181], v[126:129]
	v_mfma_f32_16x16x32_bf16 v[118:121], v[82:85], v[186:189], v[118:121]
	v_mfma_f32_16x16x32_bf16 v[110:113], v[90:93], v[186:189], v[110:113]
	v_mfma_f32_16x16x32_bf16 v[102:105], v[82:85], v[194:197], v[102:105]
	v_mfma_f32_16x16x32_bf16 v[94:97], v[90:93], v[194:197], v[94:97]
	s_setprio 0
	s_setprio 1
	v_mfma_f32_16x16x32_bf16 v[138:141], v[142:145], v[166:169], v[138:141]
	v_mfma_f32_16x16x32_bf16 v[130:133], v[158:161], v[166:169], v[130:133]
	v_mfma_f32_16x16x32_bf16 v[122:125], v[142:145], v[174:177], v[122:125]
	v_mfma_f32_16x16x32_bf16 v[114:117], v[158:161], v[174:177], v[114:117]
	v_mfma_f32_16x16x32_bf16 v[106:109], v[142:145], v[182:185], v[106:109]
	v_mfma_f32_16x16x32_bf16 v[98:101], v[158:161], v[182:185], v[98:101]
	v_mfma_f32_16x16x32_bf16 v[74:77], v[142:145], v[190:193], v[74:77]
	v_mfma_f32_16x16x32_bf16 v[70:73], v[158:161], v[190:193], v[70:73]
	v_mfma_f32_16x16x32_bf16 v[138:141], v[146:149], v[170:173], v[138:141]
	v_mfma_f32_16x16x32_bf16 v[130:133], v[162:165], v[170:173], v[130:133]
	v_mfma_f32_16x16x32_bf16 v[122:125], v[146:149], v[178:181], v[122:125]
	v_mfma_f32_16x16x32_bf16 v[114:117], v[162:165], v[178:181], v[114:117]
	v_mfma_f32_16x16x32_bf16 v[106:109], v[146:149], v[186:189], v[106:109]
	v_mfma_f32_16x16x32_bf16 v[98:101], v[162:165], v[186:189], v[98:101]
	v_mfma_f32_16x16x32_bf16 v[74:77], v[146:149], v[194:197], v[74:77]
	v_mfma_f32_16x16x32_bf16 v[70:73], v[162:165], v[194:197], v[70:73]
	s_setprio 0
	s_barrier
	s_add_i32 s48, s50, s29
	v_lshl_add_u64 v[198:199], s[24:25], 0, v[216:217]
	s_mov_b32 m0, s48
	ds_read_b128 v[166:169], v5 offset:16384
	ds_read_b128 v[170:173], v5 offset:17408
	ds_read_b128 v[174:177], v5 offset:18432
	ds_read_b128 v[178:181], v5 offset:19456
	ds_read_b128 v[182:185], v5 offset:20480
	ds_read_b128 v[186:189], v5 offset:21504
	ds_read_b128 v[190:193], v5 offset:22528
	ds_read_b128 v[194:197], v5 offset:23552
	global_load_lds_dwordx4 v[198:199], off
	s_add_i32 m0, s48, 0x2000
	v_lshl_add_u64 v[198:199], s[24:25], 0, v[220:221]
	s_add_u32 s24, s24, 0x100000
	s_addc_u32 s25, s25, 0
	s_add_i32 s48, s51, s29
	global_load_lds_dwordx4 v[198:199], off
	v_lshl_add_u64 v[198:199], s[24:25], 0, v[216:217]
	s_mov_b32 m0, s48
	s_nop 0
	global_load_lds_dwordx4 v[198:199], off
	v_lshl_add_u64 v[198:199], s[24:25], 0, v[220:221]
	s_add_i32 m0, s48, 0x2000
	s_nop 0
	global_load_lds_dwordx4 v[198:199], off
	v_lshl_add_u64 v[198:199], s[22:23], 0, v[2:3]
	s_mov_b32 m0, s35
	s_nop 0
	global_load_lds_dwordx4 v[198:199], off
	v_lshl_add_u64 v[198:199], s[22:23], 0, v[218:219]
	s_mov_b32 m0, s36
	s_nop 0
	global_load_lds_dwordx4 v[198:199], off
	s_waitcnt vmcnt(8) lgkmcnt(0)
	s_barrier
	s_setprio 1
	v_mfma_f32_16x16x32_bf16 v[66:69], v[78:81], v[166:169], v[66:69]
	v_mfma_f32_16x16x32_bf16 v[62:65], v[86:89], v[166:169], v[62:65]
	v_mfma_f32_16x16x32_bf16 v[54:57], v[78:81], v[174:177], v[54:57]
	v_mfma_f32_16x16x32_bf16 v[46:49], v[86:89], v[174:177], v[46:49]
	v_mfma_f32_16x16x32_bf16 v[38:41], v[78:81], v[182:185], v[38:41]
	v_mfma_f32_16x16x32_bf16 v[30:33], v[86:89], v[182:185], v[30:33]
	v_mfma_f32_16x16x32_bf16 v[22:25], v[78:81], v[190:193], v[22:25]
	v_mfma_f32_16x16x32_bf16 v[14:17], v[86:89], v[190:193], v[14:17]
	v_mfma_f32_16x16x32_bf16 v[66:69], v[82:85], v[170:173], v[66:69]
	v_mfma_f32_16x16x32_bf16 v[62:65], v[90:93], v[170:173], v[62:65]
	v_mfma_f32_16x16x32_bf16 v[54:57], v[82:85], v[178:181], v[54:57]
	v_mfma_f32_16x16x32_bf16 v[46:49], v[90:93], v[178:181], v[46:49]
	v_mfma_f32_16x16x32_bf16 v[38:41], v[82:85], v[186:189], v[38:41]
	v_mfma_f32_16x16x32_bf16 v[30:33], v[90:93], v[186:189], v[30:33]
	v_mfma_f32_16x16x32_bf16 v[22:25], v[82:85], v[194:197], v[22:25]
	v_mfma_f32_16x16x32_bf16 v[14:17], v[90:93], v[194:197], v[14:17]
	s_setprio 0
	s_setprio 1
	v_mfma_f32_16x16x32_bf16 v[58:61], v[142:145], v[166:169], v[58:61]
	v_mfma_f32_16x16x32_bf16 v[50:53], v[158:161], v[166:169], v[50:53]
	v_mfma_f32_16x16x32_bf16 v[42:45], v[142:145], v[174:177], v[42:45]
	v_mfma_f32_16x16x32_bf16 v[34:37], v[158:161], v[174:177], v[34:37]
	v_mfma_f32_16x16x32_bf16 v[26:29], v[142:145], v[182:185], v[26:29]
	v_mfma_f32_16x16x32_bf16 v[18:21], v[158:161], v[182:185], v[18:21]
	v_mfma_f32_16x16x32_bf16 v[10:13], v[142:145], v[190:193], v[10:13]
	v_mfma_f32_16x16x32_bf16 v[6:9], v[158:161], v[190:193], v[6:9]
	v_mfma_f32_16x16x32_bf16 v[58:61], v[146:149], v[170:173], v[58:61]
	v_mfma_f32_16x16x32_bf16 v[50:53], v[162:165], v[170:173], v[50:53]
	v_mfma_f32_16x16x32_bf16 v[42:45], v[146:149], v[178:181], v[42:45]
	v_mfma_f32_16x16x32_bf16 v[34:37], v[162:165], v[178:181], v[34:37]
	v_mfma_f32_16x16x32_bf16 v[26:29], v[146:149], v[186:189], v[26:29]
	v_mfma_f32_16x16x32_bf16 v[18:21], v[162:165], v[186:189], v[18:21]
	v_mfma_f32_16x16x32_bf16 v[10:13], v[146:149], v[194:197], v[10:13]
	v_mfma_f32_16x16x32_bf16 v[6:9], v[162:165], v[194:197], v[6:9]
	s_setprio 0
	s_barrier
	s_add_i32 s24, 0, 0x18000
	s_add_i32 s25, 0, 0x1c000
	v_add_u32_e32 v90, s24, v1
	v_add_u32_e32 v162, s25, v1
	ds_read_b128 v[78:81], v90
	ds_read_b128 v[82:85], v90 offset:1024
	ds_read_b128 v[86:89], v90 offset:2048
	ds_read_b128 v[90:93], v90 offset:3072
	ds_read_b128 v[142:145], v162
	ds_read_b128 v[146:149], v162 offset:1024
	ds_read_b128 v[158:161], v162 offset:2048
	ds_read_b128 v[162:165], v162 offset:3072
	s_add_u32 s22, s22, 0x100000
	s_addc_u32 s23, s23, 0
	s_mov_b32 m0, s37
	v_lshl_add_u64 v[198:199], s[22:23], 0, v[2:3]
	ds_read_b128 v[166:169], v5 offset:32768
	ds_read_b128 v[170:173], v5 offset:33792
	ds_read_b128 v[174:177], v5 offset:34816
	ds_read_b128 v[178:181], v5 offset:35840
	ds_read_b128 v[182:185], v5 offset:36864
	ds_read_b128 v[186:189], v5 offset:37888
	ds_read_b128 v[190:193], v5 offset:38912
	ds_read_b128 v[194:197], v5 offset:39936
	global_load_lds_dwordx4 v[198:199], off
	v_lshl_add_u64 v[198:199], s[22:23], 0, v[218:219]
	s_mov_b32 m0, s38
	s_nop 0
	global_load_lds_dwordx4 v[198:199], off
	s_waitcnt vmcnt(8) lgkmcnt(0)
	s_barrier
	s_setprio 1
	v_mfma_f32_16x16x32_bf16 v[154:157], v[78:81], v[166:169], v[154:157]
	v_mfma_f32_16x16x32_bf16 v[150:153], v[86:89], v[166:169], v[150:153]
	v_mfma_f32_16x16x32_bf16 v[134:137], v[78:81], v[174:177], v[134:137]
	v_mfma_f32_16x16x32_bf16 v[126:129], v[86:89], v[174:177], v[126:129]
	v_mfma_f32_16x16x32_bf16 v[118:121], v[78:81], v[182:185], v[118:121]
	v_mfma_f32_16x16x32_bf16 v[110:113], v[86:89], v[182:185], v[110:113]
	v_mfma_f32_16x16x32_bf16 v[102:105], v[78:81], v[190:193], v[102:105]
	v_mfma_f32_16x16x32_bf16 v[94:97], v[86:89], v[190:193], v[94:97]
	v_mfma_f32_16x16x32_bf16 v[154:157], v[82:85], v[170:173], v[154:157]
	v_mfma_f32_16x16x32_bf16 v[150:153], v[90:93], v[170:173], v[150:153]
	v_mfma_f32_16x16x32_bf16 v[134:137], v[82:85], v[178:181], v[134:137]
	v_mfma_f32_16x16x32_bf16 v[126:129], v[90:93], v[178:181], v[126:129]
	v_mfma_f32_16x16x32_bf16 v[118:121], v[82:85], v[186:189], v[118:121]
	v_mfma_f32_16x16x32_bf16 v[110:113], v[90:93], v[186:189], v[110:113]
	v_mfma_f32_16x16x32_bf16 v[102:105], v[82:85], v[194:197], v[102:105]
	v_mfma_f32_16x16x32_bf16 v[94:97], v[90:93], v[194:197], v[94:97]
	s_setprio 0
	s_setprio 1
	v_mfma_f32_16x16x32_bf16 v[138:141], v[142:145], v[166:169], v[138:141]
	v_mfma_f32_16x16x32_bf16 v[130:133], v[158:161], v[166:169], v[130:133]
	v_mfma_f32_16x16x32_bf16 v[122:125], v[142:145], v[174:177], v[122:125]
	v_mfma_f32_16x16x32_bf16 v[114:117], v[158:161], v[174:177], v[114:117]
	v_mfma_f32_16x16x32_bf16 v[106:109], v[142:145], v[182:185], v[106:109]
	v_mfma_f32_16x16x32_bf16 v[98:101], v[158:161], v[182:185], v[98:101]
	v_mfma_f32_16x16x32_bf16 v[74:77], v[142:145], v[190:193], v[74:77]
	v_mfma_f32_16x16x32_bf16 v[70:73], v[158:161], v[190:193], v[70:73]
	v_mfma_f32_16x16x32_bf16 v[138:141], v[146:149], v[170:173], v[138:141]
	v_mfma_f32_16x16x32_bf16 v[130:133], v[162:165], v[170:173], v[130:133]
	v_mfma_f32_16x16x32_bf16 v[122:125], v[146:149], v[178:181], v[122:125]
	v_mfma_f32_16x16x32_bf16 v[114:117], v[162:165], v[178:181], v[114:117]
	v_mfma_f32_16x16x32_bf16 v[106:109], v[146:149], v[186:189], v[106:109]
	v_mfma_f32_16x16x32_bf16 v[98:101], v[162:165], v[186:189], v[98:101]
	v_mfma_f32_16x16x32_bf16 v[74:77], v[146:149], v[194:197], v[74:77]
	v_mfma_f32_16x16x32_bf16 v[70:73], v[162:165], v[194:197], v[70:73]
	s_setprio 0
	s_barrier
	s_add_i32 s22, s24, s29
	v_lshl_add_u64 v[198:199], s[20:21], 0, v[216:217]
	s_mov_b32 m0, s22
	ds_read_b128 v[166:169], v5 offset:49152
	ds_read_b128 v[170:173], v5 offset:50176
	ds_read_b128 v[174:177], v5 offset:51200
	ds_read_b128 v[178:181], v5 offset:52224
	ds_read_b128 v[182:185], v5 offset:53248
	ds_read_b128 v[186:189], v5 offset:54272
	ds_read_b128 v[190:193], v5 offset:55296
	ds_read_b128 v[194:197], v5 offset:56320
	global_load_lds_dwordx4 v[198:199], off
	s_add_i32 m0, s22, 0x2000
	v_lshl_add_u64 v[198:199], s[20:21], 0, v[220:221]
	s_add_u32 s20, s20, 0x100000
	s_addc_u32 s21, s21, 0
	s_add_i32 s22, s25, s29
	global_load_lds_dwordx4 v[198:199], off
	v_lshl_add_u64 v[198:199], s[20:21], 0, v[216:217]
	s_mov_b32 m0, s22
	s_nop 0
	global_load_lds_dwordx4 v[198:199], off
	v_lshl_add_u64 v[198:199], s[20:21], 0, v[220:221]
	s_add_i32 m0, s22, 0x2000
	s_nop 0
	global_load_lds_dwordx4 v[198:199], off
	v_lshl_add_u64 v[198:199], s[18:19], 0, v[2:3]
	s_mov_b32 m0, s41
	s_nop 0
	global_load_lds_dwordx4 v[198:199], off
	v_lshl_add_u64 v[198:199], s[18:19], 0, v[218:219]
	s_mov_b32 m0, s42
	s_nop 0
	global_load_lds_dwordx4 v[198:199], off
	s_waitcnt vmcnt(8) lgkmcnt(0)
	s_barrier
	s_setprio 1
	v_mfma_f32_16x16x32_bf16 v[66:69], v[78:81], v[166:169], v[66:69]
	v_mfma_f32_16x16x32_bf16 v[62:65], v[86:89], v[166:169], v[62:65]
	v_mfma_f32_16x16x32_bf16 v[54:57], v[78:81], v[174:177], v[54:57]
	v_mfma_f32_16x16x32_bf16 v[46:49], v[86:89], v[174:177], v[46:49]
	v_mfma_f32_16x16x32_bf16 v[38:41], v[78:81], v[182:185], v[38:41]
	v_mfma_f32_16x16x32_bf16 v[30:33], v[86:89], v[182:185], v[30:33]
	v_mfma_f32_16x16x32_bf16 v[22:25], v[78:81], v[190:193], v[22:25]
	v_mfma_f32_16x16x32_bf16 v[14:17], v[86:89], v[190:193], v[14:17]
	v_mfma_f32_16x16x32_bf16 v[66:69], v[82:85], v[170:173], v[66:69]
	v_mfma_f32_16x16x32_bf16 v[62:65], v[90:93], v[170:173], v[62:65]
	v_mfma_f32_16x16x32_bf16 v[54:57], v[82:85], v[178:181], v[54:57]
	v_mfma_f32_16x16x32_bf16 v[46:49], v[90:93], v[178:181], v[46:49]
	v_mfma_f32_16x16x32_bf16 v[38:41], v[82:85], v[186:189], v[38:41]
	v_mfma_f32_16x16x32_bf16 v[30:33], v[90:93], v[186:189], v[30:33]
	v_mfma_f32_16x16x32_bf16 v[22:25], v[82:85], v[194:197], v[22:25]
	v_mfma_f32_16x16x32_bf16 v[14:17], v[90:93], v[194:197], v[14:17]
	s_setprio 0
	s_setprio 1
	v_mfma_f32_16x16x32_bf16 v[58:61], v[142:145], v[166:169], v[58:61]
	v_mfma_f32_16x16x32_bf16 v[50:53], v[158:161], v[166:169], v[50:53]
	v_mfma_f32_16x16x32_bf16 v[42:45], v[142:145], v[174:177], v[42:45]
	v_mfma_f32_16x16x32_bf16 v[34:37], v[158:161], v[174:177], v[34:37]
	v_mfma_f32_16x16x32_bf16 v[26:29], v[142:145], v[182:185], v[26:29]
	v_mfma_f32_16x16x32_bf16 v[18:21], v[158:161], v[182:185], v[18:21]
	v_mfma_f32_16x16x32_bf16 v[10:13], v[142:145], v[190:193], v[10:13]
	v_mfma_f32_16x16x32_bf16 v[6:9], v[158:161], v[190:193], v[6:9]
	v_mfma_f32_16x16x32_bf16 v[58:61], v[146:149], v[170:173], v[58:61]
	v_mfma_f32_16x16x32_bf16 v[50:53], v[162:165], v[170:173], v[50:53]
	v_mfma_f32_16x16x32_bf16 v[42:45], v[146:149], v[178:181], v[42:45]
	v_mfma_f32_16x16x32_bf16 v[34:37], v[162:165], v[178:181], v[34:37]
	v_mfma_f32_16x16x32_bf16 v[26:29], v[146:149], v[186:189], v[26:29]
	v_mfma_f32_16x16x32_bf16 v[18:21], v[162:165], v[186:189], v[18:21]
	v_mfma_f32_16x16x32_bf16 v[10:13], v[146:149], v[194:197], v[10:13]
	v_mfma_f32_16x16x32_bf16 v[6:9], v[162:165], v[194:197], v[6:9]
	s_setprio 0
	s_barrier
	s_add_i32 s47, s47, 2
	s_add_u32 s33, s33, 0x100
	s_addc_u32 s44, s44, 0
	s_add_u32 s45, s45, 0x100
	s_addc_u32 s46, s46, 0
	s_cmp_gt_u32 s47, 61
	s_cbranch_scc0 .LBB0_924
	v_mov_b32_e32 v142, v0
	s_mov_b64 s[20:21], s[84:85]
	s_add_u32 s7, s20, 0x4179c000
	v_readlane_b32 s18, v254, 26
	s_addc_u32 s9, s21, 0
	v_readlane_b32 s19, v254, 27
	v_readlane_b32 s44, v253, 35
	s_and_b64 s[18:19], s[18:19], exec
	v_readlane_b32 s45, v253, 36
	v_bfe_u32 v144, v142, 4, 2
	s_cselect_b32 s23, s9, s45
	s_cselect_b32 s22, s7, s44
	s_cselect_b32 s19, s83, s9
	s_cselect_b32 s18, s82, s7
	s_lshl_b32 s7, s8, 8
	s_lshl_b32 s6, s6, 8
	v_lshl_or_b32 v78, v144, 3, s7
	s_add_i32 s6, s6, s39
	v_or_b32_e32 v226, s40, v78
	v_ashrrev_i32_e32 v227, 31, v226
	v_readlane_b32 s8, v254, 9
	v_and_or_b32 v230, v142, 15, s6
	v_lshlrev_b64 v[244:245], 2, v[226:227]
	v_readlane_b32 s9, v254, 10
	v_lshl_add_u64 v[142:143], v[226:227], 1, s[20:21]
	s_mov_b64 s[6:7], 0x10f80000
	v_ashrrev_i32_e32 v231, 31, v230
	v_or_b32_e32 v240, 16, v230
	v_lshl_add_u64 v[82:83], s[8:9], 0, v[244:245]
	v_lshl_add_u64 v[228:229], s[22:23], 0, v[244:245]
	v_lshl_add_u64 v[224:225], v[142:143], 0, s[6:7]
	v_lshl_add_u64 v[142:143], v[230:231], 2, s[20:21]
	s_mov_b64 s[8:9], 0x18400
	v_lshlrev_b64 v[248:249], 14, v[230:231]
	v_ashrrev_i32_e32 v241, 31, v240
	v_or_b32_e32 v236, 32, v230
	v_or_b32_e32 v232, 48, v230
	v_lshl_add_u64 v[222:223], v[142:143], 0, s[8:9]
	v_lshl_add_u64 v[142:143], v[228:229], 0, v[248:249]
	v_lshlrev_b64 v[242:243], 14, v[240:241]
	v_ashrrev_i32_e32 v237, 31, v236
	v_ashrrev_i32_e32 v233, 31, v232
	global_load_dwordx4 v[86:89], v[82:83], off offset:16
	global_load_dwordx4 v[90:93], v[82:83], off
	global_load_dwordx4 v[78:81], v[82:83], off offset:528
	s_nop 0
	global_load_dwordx4 v[82:85], v[82:83], off offset:512
	s_nop 0
	global_load_dwordx4 v[206:209], v[142:143], off offset:16
	global_load_dwordx4 v[210:213], v[142:143], off
	global_load_dwordx4 v[198:201], v[142:143], off offset:528
	global_load_dwordx4 v[202:205], v[142:143], off offset:512
	v_lshl_add_u64 v[142:143], v[228:229], 0, v[242:243]
	v_lshlrev_b64 v[238:239], 14, v[236:237]
	v_lshlrev_b64 v[234:235], 14, v[232:233]
	global_load_dwordx4 v[190:193], v[142:143], off offset:16
	global_load_dwordx4 v[194:197], v[142:143], off
	global_load_dwordx4 v[182:185], v[142:143], off offset:528
	global_load_dwordx4 v[186:189], v[142:143], off offset:512
	v_lshl_add_u64 v[142:143], v[228:229], 0, v[238:239]
	v_lshl_add_u64 v[146:147], v[228:229], 0, v[234:235]
	v_cmp_eq_u32_e64 s[6:7], 0, v144
	global_load_dwordx4 v[174:177], v[142:143], off offset:16
	global_load_dwordx4 v[178:181], v[142:143], off
	global_load_dwordx4 v[166:169], v[142:143], off offset:528
	global_load_dwordx4 v[170:173], v[142:143], off offset:512
	global_load_dwordx4 v[158:161], v[146:147], off offset:16
	global_load_dwordx4 v[162:165], v[146:147], off
	s_nop 0
	global_load_dwordx4 v[142:145], v[146:147], off offset:528
	s_nop 0
	global_load_dwordx4 v[146:149], v[146:147], off offset:512
	v_lshl_add_u64 v[248:249], s[18:19], 0, v[248:249]
	v_lshl_add_u64 v[244:245], v[248:249], 0, v[244:245]
	s_mov_b64 s[20:21], -1
	s_andn2_b64 vcc, exec, s[60:61]
	v_readlane_b32 s46, v253, 37
	v_readlane_b32 s47, v253, 38
	v_readlane_b32 s48, v253, 39
	v_readlane_b32 s49, v253, 40
	v_readlane_b32 s50, v253, 41
	v_readlane_b32 s51, v253, 42
	v_readlane_b32 s52, v253, 43
	v_readlane_b32 s53, v253, 44
	v_readlane_b32 s54, v253, 45
	v_readlane_b32 s55, v253, 46
	v_readlane_b32 s56, v253, 47
	v_readlane_b32 s57, v253, 48
	v_readlane_b32 s58, v253, 49
	v_readlane_b32 s59, v253, 50
	s_waitcnt vmcnt(0)
	v_pk_add_f32 v[206:207], v[150:151], v[206:207]
	v_cndmask_b32_e64 v150, 0, 1, s[60:61]
	v_pk_add_f32 v[212:213], v[156:157], v[212:213]
	v_pk_add_f32 v[210:211], v[154:155], v[210:211]
	v_pk_add_f32 v[208:209], v[152:153], v[208:209]
	v_cmp_ne_u32_e64 s[8:9], 1, v150
	v_pk_add_f32 v[150:151], v[138:139], v[202:203]
	v_pk_add_f32 v[154:155], v[130:131], v[198:199]
	global_store_dwordx4 v[244:245], v[210:213], off
	global_store_dwordx4 v[244:245], v[206:209], off offset:16
	s_cbranch_vccnz .LBB0_929
	v_mul_f32_e32 v138, v211, v211
	v_mul_f32_e32 v139, v213, v213
	v_fmac_f32_e32 v138, v210, v210
	v_fmac_f32_e32 v139, v212, v212
	v_add_f32_e32 v138, v138, v139
	v_mul_f32_e32 v139, v207, v207
	v_fmac_f32_e32 v139, v206, v206
	v_add_f32_e32 v138, v138, v139
	v_mul_f32_e32 v139, v209, v209
	v_lshlrev_b64 v[130:131], 12, v[230:231]
	v_fmac_f32_e32 v139, v208, v208
	v_pk_mul_f32 v[152:153], v[90:91], v[210:211]
	v_pk_mul_f32 v[156:157], v[88:89], v[208:209]
	v_lshl_add_u64 v[130:131], v[130:131], 1, v[224:225]
	v_add_f32_e32 v231, v139, v138
	v_pk_mul_f32 v[138:139], v[92:93], v[212:213]
	v_pk_mul_f32 v[198:199], v[86:87], v[206:207]
	v_cvt_pk_bf16_f32 v206, v152, v153
	v_cvt_pk_bf16_f32 v207, v138, v139
	v_pk_add_f32 v[152:153], v[140:141], v[204:205]
	v_cvt_pk_bf16_f32 v208, v198, v199
	v_cvt_pk_bf16_f32 v209, v156, v157
	v_pk_add_f32 v[156:157], v[132:133], v[200:201]
	global_store_dwordx4 v[130:131], v[206:209], off
	global_store_dwordx4 v[244:245], v[150:153], off offset:512
	global_store_dwordx4 v[244:245], v[154:157], off offset:528
	v_pk_mul_f32 v[202:203], v[80:81], v[156:157]
	v_pk_mul_f32 v[138:139], v[84:85], v[152:153]
	v_mul_f32_e32 v157, v157, v157
	v_fmac_f32_e32 v157, v156, v156
	v_mul_f32_e32 v156, v151, v151
	v_mul_f32_e32 v153, v153, v153
	v_fmac_f32_e32 v156, v150, v150
	v_fmac_f32_e32 v153, v152, v152
	v_add_f32_e32 v152, v156, v153
	v_mul_f32_e32 v153, v155, v155
	v_fmac_f32_e32 v153, v154, v154
	v_add_f32_e32 v152, v152, v153
	v_add_f32_e32 v152, v157, v152
	v_add_f32_e32 v152, v231, v152
	ds_swizzle_b32 v153, v152 offset:swizzle(SWAP,16)
	v_pk_mul_f32 v[208:209], v[78:79], v[154:155]
	v_pk_mul_f32 v[198:199], v[82:83], v[150:151]
	s_nop 0
	v_cvt_pk_bf16_f32 v206, v198, v199
	v_cvt_pk_bf16_f32 v207, v138, v139
	v_cvt_pk_bf16_f32 v208, v208, v209
	v_cvt_pk_bf16_f32 v209, v202, v203
	global_store_dwordx4 v[130:131], v[206:209], off offset:256
	s_waitcnt lgkmcnt(0)
	v_add_f32_e32 v130, v152, v153
	v_mov_b32_e32 v131, v130
	s_nop 1
	v_permlane32_swap_b32_e32 v130, v131
	s_and_saveexec_b64 s[20:21], s[6:7]
	s_cbranch_execz .LBB0_928
	v_add_f32_e32 v130, v130, v131
	global_atomic_add_f32 v[222:223], v130, off
